# v026 + removed the redundant post-barrier lgkmcnt(0) before each 32-MFMA segment in the GEMM K-loops (asm wait before the barrier already covers it)
# speedup vs baseline: 1.0222x; 1.0063x over previous
; #define PG8_STAGE(bufoff, gbase, voff) do { _Pragma("unroll") for (int _i = 0; _i < 2; ++_i) \
;         __builtin_amdgcn_global_load_lds((const unsigned*)((const char*)(gbase) + (voff)[_i]), (LAS unsigned*)(lds + (bufoff) + ldsw + _i * 8192), 16, 0, 0); } while (0)
; #define PG8_LDA(dst, b, h) do { _Pragma("unroll") for (int m = 0; m < 4; ++m) _Pragma("unroll") for (int k = 0; k < 2; ++k) dst[m][k] = *(const LAS bf16x8*)(lds + PG8_SA(b, h) + aoff + m * 2048 + k * 1024); } while (0)
; #define PG8_LDB(dst, b, h) do { _Pragma("unroll") for (int n = 0; n < 2; ++n) _Pragma("unroll") for (int k = 0; k < 2; ++k) dst[n][k] = *(const LAS bf16x8*)(lds + PG8_SB(b, h) + boff + n * 2048 + k * 1024); } while (0)
; #define PG8_MMA(ai, bj, At, Bt) do { __builtin_amdgcn_s_setprio(1); _Pragma("unroll") for (int m = 0; m < 4; ++m) _Pragma("unroll") for (int n = 0; n < 2; ++n) _Pragma("unroll") for (int k = 0; k < 2; ++k) \
;         acc[ai][bj][m][n] = __builtin_amdgcn_mfma_f32_16x16x32_bf16(Bt[n][k], At[m][k], acc[ai][bj][m][n], 0, 0, 0); __builtin_amdgcn_s_setprio(0); } while (0)
; #define PG8_WAIT_V(n) asm volatile("s_waitcnt vmcnt(" #n ")" ::: "memory")
; #define PG8_WAIT_L(n) asm volatile("s_waitcnt lgkmcnt(" #n ")" ::: "memory")
; #define PG8_BAR __builtin_amdgcn_s_barrier()
; #define PG8_SCHED __builtin_amdgcn_sched_barrier(0)
; template <class Epi, class Sched>
; DI void gemm_phase(LAS unsigned char* lds, const Gemm g, const Sched& S, const Epi& E) {
;     ...
;             PG8_LDB(B0, 0, 0); PG8_LDB(B1, 0, 1); PG8_SCHED; PG8_LDA(At, 0, 0); PG8_STAGE(PG8_SA(1, 1), a1 + hstepA, voffA);
;             PG8_WAIT_V(8); PG8_WAIT_L(0); PG8_BAR; PG8_MMA(0, 0, At, B0); PG8_MMA(0, 1, At, B1); PG8_BAR; PG8_SCHED;
;             PG8_LDA(At, 0, 1); PG8_STAGE(PG8_SB(0, 0), b2, voffB); PG8_STAGE(PG8_SB(0, 1), b2 + hstepB, voffB); PG8_STAGE(PG8_SA(0, 0), a2, voffA);
;             PG8_WAIT_V(8); PG8_WAIT_L(0); PG8_BAR; PG8_MMA(1, 0, At, B0); PG8_MMA(1, 1, At, B1); PG8_BAR; PG8_SCHED;
.LBB0_179:
	ds_read_b128 v[168:171], v162
	ds_read_b128 v[172:175], v162 offset:1024
	ds_read_b128 v[176:179], v162 offset:2048
	ds_read_b128 v[180:183], v162 offset:3072
	ds_read_b128 v[186:189], v163
	ds_read_b128 v[190:193], v163 offset:1024
	ds_read_b128 v[194:197], v163 offset:2048
	ds_read_b128 v[198:201], v163 offset:3072
	s_add_u32 s42, s40, 0xfffc0080
	s_addc_u32 s43, s41, -1
	s_cmp_eq_u32 s65, 12
	s_cselect_b32 s45, s35, s43
	s_cselect_b32 s44, s61, s42
	s_cselect_b32 s43, s21, s64
	s_cselect_b32 s42, s62, s63
	v_lshl_add_u64 v[234:235], s[40:41], 0, v[138:139]
	s_add_i32 m0, s49, 0xc000
	ds_read_b128 v[202:205], v160
	ds_read_b128 v[206:209], v160 offset:1024
	ds_read_b128 v[210:213], v160 offset:2048
	ds_read_b128 v[214:217], v160 offset:3072
	ds_read_b128 v[218:221], v160 offset:4096
	ds_read_b128 v[222:225], v160 offset:5120
	ds_read_b128 v[226:229], v160 offset:6144
	ds_read_b128 v[230:233], v160 offset:7168
	global_load_lds_dwordx4 v[234:235], off
	v_lshl_add_u64 v[234:235], s[40:41], 0, v[140:141]
	s_add_i32 m0, s49, 0xe000
	s_nop 0
	global_load_lds_dwordx4 v[234:235], off
	s_waitcnt vmcnt(8)
	s_waitcnt lgkmcnt(0)
	s_barrier
	s_setprio 1
	v_mfma_f32_16x16x32_bf16 v[126:129], v[168:171], v[202:205], v[126:129]
	v_mfma_f32_16x16x32_bf16 v[118:121], v[176:179], v[202:205], v[118:121]
	v_mfma_f32_16x16x32_bf16 v[110:113], v[168:171], v[210:213], v[110:113]
	v_mfma_f32_16x16x32_bf16 v[102:105], v[176:179], v[210:213], v[102:105]
	v_mfma_f32_16x16x32_bf16 v[94:97], v[168:171], v[218:221], v[94:97]
	v_mfma_f32_16x16x32_bf16 v[86:89], v[176:179], v[218:221], v[86:89]
	v_mfma_f32_16x16x32_bf16 v[78:81], v[168:171], v[226:229], v[78:81]
	v_mfma_f32_16x16x32_bf16 v[70:73], v[176:179], v[226:229], v[70:73]
	v_mfma_f32_16x16x32_bf16 v[126:129], v[172:175], v[206:209], v[126:129]
	v_mfma_f32_16x16x32_bf16 v[118:121], v[180:183], v[206:209], v[118:121]
	v_mfma_f32_16x16x32_bf16 v[110:113], v[172:175], v[214:217], v[110:113]
	v_mfma_f32_16x16x32_bf16 v[102:105], v[180:183], v[214:217], v[102:105]
	v_mfma_f32_16x16x32_bf16 v[94:97], v[172:175], v[222:225], v[94:97]
	v_mfma_f32_16x16x32_bf16 v[86:89], v[180:183], v[222:225], v[86:89]
	v_mfma_f32_16x16x32_bf16 v[78:81], v[172:175], v[230:233], v[78:81]
	v_mfma_f32_16x16x32_bf16 v[70:73], v[180:183], v[230:233], v[70:73]
	s_setprio 0
	s_setprio 1
	v_mfma_f32_16x16x32_bf16 v[122:125], v[186:189], v[202:205], v[122:125]
	v_mfma_f32_16x16x32_bf16 v[114:117], v[194:197], v[202:205], v[114:117]
	v_mfma_f32_16x16x32_bf16 v[106:109], v[186:189], v[210:213], v[106:109]
	v_mfma_f32_16x16x32_bf16 v[98:101], v[194:197], v[210:213], v[98:101]
	v_mfma_f32_16x16x32_bf16 v[90:93], v[186:189], v[218:221], v[90:93]
	v_mfma_f32_16x16x32_bf16 v[82:85], v[194:197], v[218:221], v[82:85]
	v_mfma_f32_16x16x32_bf16 v[74:77], v[186:189], v[226:229], v[74:77]
	v_mfma_f32_16x16x32_bf16 v[66:69], v[194:197], v[226:229], v[66:69]
	v_mfma_f32_16x16x32_bf16 v[122:125], v[190:193], v[206:209], v[122:125]
	v_mfma_f32_16x16x32_bf16 v[114:117], v[198:201], v[206:209], v[114:117]
	v_mfma_f32_16x16x32_bf16 v[106:109], v[190:193], v[214:217], v[106:109]
	v_mfma_f32_16x16x32_bf16 v[98:101], v[198:201], v[214:217], v[98:101]
	v_mfma_f32_16x16x32_bf16 v[90:93], v[190:193], v[222:225], v[90:93]
	v_mfma_f32_16x16x32_bf16 v[82:85], v[198:201], v[222:225], v[82:85]
	v_mfma_f32_16x16x32_bf16 v[74:77], v[190:193], v[230:233], v[74:77]
	v_mfma_f32_16x16x32_bf16 v[66:69], v[198:201], v[230:233], v[66:69]
	s_setprio 0
	s_barrier
	s_add_i32 s66, s57, s46
	v_lshl_add_u64 v[234:235], s[42:43], 0, v[134:135]
	s_mov_b32 m0, s66
	ds_read_b128 v[202:205], v160 offset:16384
	ds_read_b128 v[206:209], v160 offset:17408
	ds_read_b128 v[210:213], v160 offset:18432
	ds_read_b128 v[214:217], v160 offset:19456
	ds_read_b128 v[218:221], v160 offset:20480
	ds_read_b128 v[222:225], v160 offset:21504
	ds_read_b128 v[226:229], v160 offset:22528
	ds_read_b128 v[230:233], v160 offset:23552
	global_load_lds_dwordx4 v[234:235], off
	s_add_i32 m0, s66, 0x2000
	s_add_u32 s66, s42, 0x40000
	v_lshl_add_u64 v[236:237], s[42:43], 0, v[130:131]
	s_addc_u32 s67, s43, 0
	s_add_i32 s68, s58, s46
	global_load_lds_dwordx4 v[236:237], off
	v_lshl_add_u64 v[238:239], s[66:67], 0, v[134:135]
	s_mov_b32 m0, s68
	v_lshl_add_u64 v[240:241], s[44:45], 0, v[132:133]
	global_load_lds_dwordx4 v[238:239], off
	v_lshl_add_u64 v[238:239], s[66:67], 0, v[130:131]
	s_add_i32 m0, s68, 0x2000
	s_nop 0
	global_load_lds_dwordx4 v[238:239], off
	v_lshl_add_u64 v[238:239], s[44:45], 0, v[136:137]
	s_mov_b32 m0, s49
	s_nop 0
	global_load_lds_dwordx4 v[238:239], off
	s_mov_b32 m0, s50
	s_nop 0
	global_load_lds_dwordx4 v[240:241], off
	s_waitcnt vmcnt(8)
	s_waitcnt lgkmcnt(0)
	s_barrier
; #define PG8_STAGE(bufoff, gbase, voff) do { _Pragma("unroll") for (int _i = 0; _i < 2; ++_i) \
;         __builtin_amdgcn_global_load_lds((const unsigned*)((const char*)(gbase) + (voff)[_i]), (LAS unsigned*)(lds + (bufoff) + ldsw + _i * 8192), 16, 0, 0); } while (0)
; #define PG8_LDA(dst, b, h) do { _Pragma("unroll") for (int m = 0; m < 4; ++m) _Pragma("unroll") for (int k = 0; k < 2; ++k) dst[m][k] = *(const LAS bf16x8*)(lds + PG8_SA(b, h) + aoff + m * 2048 + k * 1024); } while (0)
; #define PG8_LDB(dst, b, h) do { _Pragma("unroll") for (int n = 0; n < 2; ++n) _Pragma("unroll") for (int k = 0; k < 2; ++k) dst[n][k] = *(const LAS bf16x8*)(lds + PG8_SB(b, h) + boff + n * 2048 + k * 1024); } while (0)
; #define PG8_MMA(ai, bj, At, Bt) do { __builtin_amdgcn_s_setprio(1); _Pragma("unroll") for (int m = 0; m < 4; ++m) _Pragma("unroll") for (int n = 0; n < 2; ++n) _Pragma("unroll") for (int k = 0; k < 2; ++k) \
;         acc[ai][bj][m][n] = __builtin_amdgcn_mfma_f32_16x16x32_bf16(Bt[n][k], At[m][k], acc[ai][bj][m][n], 0, 0, 0); __builtin_amdgcn_s_setprio(0); } while (0)
; #define PG8_WAIT_V(n) asm volatile("s_waitcnt vmcnt(" #n ")" ::: "memory")
; #define PG8_WAIT_L(n) asm volatile("s_waitcnt lgkmcnt(" #n ")" ::: "memory")
; #define PG8_BAR __builtin_amdgcn_s_barrier()
; #define PG8_SCHED __builtin_amdgcn_sched_barrier(0)
; template <class Epi, class Sched>
; DI void gemm_phase(LAS unsigned char* lds, const Gemm g, const Sched& S, const Epi& E) {
;     ...
;             PG8_WAIT_V(8); PG8_WAIT_L(0); PG8_BAR; PG8_MMA(1, 0, At, B0); PG8_MMA(1, 1, At, B1); PG8_BAR; PG8_SCHED;
;             PG8_LDB(B0, 1, 0); PG8_LDB(B1, 1, 1); PG8_SCHED; PG8_LDA(At, 1, 0); PG8_STAGE(PG8_SA(0, 1), a2 + hstepA, voffA);
;             PG8_WAIT_V(8); PG8_WAIT_L(0); PG8_BAR; PG8_MMA(0, 0, At, B0); PG8_MMA(0, 1, At, B1); PG8_BAR; PG8_SCHED;
	s_setprio 1
	v_mfma_f32_16x16x32_bf16 v[62:65], v[168:171], v[202:205], v[62:65]
	v_mfma_f32_16x16x32_bf16 v[54:57], v[176:179], v[202:205], v[54:57]
	v_mfma_f32_16x16x32_bf16 v[46:49], v[168:171], v[210:213], v[46:49]
	v_mfma_f32_16x16x32_bf16 v[38:41], v[176:179], v[210:213], v[38:41]
	v_mfma_f32_16x16x32_bf16 v[30:33], v[168:171], v[218:221], v[30:33]
	v_mfma_f32_16x16x32_bf16 v[22:25], v[176:179], v[218:221], v[22:25]
	v_mfma_f32_16x16x32_bf16 v[14:17], v[168:171], v[226:229], v[14:17]
	v_mfma_f32_16x16x32_bf16 v[6:9], v[176:179], v[226:229], v[6:9]
	v_mfma_f32_16x16x32_bf16 v[62:65], v[172:175], v[206:209], v[62:65]
	v_mfma_f32_16x16x32_bf16 v[54:57], v[180:183], v[206:209], v[54:57]
	v_mfma_f32_16x16x32_bf16 v[46:49], v[172:175], v[214:217], v[46:49]
	v_mfma_f32_16x16x32_bf16 v[38:41], v[180:183], v[214:217], v[38:41]
	v_mfma_f32_16x16x32_bf16 v[30:33], v[172:175], v[222:225], v[30:33]
	v_mfma_f32_16x16x32_bf16 v[22:25], v[180:183], v[222:225], v[22:25]
	v_mfma_f32_16x16x32_bf16 v[14:17], v[172:175], v[230:233], v[14:17]
	v_mfma_f32_16x16x32_bf16 v[6:9], v[180:183], v[230:233], v[6:9]
	s_setprio 0
	s_setprio 1
	v_mfma_f32_16x16x32_bf16 v[58:61], v[186:189], v[202:205], v[58:61]
	v_mfma_f32_16x16x32_bf16 v[50:53], v[194:197], v[202:205], v[50:53]
	v_mfma_f32_16x16x32_bf16 v[42:45], v[186:189], v[210:213], v[42:45]
	v_mfma_f32_16x16x32_bf16 v[34:37], v[194:197], v[210:213], v[34:37]
	v_mfma_f32_16x16x32_bf16 v[26:29], v[186:189], v[218:221], v[26:29]
	v_mfma_f32_16x16x32_bf16 v[18:21], v[194:197], v[218:221], v[18:21]
	v_mfma_f32_16x16x32_bf16 v[10:13], v[186:189], v[226:229], v[10:13]
	v_mfma_f32_16x16x32_bf16 v[2:5], v[194:197], v[226:229], v[2:5]
	v_mfma_f32_16x16x32_bf16 v[58:61], v[190:193], v[206:209], v[58:61]
	v_mfma_f32_16x16x32_bf16 v[50:53], v[198:201], v[206:209], v[50:53]
	v_mfma_f32_16x16x32_bf16 v[42:45], v[190:193], v[214:217], v[42:45]
	v_mfma_f32_16x16x32_bf16 v[34:37], v[198:201], v[214:217], v[34:37]
	v_mfma_f32_16x16x32_bf16 v[26:29], v[190:193], v[222:225], v[26:29]
	v_mfma_f32_16x16x32_bf16 v[18:21], v[198:201], v[222:225], v[18:21]
	v_mfma_f32_16x16x32_bf16 v[10:13], v[190:193], v[230:233], v[10:13]
	v_mfma_f32_16x16x32_bf16 v[2:5], v[198:201], v[230:233], v[2:5]
	s_setprio 0
	s_barrier
	s_add_i32 s66, 0, 0x18000
	v_add_u32_e32 v167, s66, v158
	s_add_i32 s67, 0, 0x1c000
	ds_read_b128 v[168:171], v167
	ds_read_b128 v[172:175], v167 offset:1024
	ds_read_b128 v[176:179], v167 offset:2048
	ds_read_b128 v[180:183], v167 offset:3072
	v_add_u32_e32 v167, s67, v158
	ds_read_b128 v[186:189], v167
	ds_read_b128 v[190:193], v167 offset:1024
	ds_read_b128 v[194:197], v167 offset:2048
	ds_read_b128 v[198:201], v167 offset:3072
	s_add_u32 s44, s44, 0x40000
	s_addc_u32 s45, s45, 0
	s_mov_b32 m0, s51
	v_lshl_add_u64 v[242:243], s[44:45], 0, v[136:137]
	ds_read_b128 v[202:205], v160 offset:32768
	ds_read_b128 v[206:209], v160 offset:33792
	ds_read_b128 v[210:213], v160 offset:34816
	ds_read_b128 v[214:217], v160 offset:35840
	ds_read_b128 v[218:221], v160 offset:36864
	ds_read_b128 v[222:225], v160 offset:37888
	ds_read_b128 v[226:229], v160 offset:38912
	ds_read_b128 v[230:233], v160 offset:39936
	global_load_lds_dwordx4 v[242:243], off
	v_lshl_add_u64 v[242:243], s[44:45], 0, v[132:133]
	s_mov_b32 m0, s52
	s_nop 0
	global_load_lds_dwordx4 v[242:243], off
	s_waitcnt vmcnt(8)
	s_waitcnt lgkmcnt(0)
	s_barrier
	s_setprio 1
	v_mfma_f32_16x16x32_bf16 v[126:129], v[168:171], v[202:205], v[126:129]
	v_mfma_f32_16x16x32_bf16 v[118:121], v[176:179], v[202:205], v[118:121]
	v_mfma_f32_16x16x32_bf16 v[110:113], v[168:171], v[210:213], v[110:113]
	v_mfma_f32_16x16x32_bf16 v[102:105], v[176:179], v[210:213], v[102:105]
	v_mfma_f32_16x16x32_bf16 v[94:97], v[168:171], v[218:221], v[94:97]
	v_mfma_f32_16x16x32_bf16 v[86:89], v[176:179], v[218:221], v[86:89]
	v_mfma_f32_16x16x32_bf16 v[78:81], v[168:171], v[226:229], v[78:81]
	v_mfma_f32_16x16x32_bf16 v[70:73], v[176:179], v[226:229], v[70:73]
	v_mfma_f32_16x16x32_bf16 v[126:129], v[172:175], v[206:209], v[126:129]
	v_mfma_f32_16x16x32_bf16 v[118:121], v[180:183], v[206:209], v[118:121]
	v_mfma_f32_16x16x32_bf16 v[110:113], v[172:175], v[214:217], v[110:113]
	v_mfma_f32_16x16x32_bf16 v[102:105], v[180:183], v[214:217], v[102:105]
	v_mfma_f32_16x16x32_bf16 v[94:97], v[172:175], v[222:225], v[94:97]
	v_mfma_f32_16x16x32_bf16 v[86:89], v[180:183], v[222:225], v[86:89]
	v_mfma_f32_16x16x32_bf16 v[78:81], v[172:175], v[230:233], v[78:81]
	v_mfma_f32_16x16x32_bf16 v[70:73], v[180:183], v[230:233], v[70:73]
	s_setprio 0
	s_setprio 1
	v_mfma_f32_16x16x32_bf16 v[122:125], v[186:189], v[202:205], v[122:125]
	v_mfma_f32_16x16x32_bf16 v[114:117], v[194:197], v[202:205], v[114:117]
	v_mfma_f32_16x16x32_bf16 v[106:109], v[186:189], v[210:213], v[106:109]
	v_mfma_f32_16x16x32_bf16 v[98:101], v[194:197], v[210:213], v[98:101]
	v_mfma_f32_16x16x32_bf16 v[90:93], v[186:189], v[218:221], v[90:93]
	v_mfma_f32_16x16x32_bf16 v[82:85], v[194:197], v[218:221], v[82:85]
	v_mfma_f32_16x16x32_bf16 v[74:77], v[186:189], v[226:229], v[74:77]
	v_mfma_f32_16x16x32_bf16 v[66:69], v[194:197], v[226:229], v[66:69]
	v_mfma_f32_16x16x32_bf16 v[122:125], v[190:193], v[206:209], v[122:125]
	v_mfma_f32_16x16x32_bf16 v[114:117], v[198:201], v[206:209], v[114:117]
	v_mfma_f32_16x16x32_bf16 v[106:109], v[190:193], v[214:217], v[106:109]
	v_mfma_f32_16x16x32_bf16 v[98:101], v[198:201], v[214:217], v[98:101]
	v_mfma_f32_16x16x32_bf16 v[90:93], v[190:193], v[222:225], v[90:93]
	v_mfma_f32_16x16x32_bf16 v[82:85], v[198:201], v[222:225], v[82:85]
	v_mfma_f32_16x16x32_bf16 v[74:77], v[190:193], v[230:233], v[74:77]
	v_mfma_f32_16x16x32_bf16 v[66:69], v[198:201], v[230:233], v[66:69]
	s_setprio 0
	s_barrier
; #define PG8_STAGE(bufoff, gbase, voff) do { _Pragma("unroll") for (int _i = 0; _i < 2; ++_i) \
;         __builtin_amdgcn_global_load_lds((const unsigned*)((const char*)(gbase) + (voff)[_i]), (LAS unsigned*)(lds + (bufoff) + ldsw + _i * 8192), 16, 0, 0); } while (0)
; #define PG8_LDA(dst, b, h) do { _Pragma("unroll") for (int m = 0; m < 4; ++m) _Pragma("unroll") for (int k = 0; k < 2; ++k) dst[m][k] = *(const LAS bf16x8*)(lds + PG8_SA(b, h) + aoff + m * 2048 + k * 1024); } while (0)
; #define PG8_MMA(ai, bj, At, Bt) do { __builtin_amdgcn_s_setprio(1); _Pragma("unroll") for (int m = 0; m < 4; ++m) _Pragma("unroll") for (int n = 0; n < 2; ++n) _Pragma("unroll") for (int k = 0; k < 2; ++k) \
;         acc[ai][bj][m][n] = __builtin_amdgcn_mfma_f32_16x16x32_bf16(Bt[n][k], At[m][k], acc[ai][bj][m][n], 0, 0, 0); __builtin_amdgcn_s_setprio(0); } while (0)
; #define PG8_WAIT_V(n) asm volatile("s_waitcnt vmcnt(" #n ")" ::: "memory")
; #define PG8_WAIT_L(n) asm volatile("s_waitcnt lgkmcnt(" #n ")" ::: "memory")
; #define PG8_BAR __builtin_amdgcn_s_barrier()
; #define PG8_SCHED __builtin_amdgcn_sched_barrier(0)
; template <class Epi, class Sched>
; DI void gemm_phase(LAS unsigned char* lds, const Gemm g, const Sched& S, const Epi& E) {
;     ...
;             PG8_LDA(At, 1, 1); PG8_STAGE(PG8_SB(1, 0), b3, voffB); PG8_STAGE(PG8_SB(1, 1), b3 + hstepB, voffB); PG8_STAGE(PG8_SA(1, 0), a3, voffA);
;             PG8_WAIT_V(8); PG8_WAIT_L(0); PG8_BAR; PG8_MMA(1, 0, At, B0); PG8_MMA(1, 1, At, B1); PG8_BAR; PG8_SCHED;
;         }
;         if (wr == 0) PG8_BAR;
	s_add_i32 s44, s66, s46
	v_lshl_add_u64 v[234:235], v[234:235], 0, s[16:17]
	s_mov_b32 m0, s44
	ds_read_b128 v[202:205], v160 offset:49152
	ds_read_b128 v[206:209], v160 offset:50176
	ds_read_b128 v[210:213], v160 offset:51200
	ds_read_b128 v[214:217], v160 offset:52224
	ds_read_b128 v[218:221], v160 offset:53248
	ds_read_b128 v[222:225], v160 offset:54272
	ds_read_b128 v[226:229], v160 offset:55296
	ds_read_b128 v[230:233], v160 offset:56320
	global_load_lds_dwordx4 v[234:235], off
	s_add_i32 m0, s44, 0x2000
	s_add_u32 s42, s42, 0x40080
	v_lshl_add_u64 v[234:235], v[236:237], 0, s[16:17]
	s_addc_u32 s43, s43, 0
	s_add_i32 s44, s67, s46
	global_load_lds_dwordx4 v[234:235], off
	v_lshl_add_u64 v[234:235], s[42:43], 0, v[134:135]
	s_mov_b32 m0, s44
	s_nop 0
	global_load_lds_dwordx4 v[234:235], off
	v_lshl_add_u64 v[234:235], s[42:43], 0, v[130:131]
	s_add_i32 m0, s44, 0x2000
	s_nop 0
	global_load_lds_dwordx4 v[234:235], off
	v_lshl_add_u64 v[234:235], v[238:239], 0, s[16:17]
	s_mov_b32 m0, s54
	s_nop 0
	global_load_lds_dwordx4 v[234:235], off
	v_lshl_add_u64 v[234:235], v[240:241], 0, s[16:17]
	s_mov_b32 m0, s55
	s_nop 0
	global_load_lds_dwordx4 v[234:235], off
	s_waitcnt vmcnt(8)
	s_waitcnt lgkmcnt(0)
	s_barrier
	s_setprio 1
	v_mfma_f32_16x16x32_bf16 v[62:65], v[168:171], v[202:205], v[62:65]
	v_mfma_f32_16x16x32_bf16 v[54:57], v[176:179], v[202:205], v[54:57]
	v_mfma_f32_16x16x32_bf16 v[46:49], v[168:171], v[210:213], v[46:49]
	v_mfma_f32_16x16x32_bf16 v[38:41], v[176:179], v[210:213], v[38:41]
	v_mfma_f32_16x16x32_bf16 v[30:33], v[168:171], v[218:221], v[30:33]
	v_mfma_f32_16x16x32_bf16 v[22:25], v[176:179], v[218:221], v[22:25]
	v_mfma_f32_16x16x32_bf16 v[14:17], v[168:171], v[226:229], v[14:17]
	v_mfma_f32_16x16x32_bf16 v[6:9], v[176:179], v[226:229], v[6:9]
	v_mfma_f32_16x16x32_bf16 v[62:65], v[172:175], v[206:209], v[62:65]
	v_mfma_f32_16x16x32_bf16 v[54:57], v[180:183], v[206:209], v[54:57]
	v_mfma_f32_16x16x32_bf16 v[46:49], v[172:175], v[214:217], v[46:49]
	v_mfma_f32_16x16x32_bf16 v[38:41], v[180:183], v[214:217], v[38:41]
	v_mfma_f32_16x16x32_bf16 v[30:33], v[172:175], v[222:225], v[30:33]
	v_mfma_f32_16x16x32_bf16 v[22:25], v[180:183], v[222:225], v[22:25]
	v_mfma_f32_16x16x32_bf16 v[14:17], v[172:175], v[230:233], v[14:17]
	v_mfma_f32_16x16x32_bf16 v[6:9], v[180:183], v[230:233], v[6:9]
	s_setprio 0
	s_setprio 1
	v_mfma_f32_16x16x32_bf16 v[58:61], v[186:189], v[202:205], v[58:61]
	v_mfma_f32_16x16x32_bf16 v[50:53], v[194:197], v[202:205], v[50:53]
	v_mfma_f32_16x16x32_bf16 v[42:45], v[186:189], v[210:213], v[42:45]
	v_mfma_f32_16x16x32_bf16 v[34:37], v[194:197], v[210:213], v[34:37]
	v_mfma_f32_16x16x32_bf16 v[26:29], v[186:189], v[218:221], v[26:29]
	v_mfma_f32_16x16x32_bf16 v[18:21], v[194:197], v[218:221], v[18:21]
	v_mfma_f32_16x16x32_bf16 v[10:13], v[186:189], v[226:229], v[10:13]
	v_mfma_f32_16x16x32_bf16 v[2:5], v[194:197], v[226:229], v[2:5]
	v_mfma_f32_16x16x32_bf16 v[58:61], v[190:193], v[206:209], v[58:61]
	v_mfma_f32_16x16x32_bf16 v[50:53], v[198:201], v[206:209], v[50:53]
	v_mfma_f32_16x16x32_bf16 v[42:45], v[190:193], v[214:217], v[42:45]
	v_mfma_f32_16x16x32_bf16 v[34:37], v[198:201], v[214:217], v[34:37]
	v_mfma_f32_16x16x32_bf16 v[26:29], v[190:193], v[222:225], v[26:29]
	v_mfma_f32_16x16x32_bf16 v[18:21], v[198:201], v[222:225], v[18:21]
	v_mfma_f32_16x16x32_bf16 v[10:13], v[190:193], v[230:233], v[10:13]
	v_mfma_f32_16x16x32_bf16 v[2:5], v[198:201], v[230:233], v[2:5]
	s_setprio 0
	s_barrier
	s_add_i32 s65, s65, 2
	s_add_u32 s40, s40, 0x100
	s_addc_u32 s41, s41, 0
	s_add_u32 s63, s63, 0x100
	s_addc_u32 s64, s64, 0
	s_cmp_gt_u32 s65, 13
	s_cbranch_scc0 .LBB0_179
	s_and_b64 vcc, exec, s[18:19]
	s_cbranch_vccz .LBB0_182
	s_barrier

; #define PG8_STAGE(bufoff, gbase, voff) do { _Pragma("unroll") for (int _i = 0; _i < 2; ++_i) \
;         __builtin_amdgcn_global_load_lds((const unsigned*)((const char*)(gbase) + (voff)[_i]), (LAS unsigned*)(lds + (bufoff) + ldsw + _i * 8192), 16, 0, 0); } while (0)
; #define PG8_LDA(dst, b, h) do { _Pragma("unroll") for (int m = 0; m < 4; ++m) _Pragma("unroll") for (int k = 0; k < 2; ++k) dst[m][k] = *(const LAS bf16x8*)(lds + PG8_SA(b, h) + aoff + m * 2048 + k * 1024); } while (0)
; #define PG8_LDB(dst, b, h) do { _Pragma("unroll") for (int n = 0; n < 2; ++n) _Pragma("unroll") for (int k = 0; k < 2; ++k) dst[n][k] = *(const LAS bf16x8*)(lds + PG8_SB(b, h) + boff + n * 2048 + k * 1024); } while (0)
; #define PG8_MMA(ai, bj, At, Bt) do { __builtin_amdgcn_s_setprio(1); _Pragma("unroll") for (int m = 0; m < 4; ++m) _Pragma("unroll") for (int n = 0; n < 2; ++n) _Pragma("unroll") for (int k = 0; k < 2; ++k) \
;         acc[ai][bj][m][n] = __builtin_amdgcn_mfma_f32_16x16x32_bf16(Bt[n][k], At[m][k], acc[ai][bj][m][n], 0, 0, 0); __builtin_amdgcn_s_setprio(0); } while (0)
; #define PG8_WAIT_V(n) asm volatile("s_waitcnt vmcnt(" #n ")" ::: "memory")
; #define PG8_WAIT_L(n) asm volatile("s_waitcnt lgkmcnt(" #n ")" ::: "memory")
; #define PG8_BAR __builtin_amdgcn_s_barrier()
; #define PG8_SCHED __builtin_amdgcn_sched_barrier(0)
; template <class Epi, class Sched>
; DI void gemm_phase(LAS unsigned char* lds, const Gemm g, const Sched& S, const Epi& E) {
;     ...
;             const bool last = (t == nt - 2);
;             const char* a1 = cA + (size_t)(t + 1) * kstep;
;             const char* a2 = last ? nA : cA + (size_t)(t + 2) * kstep; const char* b2 = last ? nB : cB + (size_t)(t + 2) * kstep;
;             const char* a3 = a2 + kstep; const char* b3 = b2 + kstep;
;             PG8_LDB(B0, 0, 0); PG8_LDB(B1, 0, 1); PG8_SCHED; PG8_LDA(At, 0, 0); PG8_STAGE(PG8_SA(1, 1), a1 + hstepA, voffA);
;             PG8_WAIT_V(8); PG8_WAIT_L(0); PG8_BAR; PG8_MMA(0, 0, At, B0); PG8_MMA(0, 1, At, B1); PG8_BAR; PG8_SCHED;
;             PG8_LDA(At, 0, 1); PG8_STAGE(PG8_SB(0, 0), b2, voffB); PG8_STAGE(PG8_SB(0, 1), b2 + hstepB, voffB); PG8_STAGE(PG8_SA(0, 0), a2, voffA);
;             PG8_WAIT_V(8); PG8_WAIT_L(0); PG8_BAR; PG8_MMA(1, 0, At, B0); PG8_MMA(1, 1, At, B1); PG8_BAR; PG8_SCHED;
.LBB0_278:
	ds_read_b128 v[148:151], v154
	ds_read_b128 v[158:161], v154 offset:1024
	ds_read_b128 v[162:165], v154 offset:2048
	ds_read_b128 v[166:169], v154 offset:3072
	ds_read_b128 v[170:173], v155
	ds_read_b128 v[174:177], v155 offset:1024
	ds_read_b128 v[178:181], v155 offset:2048
	ds_read_b128 v[186:189], v155 offset:3072
	s_add_u32 s38, s36, 0xfff50080
	s_addc_u32 s39, s37, -1
	s_cmp_eq_u32 s62, 40
	s_cselect_b32 s41, s9, s39
	s_cselect_b32 s40, s8, s38
	s_cselect_b32 s39, s35, s61
	s_cselect_b32 s38, s34, s60
	v_lshl_add_u64 v[182:183], s[36:37], 0, v[138:139]
	s_add_i32 m0, s45, 0xc000
	ds_read_b128 v[190:193], v156
	ds_read_b128 v[194:197], v156 offset:1024
	ds_read_b128 v[198:201], v156 offset:2048
	ds_read_b128 v[202:205], v156 offset:3072
	ds_read_b128 v[206:209], v156 offset:4096
	ds_read_b128 v[210:213], v156 offset:5120
	ds_read_b128 v[214:217], v156 offset:6144
	ds_read_b128 v[218:221], v156 offset:7168
	global_load_lds_dwordx4 v[182:183], off
	v_lshl_add_u64 v[182:183], s[36:37], 0, v[140:141]
	s_add_i32 m0, s45, 0xe000
	s_nop 0
	global_load_lds_dwordx4 v[182:183], off
	s_waitcnt vmcnt(8)
	s_waitcnt lgkmcnt(0)
	s_barrier
	s_setprio 1
	v_mfma_f32_16x16x32_bf16 v[126:129], v[148:151], v[190:193], v[126:129]
	v_mfma_f32_16x16x32_bf16 v[122:125], v[162:165], v[190:193], v[122:125]
	v_mfma_f32_16x16x32_bf16 v[110:113], v[148:151], v[198:201], v[110:113]
	v_mfma_f32_16x16x32_bf16 v[106:109], v[162:165], v[198:201], v[106:109]
	v_mfma_f32_16x16x32_bf16 v[94:97], v[148:151], v[206:209], v[94:97]
	v_mfma_f32_16x16x32_bf16 v[90:93], v[162:165], v[206:209], v[90:93]
	v_mfma_f32_16x16x32_bf16 v[78:81], v[148:151], v[214:217], v[78:81]
	v_mfma_f32_16x16x32_bf16 v[74:77], v[162:165], v[214:217], v[74:77]
	v_mfma_f32_16x16x32_bf16 v[126:129], v[158:161], v[194:197], v[126:129]
	v_mfma_f32_16x16x32_bf16 v[122:125], v[166:169], v[194:197], v[122:125]
	v_mfma_f32_16x16x32_bf16 v[110:113], v[158:161], v[202:205], v[110:113]
	v_mfma_f32_16x16x32_bf16 v[106:109], v[166:169], v[202:205], v[106:109]
	v_mfma_f32_16x16x32_bf16 v[94:97], v[158:161], v[210:213], v[94:97]
	v_mfma_f32_16x16x32_bf16 v[90:93], v[166:169], v[210:213], v[90:93]
	v_mfma_f32_16x16x32_bf16 v[78:81], v[158:161], v[218:221], v[78:81]
	v_mfma_f32_16x16x32_bf16 v[74:77], v[166:169], v[218:221], v[74:77]
	s_setprio 0
	s_setprio 1
	v_mfma_f32_16x16x32_bf16 v[118:121], v[170:173], v[190:193], v[118:121]
	v_mfma_f32_16x16x32_bf16 v[114:117], v[178:181], v[190:193], v[114:117]
	v_mfma_f32_16x16x32_bf16 v[102:105], v[170:173], v[198:201], v[102:105]
	v_mfma_f32_16x16x32_bf16 v[98:101], v[178:181], v[198:201], v[98:101]
	v_mfma_f32_16x16x32_bf16 v[86:89], v[170:173], v[206:209], v[86:89]
	v_mfma_f32_16x16x32_bf16 v[82:85], v[178:181], v[206:209], v[82:85]
	v_mfma_f32_16x16x32_bf16 v[70:73], v[170:173], v[214:217], v[70:73]
	v_mfma_f32_16x16x32_bf16 v[66:69], v[178:181], v[214:217], v[66:69]
	v_mfma_f32_16x16x32_bf16 v[118:121], v[174:177], v[194:197], v[118:121]
	v_mfma_f32_16x16x32_bf16 v[114:117], v[186:189], v[194:197], v[114:117]
	v_mfma_f32_16x16x32_bf16 v[102:105], v[174:177], v[202:205], v[102:105]
	v_mfma_f32_16x16x32_bf16 v[98:101], v[186:189], v[202:205], v[98:101]
	v_mfma_f32_16x16x32_bf16 v[86:89], v[174:177], v[210:213], v[86:89]
	v_mfma_f32_16x16x32_bf16 v[82:85], v[186:189], v[210:213], v[82:85]
	v_mfma_f32_16x16x32_bf16 v[70:73], v[174:177], v[218:221], v[70:73]
	v_mfma_f32_16x16x32_bf16 v[66:69], v[186:189], v[218:221], v[66:69]
	s_setprio 0
	s_barrier
	s_add_i32 s63, s54, s44
	v_lshl_add_u64 v[182:183], s[38:39], 0, v[132:133]
	s_mov_b32 m0, s63
	ds_read_b128 v[190:193], v156 offset:16384
	ds_read_b128 v[194:197], v156 offset:17408
	ds_read_b128 v[198:201], v156 offset:18432
	ds_read_b128 v[202:205], v156 offset:19456
	ds_read_b128 v[206:209], v156 offset:20480
	ds_read_b128 v[210:213], v156 offset:21504
	ds_read_b128 v[214:217], v156 offset:22528
	ds_read_b128 v[218:221], v156 offset:23552
	global_load_lds_dwordx4 v[182:183], off
	s_add_i32 m0, s63, 0x2000
	s_add_u32 s64, s38, 0xb0000
	v_lshl_add_u64 v[222:223], s[38:39], 0, v[136:137]
	s_addc_u32 s65, s39, 0
	s_add_i32 s63, s55, s44
	global_load_lds_dwordx4 v[222:223], off
	v_lshl_add_u64 v[224:225], s[64:65], 0, v[132:133]
	s_mov_b32 m0, s63
	v_lshl_add_u64 v[226:227], s[40:41], 0, v[134:135]
	global_load_lds_dwordx4 v[224:225], off
	v_lshl_add_u64 v[224:225], s[64:65], 0, v[136:137]
	s_add_i32 m0, s63, 0x2000
	s_nop 0
	global_load_lds_dwordx4 v[224:225], off
	v_lshl_add_u64 v[224:225], s[40:41], 0, v[130:131]
	s_mov_b32 m0, s45
	s_nop 0
	global_load_lds_dwordx4 v[224:225], off
	s_mov_b32 m0, s46
	s_nop 0
	global_load_lds_dwordx4 v[226:227], off
	s_waitcnt vmcnt(8)
	s_waitcnt lgkmcnt(0)
	s_barrier
; #define PG8_STAGE(bufoff, gbase, voff) do { _Pragma("unroll") for (int _i = 0; _i < 2; ++_i) \
;         __builtin_amdgcn_global_load_lds((const unsigned*)((const char*)(gbase) + (voff)[_i]), (LAS unsigned*)(lds + (bufoff) + ldsw + _i * 8192), 16, 0, 0); } while (0)
; #define PG8_LDA(dst, b, h) do { _Pragma("unroll") for (int m = 0; m < 4; ++m) _Pragma("unroll") for (int k = 0; k < 2; ++k) dst[m][k] = *(const LAS bf16x8*)(lds + PG8_SA(b, h) + aoff + m * 2048 + k * 1024); } while (0)
; #define PG8_LDB(dst, b, h) do { _Pragma("unroll") for (int n = 0; n < 2; ++n) _Pragma("unroll") for (int k = 0; k < 2; ++k) dst[n][k] = *(const LAS bf16x8*)(lds + PG8_SB(b, h) + boff + n * 2048 + k * 1024); } while (0)
; #define PG8_MMA(ai, bj, At, Bt) do { __builtin_amdgcn_s_setprio(1); _Pragma("unroll") for (int m = 0; m < 4; ++m) _Pragma("unroll") for (int n = 0; n < 2; ++n) _Pragma("unroll") for (int k = 0; k < 2; ++k) \
;         acc[ai][bj][m][n] = __builtin_amdgcn_mfma_f32_16x16x32_bf16(Bt[n][k], At[m][k], acc[ai][bj][m][n], 0, 0, 0); __builtin_amdgcn_s_setprio(0); } while (0)
; #define PG8_WAIT_V(n) asm volatile("s_waitcnt vmcnt(" #n ")" ::: "memory")
; #define PG8_WAIT_L(n) asm volatile("s_waitcnt lgkmcnt(" #n ")" ::: "memory")
; #define PG8_BAR __builtin_amdgcn_s_barrier()
; #define PG8_SCHED __builtin_amdgcn_sched_barrier(0)
; template <class Epi, class Sched>
; DI void gemm_phase(LAS unsigned char* lds, const Gemm g, const Sched& S, const Epi& E) {
;     ...
;             PG8_WAIT_V(8); PG8_WAIT_L(0); PG8_BAR; PG8_MMA(1, 0, At, B0); PG8_MMA(1, 1, At, B1); PG8_BAR; PG8_SCHED;
;             PG8_LDB(B0, 1, 0); PG8_LDB(B1, 1, 1); PG8_SCHED; PG8_LDA(At, 1, 0); PG8_STAGE(PG8_SA(0, 1), a2 + hstepA, voffA);
;             PG8_WAIT_V(8); PG8_WAIT_L(0); PG8_BAR; PG8_MMA(0, 0, At, B0); PG8_MMA(0, 1, At, B1); PG8_BAR; PG8_SCHED;
	s_setprio 1
	v_mfma_f32_16x16x32_bf16 v[62:65], v[148:151], v[190:193], v[62:65]
	v_mfma_f32_16x16x32_bf16 v[58:61], v[162:165], v[190:193], v[58:61]
	v_mfma_f32_16x16x32_bf16 v[46:49], v[148:151], v[198:201], v[46:49]
	v_mfma_f32_16x16x32_bf16 v[42:45], v[162:165], v[198:201], v[42:45]
	v_mfma_f32_16x16x32_bf16 v[30:33], v[148:151], v[206:209], v[30:33]
	v_mfma_f32_16x16x32_bf16 v[26:29], v[162:165], v[206:209], v[26:29]
	v_mfma_f32_16x16x32_bf16 v[14:17], v[148:151], v[214:217], v[14:17]
	v_mfma_f32_16x16x32_bf16 v[10:13], v[162:165], v[214:217], v[10:13]
	v_mfma_f32_16x16x32_bf16 v[62:65], v[158:161], v[194:197], v[62:65]
	v_mfma_f32_16x16x32_bf16 v[58:61], v[166:169], v[194:197], v[58:61]
	v_mfma_f32_16x16x32_bf16 v[46:49], v[158:161], v[202:205], v[46:49]
	v_mfma_f32_16x16x32_bf16 v[42:45], v[166:169], v[202:205], v[42:45]
	v_mfma_f32_16x16x32_bf16 v[30:33], v[158:161], v[210:213], v[30:33]
	v_mfma_f32_16x16x32_bf16 v[26:29], v[166:169], v[210:213], v[26:29]
	v_mfma_f32_16x16x32_bf16 v[14:17], v[158:161], v[218:221], v[14:17]
	v_mfma_f32_16x16x32_bf16 v[10:13], v[166:169], v[218:221], v[10:13]
	s_setprio 0
	s_setprio 1
	v_mfma_f32_16x16x32_bf16 v[54:57], v[170:173], v[190:193], v[54:57]
	v_mfma_f32_16x16x32_bf16 v[50:53], v[178:181], v[190:193], v[50:53]
	v_mfma_f32_16x16x32_bf16 v[38:41], v[170:173], v[198:201], v[38:41]
	v_mfma_f32_16x16x32_bf16 v[34:37], v[178:181], v[198:201], v[34:37]
	v_mfma_f32_16x16x32_bf16 v[22:25], v[170:173], v[206:209], v[22:25]
	v_mfma_f32_16x16x32_bf16 v[18:21], v[178:181], v[206:209], v[18:21]
	v_mfma_f32_16x16x32_bf16 v[6:9], v[170:173], v[214:217], v[6:9]
	v_mfma_f32_16x16x32_bf16 v[2:5], v[178:181], v[214:217], v[2:5]
	v_mfma_f32_16x16x32_bf16 v[54:57], v[174:177], v[194:197], v[54:57]
	v_mfma_f32_16x16x32_bf16 v[50:53], v[186:189], v[194:197], v[50:53]
	v_mfma_f32_16x16x32_bf16 v[38:41], v[174:177], v[202:205], v[38:41]
	v_mfma_f32_16x16x32_bf16 v[34:37], v[186:189], v[202:205], v[34:37]
	v_mfma_f32_16x16x32_bf16 v[22:25], v[174:177], v[210:213], v[22:25]
	v_mfma_f32_16x16x32_bf16 v[18:21], v[186:189], v[210:213], v[18:21]
	v_mfma_f32_16x16x32_bf16 v[6:9], v[174:177], v[218:221], v[6:9]
	v_mfma_f32_16x16x32_bf16 v[2:5], v[186:189], v[218:221], v[2:5]
	s_setprio 0
	s_barrier
	s_add_i32 s63, 0, 0x18000
	s_add_i32 s64, 0, 0x1c000
	v_add_u32_e32 v166, s63, v152
	v_add_u32_e32 v185, s64, v152
	ds_read_b128 v[148:151], v166
	ds_read_b128 v[158:161], v166 offset:1024
	ds_read_b128 v[162:165], v166 offset:2048
	ds_read_b128 v[166:169], v166 offset:3072
	ds_read_b128 v[170:173], v185
	ds_read_b128 v[174:177], v185 offset:1024
	ds_read_b128 v[178:181], v185 offset:2048
	ds_read_b128 v[186:189], v185 offset:3072
	s_add_u32 s40, s40, 0xb0000
	s_addc_u32 s41, s41, 0
	s_mov_b32 m0, s47
	v_lshl_add_u64 v[228:229], s[40:41], 0, v[130:131]
	ds_read_b128 v[190:193], v156 offset:32768
	ds_read_b128 v[194:197], v156 offset:33792
	ds_read_b128 v[198:201], v156 offset:34816
	ds_read_b128 v[202:205], v156 offset:35840
	ds_read_b128 v[206:209], v156 offset:36864
	ds_read_b128 v[210:213], v156 offset:37888
	ds_read_b128 v[214:217], v156 offset:38912
	ds_read_b128 v[218:221], v156 offset:39936
	global_load_lds_dwordx4 v[228:229], off
	v_lshl_add_u64 v[228:229], s[40:41], 0, v[134:135]
	s_mov_b32 m0, s48
	s_nop 0
	global_load_lds_dwordx4 v[228:229], off
	s_waitcnt vmcnt(8)
	s_waitcnt lgkmcnt(0)
	s_barrier
	s_setprio 1
	v_mfma_f32_16x16x32_bf16 v[126:129], v[148:151], v[190:193], v[126:129]
	v_mfma_f32_16x16x32_bf16 v[122:125], v[162:165], v[190:193], v[122:125]
	v_mfma_f32_16x16x32_bf16 v[110:113], v[148:151], v[198:201], v[110:113]
	v_mfma_f32_16x16x32_bf16 v[106:109], v[162:165], v[198:201], v[106:109]
	v_mfma_f32_16x16x32_bf16 v[94:97], v[148:151], v[206:209], v[94:97]
	v_mfma_f32_16x16x32_bf16 v[90:93], v[162:165], v[206:209], v[90:93]
	v_mfma_f32_16x16x32_bf16 v[78:81], v[148:151], v[214:217], v[78:81]
	v_mfma_f32_16x16x32_bf16 v[74:77], v[162:165], v[214:217], v[74:77]
	v_mfma_f32_16x16x32_bf16 v[126:129], v[158:161], v[194:197], v[126:129]
	v_mfma_f32_16x16x32_bf16 v[122:125], v[166:169], v[194:197], v[122:125]
	v_mfma_f32_16x16x32_bf16 v[110:113], v[158:161], v[202:205], v[110:113]
	v_mfma_f32_16x16x32_bf16 v[106:109], v[166:169], v[202:205], v[106:109]
	v_mfma_f32_16x16x32_bf16 v[94:97], v[158:161], v[210:213], v[94:97]
	v_mfma_f32_16x16x32_bf16 v[90:93], v[166:169], v[210:213], v[90:93]
	v_mfma_f32_16x16x32_bf16 v[78:81], v[158:161], v[218:221], v[78:81]
	v_mfma_f32_16x16x32_bf16 v[74:77], v[166:169], v[218:221], v[74:77]
	s_setprio 0
	s_setprio 1
	v_mfma_f32_16x16x32_bf16 v[118:121], v[170:173], v[190:193], v[118:121]
	v_mfma_f32_16x16x32_bf16 v[114:117], v[178:181], v[190:193], v[114:117]
	v_mfma_f32_16x16x32_bf16 v[102:105], v[170:173], v[198:201], v[102:105]
	v_mfma_f32_16x16x32_bf16 v[98:101], v[178:181], v[198:201], v[98:101]
	v_mfma_f32_16x16x32_bf16 v[86:89], v[170:173], v[206:209], v[86:89]
	v_mfma_f32_16x16x32_bf16 v[82:85], v[178:181], v[206:209], v[82:85]
	v_mfma_f32_16x16x32_bf16 v[70:73], v[170:173], v[214:217], v[70:73]
	v_mfma_f32_16x16x32_bf16 v[66:69], v[178:181], v[214:217], v[66:69]
	v_mfma_f32_16x16x32_bf16 v[118:121], v[174:177], v[194:197], v[118:121]
	v_mfma_f32_16x16x32_bf16 v[114:117], v[186:189], v[194:197], v[114:117]
	v_mfma_f32_16x16x32_bf16 v[102:105], v[174:177], v[202:205], v[102:105]
	v_mfma_f32_16x16x32_bf16 v[98:101], v[186:189], v[202:205], v[98:101]
	v_mfma_f32_16x16x32_bf16 v[86:89], v[174:177], v[210:213], v[86:89]
	v_mfma_f32_16x16x32_bf16 v[82:85], v[186:189], v[210:213], v[82:85]
	v_mfma_f32_16x16x32_bf16 v[70:73], v[174:177], v[218:221], v[70:73]
	v_mfma_f32_16x16x32_bf16 v[66:69], v[186:189], v[218:221], v[66:69]
	s_setprio 0
	s_barrier
; #define PG8_STAGE(bufoff, gbase, voff) do { _Pragma("unroll") for (int _i = 0; _i < 2; ++_i) \
;         __builtin_amdgcn_global_load_lds((const unsigned*)((const char*)(gbase) + (voff)[_i]), (LAS unsigned*)(lds + (bufoff) + ldsw + _i * 8192), 16, 0, 0); } while (0)
; #define PG8_LDA(dst, b, h) do { _Pragma("unroll") for (int m = 0; m < 4; ++m) _Pragma("unroll") for (int k = 0; k < 2; ++k) dst[m][k] = *(const LAS bf16x8*)(lds + PG8_SA(b, h) + aoff + m * 2048 + k * 1024); } while (0)
; #define PG8_MMA(ai, bj, At, Bt) do { __builtin_amdgcn_s_setprio(1); _Pragma("unroll") for (int m = 0; m < 4; ++m) _Pragma("unroll") for (int n = 0; n < 2; ++n) _Pragma("unroll") for (int k = 0; k < 2; ++k) \
;         acc[ai][bj][m][n] = __builtin_amdgcn_mfma_f32_16x16x32_bf16(Bt[n][k], At[m][k], acc[ai][bj][m][n], 0, 0, 0); __builtin_amdgcn_s_setprio(0); } while (0)
; #define PG8_WAIT_V(n) asm volatile("s_waitcnt vmcnt(" #n ")" ::: "memory")
; #define PG8_WAIT_L(n) asm volatile("s_waitcnt lgkmcnt(" #n ")" ::: "memory")
; #define PG8_BAR __builtin_amdgcn_s_barrier()
; #define PG8_SCHED __builtin_amdgcn_sched_barrier(0)
; template <class Epi, class Sched>
; DI void gemm_phase(LAS unsigned char* lds, const Gemm g, const Sched& S, const Epi& E) {
;     ...
;             PG8_LDA(At, 1, 1); PG8_STAGE(PG8_SB(1, 0), b3, voffB); PG8_STAGE(PG8_SB(1, 1), b3 + hstepB, voffB); PG8_STAGE(PG8_SA(1, 0), a3, voffA);
;             PG8_WAIT_V(8); PG8_WAIT_L(0); PG8_BAR; PG8_MMA(1, 0, At, B0); PG8_MMA(1, 1, At, B1); PG8_BAR; PG8_SCHED;
;         }
;         if (wr == 0) PG8_BAR;
	s_add_i32 s40, s63, s44
	v_lshl_add_u64 v[182:183], v[182:183], 0, s[16:17]
	s_mov_b32 m0, s40
	ds_read_b128 v[190:193], v156 offset:49152
	ds_read_b128 v[194:197], v156 offset:50176
	ds_read_b128 v[198:201], v156 offset:51200
	ds_read_b128 v[202:205], v156 offset:52224
	ds_read_b128 v[206:209], v156 offset:53248
	ds_read_b128 v[210:213], v156 offset:54272
	ds_read_b128 v[214:217], v156 offset:55296
	ds_read_b128 v[218:221], v156 offset:56320
	global_load_lds_dwordx4 v[182:183], off
	s_add_i32 m0, s40, 0x2000
	s_add_u32 s38, s38, 0xb0080
	v_lshl_add_u64 v[182:183], v[222:223], 0, s[16:17]
	s_addc_u32 s39, s39, 0
	s_add_i32 s40, s64, s44
	global_load_lds_dwordx4 v[182:183], off
	v_lshl_add_u64 v[182:183], s[38:39], 0, v[132:133]
	s_mov_b32 m0, s40
	s_nop 0
	global_load_lds_dwordx4 v[182:183], off
	v_lshl_add_u64 v[182:183], s[38:39], 0, v[136:137]
	s_add_i32 m0, s40, 0x2000
	s_nop 0
	global_load_lds_dwordx4 v[182:183], off
	v_lshl_add_u64 v[182:183], v[224:225], 0, s[16:17]
	s_mov_b32 m0, s50
	s_nop 0
	global_load_lds_dwordx4 v[182:183], off
	v_lshl_add_u64 v[182:183], v[226:227], 0, s[16:17]
	s_mov_b32 m0, s51
	s_nop 0
	global_load_lds_dwordx4 v[182:183], off
	s_waitcnt vmcnt(8)
	s_waitcnt lgkmcnt(0)
	s_barrier
	s_setprio 1
	v_mfma_f32_16x16x32_bf16 v[62:65], v[148:151], v[190:193], v[62:65]
	v_mfma_f32_16x16x32_bf16 v[58:61], v[162:165], v[190:193], v[58:61]
	v_mfma_f32_16x16x32_bf16 v[46:49], v[148:151], v[198:201], v[46:49]
	v_mfma_f32_16x16x32_bf16 v[42:45], v[162:165], v[198:201], v[42:45]
	v_mfma_f32_16x16x32_bf16 v[30:33], v[148:151], v[206:209], v[30:33]
	v_mfma_f32_16x16x32_bf16 v[26:29], v[162:165], v[206:209], v[26:29]
	v_mfma_f32_16x16x32_bf16 v[14:17], v[148:151], v[214:217], v[14:17]
	v_mfma_f32_16x16x32_bf16 v[10:13], v[162:165], v[214:217], v[10:13]
	v_mfma_f32_16x16x32_bf16 v[62:65], v[158:161], v[194:197], v[62:65]
	v_mfma_f32_16x16x32_bf16 v[58:61], v[166:169], v[194:197], v[58:61]
	v_mfma_f32_16x16x32_bf16 v[46:49], v[158:161], v[202:205], v[46:49]
	v_mfma_f32_16x16x32_bf16 v[42:45], v[166:169], v[202:205], v[42:45]
	v_mfma_f32_16x16x32_bf16 v[30:33], v[158:161], v[210:213], v[30:33]
	v_mfma_f32_16x16x32_bf16 v[26:29], v[166:169], v[210:213], v[26:29]
	v_mfma_f32_16x16x32_bf16 v[14:17], v[158:161], v[218:221], v[14:17]
	v_mfma_f32_16x16x32_bf16 v[10:13], v[166:169], v[218:221], v[10:13]
	s_setprio 0
	s_setprio 1
	v_mfma_f32_16x16x32_bf16 v[54:57], v[170:173], v[190:193], v[54:57]
	v_mfma_f32_16x16x32_bf16 v[50:53], v[178:181], v[190:193], v[50:53]
	v_mfma_f32_16x16x32_bf16 v[38:41], v[170:173], v[198:201], v[38:41]
	v_mfma_f32_16x16x32_bf16 v[34:37], v[178:181], v[198:201], v[34:37]
	v_mfma_f32_16x16x32_bf16 v[22:25], v[170:173], v[206:209], v[22:25]
	v_mfma_f32_16x16x32_bf16 v[18:21], v[178:181], v[206:209], v[18:21]
	v_mfma_f32_16x16x32_bf16 v[6:9], v[170:173], v[214:217], v[6:9]
	v_mfma_f32_16x16x32_bf16 v[2:5], v[178:181], v[214:217], v[2:5]
	v_mfma_f32_16x16x32_bf16 v[54:57], v[174:177], v[194:197], v[54:57]
	v_mfma_f32_16x16x32_bf16 v[50:53], v[186:189], v[194:197], v[50:53]
	v_mfma_f32_16x16x32_bf16 v[38:41], v[174:177], v[202:205], v[38:41]
	v_mfma_f32_16x16x32_bf16 v[34:37], v[186:189], v[202:205], v[34:37]
	v_mfma_f32_16x16x32_bf16 v[22:25], v[174:177], v[210:213], v[22:25]
	v_mfma_f32_16x16x32_bf16 v[18:21], v[186:189], v[210:213], v[18:21]
	v_mfma_f32_16x16x32_bf16 v[6:9], v[174:177], v[218:221], v[6:9]
	v_mfma_f32_16x16x32_bf16 v[2:5], v[186:189], v[218:221], v[2:5]
	s_setprio 0
	s_barrier
	s_add_i32 s62, s62, 2
	s_add_u32 s36, s36, 0x100
	s_addc_u32 s37, s37, 0
	s_add_u32 s60, s60, 0x100
	s_addc_u32 s61, s61, 0
	s_cmp_gt_u32 s62, 41
	s_cbranch_scc0 .LBB0_278
	s_and_b64 vcc, exec, s[18:19]
	s_cbranch_vccz .LBB0_281
	s_barrier

; #define PG8_STAGE(bufoff, gbase, voff) do { _Pragma("unroll") for (int _i = 0; _i < 2; ++_i) \
;         __builtin_amdgcn_global_load_lds((const unsigned*)((const char*)(gbase) + (voff)[_i]), (LAS unsigned*)(lds + (bufoff) + ldsw + _i * 8192), 16, 0, 0); } while (0)
; #define PG8_LDA(dst, b, h) do { _Pragma("unroll") for (int m = 0; m < 4; ++m) _Pragma("unroll") for (int k = 0; k < 2; ++k) dst[m][k] = *(const LAS bf16x8*)(lds + PG8_SA(b, h) + aoff + m * 2048 + k * 1024); } while (0)
; #define PG8_LDB(dst, b, h) do { _Pragma("unroll") for (int n = 0; n < 2; ++n) _Pragma("unroll") for (int k = 0; k < 2; ++k) dst[n][k] = *(const LAS bf16x8*)(lds + PG8_SB(b, h) + boff + n * 2048 + k * 1024); } while (0)
; #define PG8_MMA(ai, bj, At, Bt) do { __builtin_amdgcn_s_setprio(1); _Pragma("unroll") for (int m = 0; m < 4; ++m) _Pragma("unroll") for (int n = 0; n < 2; ++n) _Pragma("unroll") for (int k = 0; k < 2; ++k) \
;         acc[ai][bj][m][n] = __builtin_amdgcn_mfma_f32_16x16x32_bf16(Bt[n][k], At[m][k], acc[ai][bj][m][n], 0, 0, 0); __builtin_amdgcn_s_setprio(0); } while (0)
; #define PG8_WAIT_V(n) asm volatile("s_waitcnt vmcnt(" #n ")" ::: "memory")
; #define PG8_WAIT_L(n) asm volatile("s_waitcnt lgkmcnt(" #n ")" ::: "memory")
; #define PG8_BAR __builtin_amdgcn_s_barrier()
; #define PG8_SCHED __builtin_amdgcn_sched_barrier(0)
; template <class Epi, class Sched>
; DI void gemm_phase(LAS unsigned char* lds, const Gemm g, const Sched& S, const Epi& E) {
;     ...
;             const bool last = (t == nt - 2);
;             const char* a1 = cA + (size_t)(t + 1) * kstep;
;             const char* a2 = last ? nA : cA + (size_t)(t + 2) * kstep; const char* b2 = last ? nB : cB + (size_t)(t + 2) * kstep;
;             const char* a3 = a2 + kstep; const char* b3 = b2 + kstep;
;             PG8_LDB(B0, 0, 0); PG8_LDB(B1, 0, 1); PG8_SCHED; PG8_LDA(At, 0, 0); PG8_STAGE(PG8_SA(1, 1), a1 + hstepA, voffA);
;             PG8_WAIT_V(8); PG8_WAIT_L(0); PG8_BAR; PG8_MMA(0, 0, At, B0); PG8_MMA(0, 1, At, B1); PG8_BAR; PG8_SCHED;
;             PG8_LDA(At, 0, 1); PG8_STAGE(PG8_SB(0, 0), b2, voffB); PG8_STAGE(PG8_SB(0, 1), b2 + hstepB, voffB); PG8_STAGE(PG8_SA(0, 0), a2, voffA);
;             PG8_WAIT_V(8); PG8_WAIT_L(0); PG8_BAR; PG8_MMA(1, 0, At, B0); PG8_MMA(1, 1, At, B1); PG8_BAR; PG8_SCHED;
.LBB0_381:
	ds_read_b128 v[138:141], v188
	ds_read_b128 v[142:145], v188 offset:1024
	ds_read_b128 v[176:179], v188 offset:2048
	ds_read_b128 v[198:201], v188 offset:3072
	ds_read_b128 v[202:205], v189
	ds_read_b128 v[206:209], v189 offset:1024
	ds_read_b128 v[210:213], v189 offset:2048
	ds_read_b128 v[214:217], v189 offset:3072
	s_add_u32 s64, s10, 0xfffc0080
	s_addc_u32 s65, s11, -1
	s_cmp_eq_u32 s69, 12
	s_cselect_b32 s67, s13, s65
	s_cselect_b32 s66, s29, s64
	s_cselect_b32 s65, s36, s68
	s_cselect_b32 s64, s57, s59
	v_lshl_add_u64 v[172:173], s[10:11], 0, v[162:163]
	s_add_i32 m0, s79, 0xc000
	ds_read_b128 v[218:221], v186
	ds_read_b128 v[222:225], v186 offset:1024
	ds_read_b128 v[226:229], v186 offset:2048
	ds_read_b128 v[230:233], v186 offset:3072
	ds_read_b128 v[234:237], v186 offset:4096
	ds_read_b128 v[238:241], v186 offset:5120
	ds_read_b128 v[242:245], v186 offset:6144
	ds_read_b128 v[246:249], v186 offset:7168
	global_load_lds_dwordx4 v[172:173], off
	v_lshl_add_u64 v[172:173], s[10:11], 0, v[164:165]
	s_add_i32 m0, s79, 0xe000
	s_nop 0
	global_load_lds_dwordx4 v[172:173], off
	s_waitcnt vmcnt(8)
	s_waitcnt lgkmcnt(0)
	s_barrier
	s_setprio 1
	v_mfma_f32_16x16x32_bf16 v[126:129], v[138:141], v[218:221], v[126:129]
	v_mfma_f32_16x16x32_bf16 v[122:125], v[176:179], v[218:221], v[122:125]
	v_mfma_f32_16x16x32_bf16 v[110:113], v[138:141], v[226:229], v[110:113]
	v_mfma_f32_16x16x32_bf16 v[106:109], v[176:179], v[226:229], v[106:109]
	v_mfma_f32_16x16x32_bf16 v[94:97], v[138:141], v[234:237], v[94:97]
	v_mfma_f32_16x16x32_bf16 v[90:93], v[176:179], v[234:237], v[90:93]
	v_mfma_f32_16x16x32_bf16 v[78:81], v[138:141], v[242:245], v[78:81]
	v_mfma_f32_16x16x32_bf16 v[74:77], v[176:179], v[242:245], v[74:77]
	v_mfma_f32_16x16x32_bf16 v[126:129], v[142:145], v[222:225], v[126:129]
	v_mfma_f32_16x16x32_bf16 v[122:125], v[198:201], v[222:225], v[122:125]
	v_mfma_f32_16x16x32_bf16 v[110:113], v[142:145], v[230:233], v[110:113]
	v_mfma_f32_16x16x32_bf16 v[106:109], v[198:201], v[230:233], v[106:109]
	v_mfma_f32_16x16x32_bf16 v[94:97], v[142:145], v[238:241], v[94:97]
	v_mfma_f32_16x16x32_bf16 v[90:93], v[198:201], v[238:241], v[90:93]
	v_mfma_f32_16x16x32_bf16 v[78:81], v[142:145], v[246:249], v[78:81]
	v_mfma_f32_16x16x32_bf16 v[74:77], v[198:201], v[246:249], v[74:77]
	s_setprio 0
	s_setprio 1
	v_mfma_f32_16x16x32_bf16 v[118:121], v[202:205], v[218:221], v[118:121]
	v_mfma_f32_16x16x32_bf16 v[114:117], v[210:213], v[218:221], v[114:117]
	v_mfma_f32_16x16x32_bf16 v[102:105], v[202:205], v[226:229], v[102:105]
	v_mfma_f32_16x16x32_bf16 v[98:101], v[210:213], v[226:229], v[98:101]
	v_mfma_f32_16x16x32_bf16 v[86:89], v[202:205], v[234:237], v[86:89]
	v_mfma_f32_16x16x32_bf16 v[82:85], v[210:213], v[234:237], v[82:85]
	v_mfma_f32_16x16x32_bf16 v[70:73], v[202:205], v[242:245], v[70:73]
	v_mfma_f32_16x16x32_bf16 v[66:69], v[210:213], v[242:245], v[66:69]
	v_mfma_f32_16x16x32_bf16 v[118:121], v[206:209], v[222:225], v[118:121]
	v_mfma_f32_16x16x32_bf16 v[114:117], v[214:217], v[222:225], v[114:117]
	v_mfma_f32_16x16x32_bf16 v[102:105], v[206:209], v[230:233], v[102:105]
	v_mfma_f32_16x16x32_bf16 v[98:101], v[214:217], v[230:233], v[98:101]
	v_mfma_f32_16x16x32_bf16 v[86:89], v[206:209], v[238:241], v[86:89]
	v_mfma_f32_16x16x32_bf16 v[82:85], v[214:217], v[238:241], v[82:85]
	v_mfma_f32_16x16x32_bf16 v[70:73], v[206:209], v[246:249], v[70:73]
	v_mfma_f32_16x16x32_bf16 v[66:69], v[214:217], v[246:249], v[66:69]
	s_setprio 0
	s_barrier
	s_add_i32 s70, s94, s78
	v_lshl_add_u64 v[172:173], s[64:65], 0, v[150:151]
	s_mov_b32 m0, s70
	ds_read_b128 v[218:221], v186 offset:16384
	ds_read_b128 v[222:225], v186 offset:17408
	ds_read_b128 v[226:229], v186 offset:18432
	ds_read_b128 v[230:233], v186 offset:19456
	ds_read_b128 v[234:237], v186 offset:20480
	ds_read_b128 v[238:241], v186 offset:21504
	ds_read_b128 v[242:245], v186 offset:22528
	ds_read_b128 v[246:249], v186 offset:23552
	global_load_lds_dwordx4 v[172:173], off
	s_add_i32 m0, s70, 0x2000
	s_add_u32 s70, s64, 0x40000
	v_lshl_add_u64 v[180:181], s[64:65], 0, v[154:155]
	s_addc_u32 s71, s65, 0
	s_add_i32 s72, s95, s78
	global_load_lds_dwordx4 v[180:181], off
	v_lshl_add_u64 v[250:251], s[70:71], 0, v[150:151]
	s_mov_b32 m0, s72
	v_lshl_add_u64 v[252:253], s[66:67], 0, v[152:153]
	global_load_lds_dwordx4 v[250:251], off
	v_lshl_add_u64 v[250:251], s[70:71], 0, v[154:155]
	s_add_i32 m0, s72, 0x2000
	s_nop 0
	global_load_lds_dwordx4 v[250:251], off
	v_lshl_add_u64 v[250:251], s[66:67], 0, v[148:149]
	s_mov_b32 m0, s79
	s_nop 0
	global_load_lds_dwordx4 v[250:251], off
	s_mov_b32 m0, s80
	s_nop 0
	global_load_lds_dwordx4 v[252:253], off
	s_waitcnt vmcnt(8)
	s_waitcnt lgkmcnt(0)
	s_barrier
; #define PG8_STAGE(bufoff, gbase, voff) do { _Pragma("unroll") for (int _i = 0; _i < 2; ++_i) \
;         __builtin_amdgcn_global_load_lds((const unsigned*)((const char*)(gbase) + (voff)[_i]), (LAS unsigned*)(lds + (bufoff) + ldsw + _i * 8192), 16, 0, 0); } while (0)
; #define PG8_LDA(dst, b, h) do { _Pragma("unroll") for (int m = 0; m < 4; ++m) _Pragma("unroll") for (int k = 0; k < 2; ++k) dst[m][k] = *(const LAS bf16x8*)(lds + PG8_SA(b, h) + aoff + m * 2048 + k * 1024); } while (0)
; #define PG8_LDB(dst, b, h) do { _Pragma("unroll") for (int n = 0; n < 2; ++n) _Pragma("unroll") for (int k = 0; k < 2; ++k) dst[n][k] = *(const LAS bf16x8*)(lds + PG8_SB(b, h) + boff + n * 2048 + k * 1024); } while (0)
; #define PG8_MMA(ai, bj, At, Bt) do { __builtin_amdgcn_s_setprio(1); _Pragma("unroll") for (int m = 0; m < 4; ++m) _Pragma("unroll") for (int n = 0; n < 2; ++n) _Pragma("unroll") for (int k = 0; k < 2; ++k) \
;         acc[ai][bj][m][n] = __builtin_amdgcn_mfma_f32_16x16x32_bf16(Bt[n][k], At[m][k], acc[ai][bj][m][n], 0, 0, 0); __builtin_amdgcn_s_setprio(0); } while (0)
; #define PG8_WAIT_V(n) asm volatile("s_waitcnt vmcnt(" #n ")" ::: "memory")
; #define PG8_WAIT_L(n) asm volatile("s_waitcnt lgkmcnt(" #n ")" ::: "memory")
; #define PG8_BAR __builtin_amdgcn_s_barrier()
; #define PG8_SCHED __builtin_amdgcn_sched_barrier(0)
; template <class Epi, class Sched>
; DI void gemm_phase(LAS unsigned char* lds, const Gemm g, const Sched& S, const Epi& E) {
;     ...
;             PG8_WAIT_V(8); PG8_WAIT_L(0); PG8_BAR; PG8_MMA(1, 0, At, B0); PG8_MMA(1, 1, At, B1); PG8_BAR; PG8_SCHED;
;             PG8_LDB(B0, 1, 0); PG8_LDB(B1, 1, 1); PG8_SCHED; PG8_LDA(At, 1, 0); PG8_STAGE(PG8_SA(0, 1), a2 + hstepA, voffA);
;             PG8_WAIT_V(8); PG8_WAIT_L(0); PG8_BAR; PG8_MMA(0, 0, At, B0); PG8_MMA(0, 1, At, B1); PG8_BAR; PG8_SCHED;
	s_setprio 1
	v_mfma_f32_16x16x32_bf16 v[62:65], v[138:141], v[218:221], v[62:65]
	v_mfma_f32_16x16x32_bf16 v[58:61], v[176:179], v[218:221], v[58:61]
	v_mfma_f32_16x16x32_bf16 v[46:49], v[138:141], v[226:229], v[46:49]
	v_mfma_f32_16x16x32_bf16 v[42:45], v[176:179], v[226:229], v[42:45]
	v_mfma_f32_16x16x32_bf16 v[30:33], v[138:141], v[234:237], v[30:33]
	v_mfma_f32_16x16x32_bf16 v[26:29], v[176:179], v[234:237], v[26:29]
	v_mfma_f32_16x16x32_bf16 v[14:17], v[138:141], v[242:245], v[14:17]
	v_mfma_f32_16x16x32_bf16 v[10:13], v[176:179], v[242:245], v[10:13]
	v_mfma_f32_16x16x32_bf16 v[62:65], v[142:145], v[222:225], v[62:65]
	v_mfma_f32_16x16x32_bf16 v[58:61], v[198:201], v[222:225], v[58:61]
	v_mfma_f32_16x16x32_bf16 v[46:49], v[142:145], v[230:233], v[46:49]
	v_mfma_f32_16x16x32_bf16 v[42:45], v[198:201], v[230:233], v[42:45]
	v_mfma_f32_16x16x32_bf16 v[30:33], v[142:145], v[238:241], v[30:33]
	v_mfma_f32_16x16x32_bf16 v[26:29], v[198:201], v[238:241], v[26:29]
	v_mfma_f32_16x16x32_bf16 v[14:17], v[142:145], v[246:249], v[14:17]
	v_mfma_f32_16x16x32_bf16 v[10:13], v[198:201], v[246:249], v[10:13]
	s_setprio 0
	s_setprio 1
	v_mfma_f32_16x16x32_bf16 v[54:57], v[202:205], v[218:221], v[54:57]
	v_mfma_f32_16x16x32_bf16 v[50:53], v[210:213], v[218:221], v[50:53]
	v_mfma_f32_16x16x32_bf16 v[38:41], v[202:205], v[226:229], v[38:41]
	v_mfma_f32_16x16x32_bf16 v[34:37], v[210:213], v[226:229], v[34:37]
	v_mfma_f32_16x16x32_bf16 v[22:25], v[202:205], v[234:237], v[22:25]
	v_mfma_f32_16x16x32_bf16 v[18:21], v[210:213], v[234:237], v[18:21]
	v_mfma_f32_16x16x32_bf16 v[6:9], v[202:205], v[242:245], v[6:9]
	v_mfma_f32_16x16x32_bf16 v[2:5], v[210:213], v[242:245], v[2:5]
	v_mfma_f32_16x16x32_bf16 v[54:57], v[206:209], v[222:225], v[54:57]
	v_mfma_f32_16x16x32_bf16 v[50:53], v[214:217], v[222:225], v[50:53]
	v_mfma_f32_16x16x32_bf16 v[38:41], v[206:209], v[230:233], v[38:41]
	v_mfma_f32_16x16x32_bf16 v[34:37], v[214:217], v[230:233], v[34:37]
	v_mfma_f32_16x16x32_bf16 v[22:25], v[206:209], v[238:241], v[22:25]
	v_mfma_f32_16x16x32_bf16 v[18:21], v[214:217], v[238:241], v[18:21]
	v_mfma_f32_16x16x32_bf16 v[6:9], v[206:209], v[246:249], v[6:9]
	v_mfma_f32_16x16x32_bf16 v[2:5], v[214:217], v[246:249], v[2:5]
	s_setprio 0
	s_barrier
	s_add_i32 s70, 0, 0x18000
	v_add_u32_e32 v156, s70, v159
	s_add_i32 s71, 0, 0x1c000
	ds_read_b128 v[138:141], v156
	ds_read_b128 v[142:145], v156 offset:1024
	ds_read_b128 v[176:179], v156 offset:2048
	ds_read_b128 v[198:201], v156 offset:3072
	v_add_u32_e32 v156, s71, v159
	ds_read_b128 v[202:205], v156
	ds_read_b128 v[206:209], v156 offset:1024
	ds_read_b128 v[210:213], v156 offset:2048
	ds_read_b128 v[214:217], v156 offset:3072
	s_add_u32 s66, s66, 0x40000
	s_addc_u32 s67, s67, 0
	s_mov_b32 m0, s81
	v_lshl_add_u64 v[254:255], s[66:67], 0, v[148:149]
	ds_read_b128 v[218:221], v186 offset:32768
	ds_read_b128 v[222:225], v186 offset:33792
	ds_read_b128 v[226:229], v186 offset:34816
	ds_read_b128 v[230:233], v186 offset:35840
	ds_read_b128 v[234:237], v186 offset:36864
	ds_read_b128 v[238:241], v186 offset:37888
	ds_read_b128 v[242:245], v186 offset:38912
	ds_read_b128 v[246:249], v186 offset:39936
	global_load_lds_dwordx4 v[254:255], off
	v_lshl_add_u64 v[254:255], s[66:67], 0, v[152:153]
	s_mov_b32 m0, s82
	s_nop 0
	global_load_lds_dwordx4 v[254:255], off
	s_waitcnt vmcnt(8)
	s_waitcnt lgkmcnt(0)
	s_barrier
	s_setprio 1
	v_mfma_f32_16x16x32_bf16 v[126:129], v[138:141], v[218:221], v[126:129]
	v_mfma_f32_16x16x32_bf16 v[122:125], v[176:179], v[218:221], v[122:125]
	v_mfma_f32_16x16x32_bf16 v[110:113], v[138:141], v[226:229], v[110:113]
	v_mfma_f32_16x16x32_bf16 v[106:109], v[176:179], v[226:229], v[106:109]
	v_mfma_f32_16x16x32_bf16 v[94:97], v[138:141], v[234:237], v[94:97]
	v_mfma_f32_16x16x32_bf16 v[90:93], v[176:179], v[234:237], v[90:93]
	v_mfma_f32_16x16x32_bf16 v[78:81], v[138:141], v[242:245], v[78:81]
	v_mfma_f32_16x16x32_bf16 v[74:77], v[176:179], v[242:245], v[74:77]
	v_mfma_f32_16x16x32_bf16 v[126:129], v[142:145], v[222:225], v[126:129]
	v_mfma_f32_16x16x32_bf16 v[122:125], v[198:201], v[222:225], v[122:125]
	v_mfma_f32_16x16x32_bf16 v[110:113], v[142:145], v[230:233], v[110:113]
	v_mfma_f32_16x16x32_bf16 v[106:109], v[198:201], v[230:233], v[106:109]
	v_mfma_f32_16x16x32_bf16 v[94:97], v[142:145], v[238:241], v[94:97]
	v_mfma_f32_16x16x32_bf16 v[90:93], v[198:201], v[238:241], v[90:93]
	v_mfma_f32_16x16x32_bf16 v[78:81], v[142:145], v[246:249], v[78:81]
	v_mfma_f32_16x16x32_bf16 v[74:77], v[198:201], v[246:249], v[74:77]
	s_setprio 0
	s_setprio 1
	v_mfma_f32_16x16x32_bf16 v[118:121], v[202:205], v[218:221], v[118:121]
	v_mfma_f32_16x16x32_bf16 v[114:117], v[210:213], v[218:221], v[114:117]
	v_mfma_f32_16x16x32_bf16 v[102:105], v[202:205], v[226:229], v[102:105]
	v_mfma_f32_16x16x32_bf16 v[98:101], v[210:213], v[226:229], v[98:101]
	v_mfma_f32_16x16x32_bf16 v[86:89], v[202:205], v[234:237], v[86:89]
	v_mfma_f32_16x16x32_bf16 v[82:85], v[210:213], v[234:237], v[82:85]
	v_mfma_f32_16x16x32_bf16 v[70:73], v[202:205], v[242:245], v[70:73]
	v_mfma_f32_16x16x32_bf16 v[66:69], v[210:213], v[242:245], v[66:69]
	v_mfma_f32_16x16x32_bf16 v[118:121], v[206:209], v[222:225], v[118:121]
	v_mfma_f32_16x16x32_bf16 v[114:117], v[214:217], v[222:225], v[114:117]
	v_mfma_f32_16x16x32_bf16 v[102:105], v[206:209], v[230:233], v[102:105]
	v_mfma_f32_16x16x32_bf16 v[98:101], v[214:217], v[230:233], v[98:101]
	v_mfma_f32_16x16x32_bf16 v[86:89], v[206:209], v[238:241], v[86:89]
	v_mfma_f32_16x16x32_bf16 v[82:85], v[214:217], v[238:241], v[82:85]
	v_mfma_f32_16x16x32_bf16 v[70:73], v[206:209], v[246:249], v[70:73]
	v_mfma_f32_16x16x32_bf16 v[66:69], v[214:217], v[246:249], v[66:69]
	s_setprio 0
	s_barrier
; #define PG8_STAGE(bufoff, gbase, voff) do { _Pragma("unroll") for (int _i = 0; _i < 2; ++_i) \
;         __builtin_amdgcn_global_load_lds((const unsigned*)((const char*)(gbase) + (voff)[_i]), (LAS unsigned*)(lds + (bufoff) + ldsw + _i * 8192), 16, 0, 0); } while (0)
; #define PG8_LDA(dst, b, h) do { _Pragma("unroll") for (int m = 0; m < 4; ++m) _Pragma("unroll") for (int k = 0; k < 2; ++k) dst[m][k] = *(const LAS bf16x8*)(lds + PG8_SA(b, h) + aoff + m * 2048 + k * 1024); } while (0)
; #define PG8_MMA(ai, bj, At, Bt) do { __builtin_amdgcn_s_setprio(1); _Pragma("unroll") for (int m = 0; m < 4; ++m) _Pragma("unroll") for (int n = 0; n < 2; ++n) _Pragma("unroll") for (int k = 0; k < 2; ++k) \
;         acc[ai][bj][m][n] = __builtin_amdgcn_mfma_f32_16x16x32_bf16(Bt[n][k], At[m][k], acc[ai][bj][m][n], 0, 0, 0); __builtin_amdgcn_s_setprio(0); } while (0)
; #define PG8_WAIT_V(n) asm volatile("s_waitcnt vmcnt(" #n ")" ::: "memory")
; #define PG8_WAIT_L(n) asm volatile("s_waitcnt lgkmcnt(" #n ")" ::: "memory")
; #define PG8_BAR __builtin_amdgcn_s_barrier()
; #define PG8_SCHED __builtin_amdgcn_sched_barrier(0)
; template <class Epi, class Sched>
; DI void gemm_phase(LAS unsigned char* lds, const Gemm g, const Sched& S, const Epi& E) {
;     ...
;             PG8_LDA(At, 1, 1); PG8_STAGE(PG8_SB(1, 0), b3, voffB); PG8_STAGE(PG8_SB(1, 1), b3 + hstepB, voffB); PG8_STAGE(PG8_SA(1, 0), a3, voffA);
;             PG8_WAIT_V(8); PG8_WAIT_L(0); PG8_BAR; PG8_MMA(1, 0, At, B0); PG8_MMA(1, 1, At, B1); PG8_BAR; PG8_SCHED;
;         }
;         if (wr == 0) PG8_BAR;
;     DI void operator()(Acc& acc, const pg8::Unit& u, int wr, int wc, int fr, int fq, const Pre& pr) const {
;         const int pn = u.pn;
;         if (pn < 5) {
;             int do_norm, slot = 0, gidx = 0; const float* gain; float scale = 1.f;
;             if (pn < 2) { do_norm = 1; gain = qng; scale = QSCALE; }
	s_add_i32 s66, s70, s78
	v_lshl_add_u64 v[172:173], v[172:173], 0, s[50:51]
	s_mov_b32 m0, s66
	ds_read_b128 v[218:221], v186 offset:49152
	ds_read_b128 v[222:225], v186 offset:50176
	ds_read_b128 v[226:229], v186 offset:51200
	ds_read_b128 v[230:233], v186 offset:52224
	ds_read_b128 v[234:237], v186 offset:53248
	ds_read_b128 v[238:241], v186 offset:54272
	ds_read_b128 v[242:245], v186 offset:55296
	ds_read_b128 v[246:249], v186 offset:56320
	global_load_lds_dwordx4 v[172:173], off
	s_add_i32 m0, s66, 0x2000
	s_add_u32 s64, s64, 0x40080
	v_lshl_add_u64 v[172:173], v[180:181], 0, s[50:51]
	s_addc_u32 s65, s65, 0
	s_add_i32 s66, s71, s78
	global_load_lds_dwordx4 v[172:173], off
	v_lshl_add_u64 v[172:173], s[64:65], 0, v[150:151]
	s_mov_b32 m0, s66
	s_nop 0
	global_load_lds_dwordx4 v[172:173], off
	v_lshl_add_u64 v[172:173], s[64:65], 0, v[154:155]
	s_add_i32 m0, s66, 0x2000
	s_nop 0
	global_load_lds_dwordx4 v[172:173], off
	v_lshl_add_u64 v[172:173], v[250:251], 0, s[50:51]
	s_mov_b32 m0, s86
	s_nop 0
	global_load_lds_dwordx4 v[172:173], off
	v_lshl_add_u64 v[172:173], v[252:253], 0, s[50:51]
	s_mov_b32 m0, s87
	s_nop 0
	global_load_lds_dwordx4 v[172:173], off
	s_waitcnt vmcnt(8)
	s_waitcnt lgkmcnt(0)
	s_barrier
	s_setprio 1
	v_mfma_f32_16x16x32_bf16 v[62:65], v[138:141], v[218:221], v[62:65]
	v_mfma_f32_16x16x32_bf16 v[58:61], v[176:179], v[218:221], v[58:61]
	v_mfma_f32_16x16x32_bf16 v[46:49], v[138:141], v[226:229], v[46:49]
	v_mfma_f32_16x16x32_bf16 v[42:45], v[176:179], v[226:229], v[42:45]
	v_mfma_f32_16x16x32_bf16 v[30:33], v[138:141], v[234:237], v[30:33]
	v_mfma_f32_16x16x32_bf16 v[26:29], v[176:179], v[234:237], v[26:29]
	v_mfma_f32_16x16x32_bf16 v[14:17], v[138:141], v[242:245], v[14:17]
	v_mfma_f32_16x16x32_bf16 v[10:13], v[176:179], v[242:245], v[10:13]
	v_mfma_f32_16x16x32_bf16 v[62:65], v[142:145], v[222:225], v[62:65]
	v_mfma_f32_16x16x32_bf16 v[58:61], v[198:201], v[222:225], v[58:61]
	v_mfma_f32_16x16x32_bf16 v[46:49], v[142:145], v[230:233], v[46:49]
	v_mfma_f32_16x16x32_bf16 v[42:45], v[198:201], v[230:233], v[42:45]
	v_mfma_f32_16x16x32_bf16 v[30:33], v[142:145], v[238:241], v[30:33]
	v_mfma_f32_16x16x32_bf16 v[26:29], v[198:201], v[238:241], v[26:29]
	v_mfma_f32_16x16x32_bf16 v[14:17], v[142:145], v[246:249], v[14:17]
	v_mfma_f32_16x16x32_bf16 v[10:13], v[198:201], v[246:249], v[10:13]
	s_setprio 0
	s_setprio 1
	v_mfma_f32_16x16x32_bf16 v[54:57], v[202:205], v[218:221], v[54:57]
	v_mfma_f32_16x16x32_bf16 v[50:53], v[210:213], v[218:221], v[50:53]
	v_mfma_f32_16x16x32_bf16 v[38:41], v[202:205], v[226:229], v[38:41]
	v_mfma_f32_16x16x32_bf16 v[34:37], v[210:213], v[226:229], v[34:37]
	v_mfma_f32_16x16x32_bf16 v[22:25], v[202:205], v[234:237], v[22:25]
	v_mfma_f32_16x16x32_bf16 v[18:21], v[210:213], v[234:237], v[18:21]
	v_mfma_f32_16x16x32_bf16 v[6:9], v[202:205], v[242:245], v[6:9]
	v_mfma_f32_16x16x32_bf16 v[2:5], v[210:213], v[242:245], v[2:5]
	v_mfma_f32_16x16x32_bf16 v[54:57], v[206:209], v[222:225], v[54:57]
	v_mfma_f32_16x16x32_bf16 v[50:53], v[214:217], v[222:225], v[50:53]
	v_mfma_f32_16x16x32_bf16 v[38:41], v[206:209], v[230:233], v[38:41]
	v_mfma_f32_16x16x32_bf16 v[34:37], v[214:217], v[230:233], v[34:37]
	v_mfma_f32_16x16x32_bf16 v[22:25], v[206:209], v[238:241], v[22:25]
	v_mfma_f32_16x16x32_bf16 v[18:21], v[214:217], v[238:241], v[18:21]
	v_mfma_f32_16x16x32_bf16 v[6:9], v[206:209], v[246:249], v[6:9]
	v_mfma_f32_16x16x32_bf16 v[2:5], v[214:217], v[246:249], v[2:5]
	s_setprio 0
	s_barrier
	s_add_i32 s69, s69, 2
	s_add_u32 s10, s10, 0x100
	s_addc_u32 s11, s11, 0
	s_add_u32 s59, s59, 0x100
	s_addc_u32 s68, s68, 0
	s_cmp_gt_u32 s69, 13
	s_cbranch_scc0 .LBB0_381
	s_and_b64 vcc, exec, s[52:53]
	s_cbranch_vccnz .LBB0_386
	s_cmp_gt_i32 s12, 4
	s_mov_b64 s[10:11], -1
	s_cbranch_scc1 .LBB0_387

; #define PG8_STAGE(bufoff, gbase, voff) do { _Pragma("unroll") for (int _i = 0; _i < 2; ++_i) \
;         __builtin_amdgcn_global_load_lds((const unsigned*)((const char*)(gbase) + (voff)[_i]), (LAS unsigned*)(lds + (bufoff) + ldsw + _i * 8192), 16, 0, 0); } while (0)
; #define PG8_LDA(dst, b, h) do { _Pragma("unroll") for (int m = 0; m < 4; ++m) _Pragma("unroll") for (int k = 0; k < 2; ++k) dst[m][k] = *(const LAS bf16x8*)(lds + PG8_SA(b, h) + aoff + m * 2048 + k * 1024); } while (0)
; #define PG8_LDB(dst, b, h) do { _Pragma("unroll") for (int n = 0; n < 2; ++n) _Pragma("unroll") for (int k = 0; k < 2; ++k) dst[n][k] = *(const LAS bf16x8*)(lds + PG8_SB(b, h) + boff + n * 2048 + k * 1024); } while (0)
; #define PG8_MMA(ai, bj, At, Bt) do { __builtin_amdgcn_s_setprio(1); _Pragma("unroll") for (int m = 0; m < 4; ++m) _Pragma("unroll") for (int n = 0; n < 2; ++n) _Pragma("unroll") for (int k = 0; k < 2; ++k) \
;         acc[ai][bj][m][n] = __builtin_amdgcn_mfma_f32_16x16x32_bf16(Bt[n][k], At[m][k], acc[ai][bj][m][n], 0, 0, 0); __builtin_amdgcn_s_setprio(0); } while (0)
; #define PG8_WAIT_V(n) asm volatile("s_waitcnt vmcnt(" #n ")" ::: "memory")
; #define PG8_WAIT_L(n) asm volatile("s_waitcnt lgkmcnt(" #n ")" ::: "memory")
; #define PG8_BAR __builtin_amdgcn_s_barrier()
; #define PG8_SCHED __builtin_amdgcn_sched_barrier(0)
; template <class Epi, class Sched>
; DI void gemm_phase(LAS unsigned char* lds, const Gemm g, const Sched& S, const Epi& E) {
;     ...
;             const bool last = (t == nt - 2);
;             const char* a1 = cA + (size_t)(t + 1) * kstep;
;             const char* a2 = last ? nA : cA + (size_t)(t + 2) * kstep; const char* b2 = last ? nB : cB + (size_t)(t + 2) * kstep;
;             const char* a3 = a2 + kstep; const char* b3 = b2 + kstep;
;             PG8_LDB(B0, 0, 0); PG8_LDB(B1, 0, 1); PG8_SCHED; PG8_LDA(At, 0, 0); PG8_STAGE(PG8_SA(1, 1), a1 + hstepA, voffA);
;             PG8_WAIT_V(8); PG8_WAIT_L(0); PG8_BAR; PG8_MMA(0, 0, At, B0); PG8_MMA(0, 1, At, B1); PG8_BAR; PG8_SCHED;
;             PG8_LDA(At, 0, 1); PG8_STAGE(PG8_SB(0, 0), b2, voffB); PG8_STAGE(PG8_SB(0, 1), b2 + hstepB, voffB); PG8_STAGE(PG8_SA(0, 0), a2, voffA);
;             PG8_WAIT_V(8); PG8_WAIT_L(0); PG8_BAR; PG8_MMA(1, 0, At, B0); PG8_MMA(1, 1, At, B1); PG8_BAR; PG8_SCHED;
.LBB0_579:
	ds_read_b128 v[150:153], v142
	ds_read_b128 v[154:157], v142 offset:1024
	ds_read_b128 v[158:161], v142 offset:2048
	ds_read_b128 v[162:165], v142 offset:3072
	ds_read_b128 v[166:169], v143
	ds_read_b128 v[170:173], v143 offset:1024
	ds_read_b128 v[174:177], v143 offset:2048
	ds_read_b128 v[178:181], v143 offset:3072
	s_add_u32 s16, s8, s12
	s_addc_u32 s17, s9, s13
	s_add_u32 s16, s16, 0x100
	s_addc_u32 s17, s17, 0
	s_add_u32 s52, s39, s12
	s_addc_u32 s53, s40, s13
	s_cmpk_eq_i32 s12, 0xf00
	s_cselect_b32 s19, s9, s17
	s_cselect_b32 s18, s8, s16
	s_cselect_b32 s17, s7, s53
	s_cselect_b32 s16, s6, s52
	s_mov_b32 m0, s42
	v_lshl_add_u64 v[182:183], v[138:139], 0, s[12:13]
	ds_read_b128 v[186:189], v145
	ds_read_b128 v[190:193], v145 offset:1024
	ds_read_b128 v[194:197], v145 offset:2048
	ds_read_b128 v[198:201], v145 offset:3072
	ds_read_b128 v[202:205], v145 offset:4096
	ds_read_b128 v[206:209], v145 offset:5120
	ds_read_b128 v[210:213], v145 offset:6144
	ds_read_b128 v[214:217], v145 offset:7168
	global_load_lds_dwordx4 v[182:183], off
	v_lshl_add_u64 v[182:183], v[140:141], 0, s[12:13]
	s_mov_b32 m0, s43
	s_nop 0
	global_load_lds_dwordx4 v[182:183], off
	s_waitcnt vmcnt(8)
	s_waitcnt lgkmcnt(0)
	s_barrier
	s_setprio 1
	v_mfma_f32_16x16x32_bf16 v[126:129], v[150:153], v[186:189], v[126:129]
	v_mfma_f32_16x16x32_bf16 v[122:125], v[158:161], v[186:189], v[122:125]
	v_mfma_f32_16x16x32_bf16 v[118:121], v[150:153], v[194:197], v[118:121]
	v_mfma_f32_16x16x32_bf16 v[114:117], v[158:161], v[194:197], v[114:117]
	v_mfma_f32_16x16x32_bf16 v[110:113], v[150:153], v[202:205], v[110:113]
	v_mfma_f32_16x16x32_bf16 v[106:109], v[158:161], v[202:205], v[106:109]
	v_mfma_f32_16x16x32_bf16 v[102:105], v[150:153], v[210:213], v[102:105]
	v_mfma_f32_16x16x32_bf16 v[98:101], v[158:161], v[210:213], v[98:101]
	v_mfma_f32_16x16x32_bf16 v[126:129], v[154:157], v[190:193], v[126:129]
	v_mfma_f32_16x16x32_bf16 v[122:125], v[162:165], v[190:193], v[122:125]
	v_mfma_f32_16x16x32_bf16 v[118:121], v[154:157], v[198:201], v[118:121]
	v_mfma_f32_16x16x32_bf16 v[114:117], v[162:165], v[198:201], v[114:117]
	v_mfma_f32_16x16x32_bf16 v[110:113], v[154:157], v[206:209], v[110:113]
	v_mfma_f32_16x16x32_bf16 v[106:109], v[162:165], v[206:209], v[106:109]
	v_mfma_f32_16x16x32_bf16 v[102:105], v[154:157], v[214:217], v[102:105]
	v_mfma_f32_16x16x32_bf16 v[98:101], v[162:165], v[214:217], v[98:101]
	s_setprio 0
	s_setprio 1
	v_mfma_f32_16x16x32_bf16 v[62:65], v[166:169], v[186:189], v[62:65]
	v_mfma_f32_16x16x32_bf16 v[58:61], v[174:177], v[186:189], v[58:61]
	v_mfma_f32_16x16x32_bf16 v[54:57], v[166:169], v[194:197], v[54:57]
	v_mfma_f32_16x16x32_bf16 v[50:53], v[174:177], v[194:197], v[50:53]
	v_mfma_f32_16x16x32_bf16 v[46:49], v[166:169], v[202:205], v[46:49]
	v_mfma_f32_16x16x32_bf16 v[42:45], v[174:177], v[202:205], v[42:45]
	v_mfma_f32_16x16x32_bf16 v[38:41], v[166:169], v[210:213], v[38:41]
	v_mfma_f32_16x16x32_bf16 v[34:37], v[174:177], v[210:213], v[34:37]
	v_mfma_f32_16x16x32_bf16 v[62:65], v[170:173], v[190:193], v[62:65]
	v_mfma_f32_16x16x32_bf16 v[58:61], v[178:181], v[190:193], v[58:61]
	v_mfma_f32_16x16x32_bf16 v[54:57], v[170:173], v[198:201], v[54:57]
	v_mfma_f32_16x16x32_bf16 v[50:53], v[178:181], v[198:201], v[50:53]
	v_mfma_f32_16x16x32_bf16 v[46:49], v[170:173], v[206:209], v[46:49]
	v_mfma_f32_16x16x32_bf16 v[42:45], v[178:181], v[206:209], v[42:45]
	v_mfma_f32_16x16x32_bf16 v[38:41], v[170:173], v[214:217], v[38:41]
	v_mfma_f32_16x16x32_bf16 v[34:37], v[178:181], v[214:217], v[34:37]
	s_setprio 0
	s_barrier
	s_mov_b32 m0, s44
	v_lshl_add_u64 v[182:183], s[16:17], 0, v[134:135]
	s_add_u32 s52, s16, 0x80000
	ds_read_b128 v[186:189], v145 offset:16384
	ds_read_b128 v[190:193], v145 offset:17408
	ds_read_b128 v[194:197], v145 offset:18432
	ds_read_b128 v[198:201], v145 offset:19456
	ds_read_b128 v[202:205], v145 offset:20480
	ds_read_b128 v[206:209], v145 offset:21504
	ds_read_b128 v[210:213], v145 offset:22528
	ds_read_b128 v[214:217], v145 offset:23552
	global_load_lds_dwordx4 v[182:183], off
	v_lshl_add_u64 v[218:219], s[16:17], 0, v[130:131]
	s_mov_b32 m0, s45
	s_addc_u32 s53, s17, 0
	global_load_lds_dwordx4 v[218:219], off
	v_lshl_add_u64 v[220:221], s[52:53], 0, v[134:135]
	s_mov_b32 m0, s46
	v_lshl_add_u64 v[222:223], s[18:19], 0, v[132:133]
	global_load_lds_dwordx4 v[220:221], off
	v_lshl_add_u64 v[220:221], s[52:53], 0, v[130:131]
	s_mov_b32 m0, s47
	s_nop 0
	global_load_lds_dwordx4 v[220:221], off
	v_lshl_add_u64 v[220:221], s[18:19], 0, v[136:137]
	s_mov_b32 m0, s28
	s_nop 0
	global_load_lds_dwordx4 v[220:221], off
	s_mov_b32 m0, s29
	s_nop 0
	global_load_lds_dwordx4 v[222:223], off
	s_waitcnt vmcnt(8)
	s_waitcnt lgkmcnt(0)
	s_barrier
; #define PG8_STAGE(bufoff, gbase, voff) do { _Pragma("unroll") for (int _i = 0; _i < 2; ++_i) \
;         __builtin_amdgcn_global_load_lds((const unsigned*)((const char*)(gbase) + (voff)[_i]), (LAS unsigned*)(lds + (bufoff) + ldsw + _i * 8192), 16, 0, 0); } while (0)
; #define PG8_LDA(dst, b, h) do { _Pragma("unroll") for (int m = 0; m < 4; ++m) _Pragma("unroll") for (int k = 0; k < 2; ++k) dst[m][k] = *(const LAS bf16x8*)(lds + PG8_SA(b, h) + aoff + m * 2048 + k * 1024); } while (0)
; #define PG8_LDB(dst, b, h) do { _Pragma("unroll") for (int n = 0; n < 2; ++n) _Pragma("unroll") for (int k = 0; k < 2; ++k) dst[n][k] = *(const LAS bf16x8*)(lds + PG8_SB(b, h) + boff + n * 2048 + k * 1024); } while (0)
; #define PG8_MMA(ai, bj, At, Bt) do { __builtin_amdgcn_s_setprio(1); _Pragma("unroll") for (int m = 0; m < 4; ++m) _Pragma("unroll") for (int n = 0; n < 2; ++n) _Pragma("unroll") for (int k = 0; k < 2; ++k) \
;         acc[ai][bj][m][n] = __builtin_amdgcn_mfma_f32_16x16x32_bf16(Bt[n][k], At[m][k], acc[ai][bj][m][n], 0, 0, 0); __builtin_amdgcn_s_setprio(0); } while (0)
; #define PG8_WAIT_V(n) asm volatile("s_waitcnt vmcnt(" #n ")" ::: "memory")
; #define PG8_WAIT_L(n) asm volatile("s_waitcnt lgkmcnt(" #n ")" ::: "memory")
; #define PG8_BAR __builtin_amdgcn_s_barrier()
; #define PG8_SCHED __builtin_amdgcn_sched_barrier(0)
; template <class Epi, class Sched>
; DI void gemm_phase(LAS unsigned char* lds, const Gemm g, const Sched& S, const Epi& E) {
;     ...
;             PG8_WAIT_V(8); PG8_WAIT_L(0); PG8_BAR; PG8_MMA(1, 0, At, B0); PG8_MMA(1, 1, At, B1); PG8_BAR; PG8_SCHED;
;             PG8_LDB(B0, 1, 0); PG8_LDB(B1, 1, 1); PG8_SCHED; PG8_LDA(At, 1, 0); PG8_STAGE(PG8_SA(0, 1), a2 + hstepA, voffA);
;             PG8_WAIT_V(8); PG8_WAIT_L(0); PG8_BAR; PG8_MMA(0, 0, At, B0); PG8_MMA(0, 1, At, B1); PG8_BAR; PG8_SCHED;
	s_setprio 1
	v_mfma_f32_16x16x32_bf16 v[94:97], v[150:153], v[186:189], v[94:97]
	v_mfma_f32_16x16x32_bf16 v[90:93], v[158:161], v[186:189], v[90:93]
	v_mfma_f32_16x16x32_bf16 v[86:89], v[150:153], v[194:197], v[86:89]
	v_mfma_f32_16x16x32_bf16 v[82:85], v[158:161], v[194:197], v[82:85]
	v_mfma_f32_16x16x32_bf16 v[78:81], v[150:153], v[202:205], v[78:81]
	v_mfma_f32_16x16x32_bf16 v[74:77], v[158:161], v[202:205], v[74:77]
	v_mfma_f32_16x16x32_bf16 v[70:73], v[150:153], v[210:213], v[70:73]
	v_mfma_f32_16x16x32_bf16 v[66:69], v[158:161], v[210:213], v[66:69]
	v_mfma_f32_16x16x32_bf16 v[94:97], v[154:157], v[190:193], v[94:97]
	v_mfma_f32_16x16x32_bf16 v[90:93], v[162:165], v[190:193], v[90:93]
	v_mfma_f32_16x16x32_bf16 v[86:89], v[154:157], v[198:201], v[86:89]
	v_mfma_f32_16x16x32_bf16 v[82:85], v[162:165], v[198:201], v[82:85]
	v_mfma_f32_16x16x32_bf16 v[78:81], v[154:157], v[206:209], v[78:81]
	v_mfma_f32_16x16x32_bf16 v[74:77], v[162:165], v[206:209], v[74:77]
	v_mfma_f32_16x16x32_bf16 v[70:73], v[154:157], v[214:217], v[70:73]
	v_mfma_f32_16x16x32_bf16 v[66:69], v[162:165], v[214:217], v[66:69]
	s_setprio 0
	s_setprio 1
	v_mfma_f32_16x16x32_bf16 v[30:33], v[166:169], v[186:189], v[30:33]
	v_mfma_f32_16x16x32_bf16 v[26:29], v[174:177], v[186:189], v[26:29]
	v_mfma_f32_16x16x32_bf16 v[22:25], v[166:169], v[194:197], v[22:25]
	v_mfma_f32_16x16x32_bf16 v[18:21], v[174:177], v[194:197], v[18:21]
	v_mfma_f32_16x16x32_bf16 v[14:17], v[166:169], v[202:205], v[14:17]
	v_mfma_f32_16x16x32_bf16 v[10:13], v[174:177], v[202:205], v[10:13]
	v_mfma_f32_16x16x32_bf16 v[6:9], v[166:169], v[210:213], v[6:9]
	v_mfma_f32_16x16x32_bf16 v[2:5], v[174:177], v[210:213], v[2:5]
	v_mfma_f32_16x16x32_bf16 v[30:33], v[170:173], v[190:193], v[30:33]
	v_mfma_f32_16x16x32_bf16 v[26:29], v[178:181], v[190:193], v[26:29]
	v_mfma_f32_16x16x32_bf16 v[22:25], v[170:173], v[198:201], v[22:25]
	v_mfma_f32_16x16x32_bf16 v[18:21], v[178:181], v[198:201], v[18:21]
	v_mfma_f32_16x16x32_bf16 v[14:17], v[170:173], v[206:209], v[14:17]
	v_mfma_f32_16x16x32_bf16 v[10:13], v[178:181], v[206:209], v[10:13]
	v_mfma_f32_16x16x32_bf16 v[6:9], v[170:173], v[214:217], v[6:9]
	v_mfma_f32_16x16x32_bf16 v[2:5], v[178:181], v[214:217], v[2:5]
	s_setprio 0
	s_barrier
	ds_read_b128 v[150:153], v147
	ds_read_b128 v[154:157], v147 offset:1024
	ds_read_b128 v[158:161], v147 offset:2048
	ds_read_b128 v[162:165], v147 offset:3072
	ds_read_b128 v[166:169], v148
	ds_read_b128 v[170:173], v148 offset:1024
	ds_read_b128 v[174:177], v148 offset:2048
	ds_read_b128 v[178:181], v148 offset:3072
	s_add_u32 s18, s18, 0x40000
	s_addc_u32 s19, s19, 0
	s_mov_b32 m0, s34
	v_lshl_add_u64 v[224:225], s[18:19], 0, v[136:137]
	ds_read_b128 v[186:189], v145 offset:32768
	ds_read_b128 v[190:193], v145 offset:33792
	ds_read_b128 v[194:197], v145 offset:34816
	ds_read_b128 v[198:201], v145 offset:35840
	ds_read_b128 v[202:205], v145 offset:36864
	ds_read_b128 v[206:209], v145 offset:37888
	ds_read_b128 v[210:213], v145 offset:38912
	ds_read_b128 v[214:217], v145 offset:39936
	global_load_lds_dwordx4 v[224:225], off
	v_lshl_add_u64 v[224:225], s[18:19], 0, v[132:133]
	s_mov_b32 m0, s35
	s_nop 0
	global_load_lds_dwordx4 v[224:225], off
	s_waitcnt vmcnt(8)
	s_waitcnt lgkmcnt(0)
	s_barrier
	s_setprio 1
	v_mfma_f32_16x16x32_bf16 v[126:129], v[150:153], v[186:189], v[126:129]
	v_mfma_f32_16x16x32_bf16 v[122:125], v[158:161], v[186:189], v[122:125]
	v_mfma_f32_16x16x32_bf16 v[118:121], v[150:153], v[194:197], v[118:121]
	v_mfma_f32_16x16x32_bf16 v[114:117], v[158:161], v[194:197], v[114:117]
	v_mfma_f32_16x16x32_bf16 v[110:113], v[150:153], v[202:205], v[110:113]
	v_mfma_f32_16x16x32_bf16 v[106:109], v[158:161], v[202:205], v[106:109]
	v_mfma_f32_16x16x32_bf16 v[102:105], v[150:153], v[210:213], v[102:105]
	v_mfma_f32_16x16x32_bf16 v[98:101], v[158:161], v[210:213], v[98:101]
	v_mfma_f32_16x16x32_bf16 v[126:129], v[154:157], v[190:193], v[126:129]
	v_mfma_f32_16x16x32_bf16 v[122:125], v[162:165], v[190:193], v[122:125]
	v_mfma_f32_16x16x32_bf16 v[118:121], v[154:157], v[198:201], v[118:121]
	v_mfma_f32_16x16x32_bf16 v[114:117], v[162:165], v[198:201], v[114:117]
	v_mfma_f32_16x16x32_bf16 v[110:113], v[154:157], v[206:209], v[110:113]
	v_mfma_f32_16x16x32_bf16 v[106:109], v[162:165], v[206:209], v[106:109]
	v_mfma_f32_16x16x32_bf16 v[102:105], v[154:157], v[214:217], v[102:105]
	v_mfma_f32_16x16x32_bf16 v[98:101], v[162:165], v[214:217], v[98:101]
	s_setprio 0
	s_setprio 1
	v_mfma_f32_16x16x32_bf16 v[62:65], v[166:169], v[186:189], v[62:65]
	v_mfma_f32_16x16x32_bf16 v[58:61], v[174:177], v[186:189], v[58:61]
	v_mfma_f32_16x16x32_bf16 v[54:57], v[166:169], v[194:197], v[54:57]
	v_mfma_f32_16x16x32_bf16 v[50:53], v[174:177], v[194:197], v[50:53]
	v_mfma_f32_16x16x32_bf16 v[46:49], v[166:169], v[202:205], v[46:49]
	v_mfma_f32_16x16x32_bf16 v[42:45], v[174:177], v[202:205], v[42:45]
	v_mfma_f32_16x16x32_bf16 v[38:41], v[166:169], v[210:213], v[38:41]
	v_mfma_f32_16x16x32_bf16 v[34:37], v[174:177], v[210:213], v[34:37]
	v_mfma_f32_16x16x32_bf16 v[62:65], v[170:173], v[190:193], v[62:65]
	v_mfma_f32_16x16x32_bf16 v[58:61], v[178:181], v[190:193], v[58:61]
	v_mfma_f32_16x16x32_bf16 v[54:57], v[170:173], v[198:201], v[54:57]
	v_mfma_f32_16x16x32_bf16 v[50:53], v[178:181], v[198:201], v[50:53]
	v_mfma_f32_16x16x32_bf16 v[46:49], v[170:173], v[206:209], v[46:49]
	v_mfma_f32_16x16x32_bf16 v[42:45], v[178:181], v[206:209], v[42:45]
	v_mfma_f32_16x16x32_bf16 v[38:41], v[170:173], v[214:217], v[38:41]
	v_mfma_f32_16x16x32_bf16 v[34:37], v[178:181], v[214:217], v[34:37]
	s_setprio 0
	s_barrier
; #define PG8_STAGE(bufoff, gbase, voff) do { _Pragma("unroll") for (int _i = 0; _i < 2; ++_i) \
;         __builtin_amdgcn_global_load_lds((const unsigned*)((const char*)(gbase) + (voff)[_i]), (LAS unsigned*)(lds + (bufoff) + ldsw + _i * 8192), 16, 0, 0); } while (0)
; #define PG8_LDA(dst, b, h) do { _Pragma("unroll") for (int m = 0; m < 4; ++m) _Pragma("unroll") for (int k = 0; k < 2; ++k) dst[m][k] = *(const LAS bf16x8*)(lds + PG8_SA(b, h) + aoff + m * 2048 + k * 1024); } while (0)
; #define PG8_MMA(ai, bj, At, Bt) do { __builtin_amdgcn_s_setprio(1); _Pragma("unroll") for (int m = 0; m < 4; ++m) _Pragma("unroll") for (int n = 0; n < 2; ++n) _Pragma("unroll") for (int k = 0; k < 2; ++k) \
;         acc[ai][bj][m][n] = __builtin_amdgcn_mfma_f32_16x16x32_bf16(Bt[n][k], At[m][k], acc[ai][bj][m][n], 0, 0, 0); __builtin_amdgcn_s_setprio(0); } while (0)
; #define PG8_WAIT_V(n) asm volatile("s_waitcnt vmcnt(" #n ")" ::: "memory")
; #define PG8_WAIT_L(n) asm volatile("s_waitcnt lgkmcnt(" #n ")" ::: "memory")
; #define PG8_BAR __builtin_amdgcn_s_barrier()
; #define PG8_SCHED __builtin_amdgcn_sched_barrier(0)
; template <class Epi, class Sched>
; DI void gemm_phase(LAS unsigned char* lds, const Gemm g, const Sched& S, const Epi& E) {
;     ...
;             PG8_LDA(At, 1, 1); PG8_STAGE(PG8_SB(1, 0), b3, voffB); PG8_STAGE(PG8_SB(1, 1), b3 + hstepB, voffB); PG8_STAGE(PG8_SA(1, 0), a3, voffA);
;             PG8_WAIT_V(8); PG8_WAIT_L(0); PG8_BAR; PG8_MMA(1, 0, At, B0); PG8_MMA(1, 1, At, B1); PG8_BAR; PG8_SCHED;
;         }
;         if (wr == 0) PG8_BAR;
	s_mov_b32 m0, s48
	v_lshl_add_u64 v[182:183], v[182:183], 0, s[10:11]
	s_add_u32 s16, s16, 0x80080
	ds_read_b128 v[186:189], v145 offset:49152
	ds_read_b128 v[190:193], v145 offset:50176
	ds_read_b128 v[194:197], v145 offset:51200
	ds_read_b128 v[198:201], v145 offset:52224
	ds_read_b128 v[202:205], v145 offset:53248
	ds_read_b128 v[206:209], v145 offset:54272
	ds_read_b128 v[210:213], v145 offset:55296
	ds_read_b128 v[214:217], v145 offset:56320
	global_load_lds_dwordx4 v[182:183], off
	v_lshl_add_u64 v[182:183], v[218:219], 0, s[10:11]
	s_mov_b32 m0, s49
	s_addc_u32 s17, s17, 0
	global_load_lds_dwordx4 v[182:183], off
	v_lshl_add_u64 v[182:183], s[16:17], 0, v[134:135]
	s_mov_b32 m0, s50
	s_nop 0
	global_load_lds_dwordx4 v[182:183], off
	v_lshl_add_u64 v[182:183], s[16:17], 0, v[130:131]
	s_mov_b32 m0, s51
	s_nop 0
	global_load_lds_dwordx4 v[182:183], off
	v_lshl_add_u64 v[182:183], v[220:221], 0, s[10:11]
	s_mov_b32 m0, s37
	s_nop 0
	global_load_lds_dwordx4 v[182:183], off
	v_lshl_add_u64 v[182:183], v[222:223], 0, s[10:11]
	s_mov_b32 m0, s38
	s_nop 0
	global_load_lds_dwordx4 v[182:183], off
	s_waitcnt vmcnt(8)
	s_waitcnt lgkmcnt(0)
	s_barrier
	s_setprio 1
	v_mfma_f32_16x16x32_bf16 v[94:97], v[150:153], v[186:189], v[94:97]
	v_mfma_f32_16x16x32_bf16 v[90:93], v[158:161], v[186:189], v[90:93]
	v_mfma_f32_16x16x32_bf16 v[86:89], v[150:153], v[194:197], v[86:89]
	v_mfma_f32_16x16x32_bf16 v[82:85], v[158:161], v[194:197], v[82:85]
	v_mfma_f32_16x16x32_bf16 v[78:81], v[150:153], v[202:205], v[78:81]
	v_mfma_f32_16x16x32_bf16 v[74:77], v[158:161], v[202:205], v[74:77]
	v_mfma_f32_16x16x32_bf16 v[70:73], v[150:153], v[210:213], v[70:73]
	v_mfma_f32_16x16x32_bf16 v[66:69], v[158:161], v[210:213], v[66:69]
	v_mfma_f32_16x16x32_bf16 v[94:97], v[154:157], v[190:193], v[94:97]
	v_mfma_f32_16x16x32_bf16 v[90:93], v[162:165], v[190:193], v[90:93]
	v_mfma_f32_16x16x32_bf16 v[86:89], v[154:157], v[198:201], v[86:89]
	v_mfma_f32_16x16x32_bf16 v[82:85], v[162:165], v[198:201], v[82:85]
	v_mfma_f32_16x16x32_bf16 v[78:81], v[154:157], v[206:209], v[78:81]
	v_mfma_f32_16x16x32_bf16 v[74:77], v[162:165], v[206:209], v[74:77]
	v_mfma_f32_16x16x32_bf16 v[70:73], v[154:157], v[214:217], v[70:73]
	v_mfma_f32_16x16x32_bf16 v[66:69], v[162:165], v[214:217], v[66:69]
	s_setprio 0
	s_setprio 1
	v_mfma_f32_16x16x32_bf16 v[30:33], v[166:169], v[186:189], v[30:33]
	v_mfma_f32_16x16x32_bf16 v[26:29], v[174:177], v[186:189], v[26:29]
	v_mfma_f32_16x16x32_bf16 v[22:25], v[166:169], v[194:197], v[22:25]
	v_mfma_f32_16x16x32_bf16 v[18:21], v[174:177], v[194:197], v[18:21]
	v_mfma_f32_16x16x32_bf16 v[14:17], v[166:169], v[202:205], v[14:17]
	v_mfma_f32_16x16x32_bf16 v[10:13], v[174:177], v[202:205], v[10:13]
	v_mfma_f32_16x16x32_bf16 v[6:9], v[166:169], v[210:213], v[6:9]
	v_mfma_f32_16x16x32_bf16 v[2:5], v[174:177], v[210:213], v[2:5]
	v_mfma_f32_16x16x32_bf16 v[30:33], v[170:173], v[190:193], v[30:33]
	v_mfma_f32_16x16x32_bf16 v[26:29], v[178:181], v[190:193], v[26:29]
	v_mfma_f32_16x16x32_bf16 v[22:25], v[170:173], v[198:201], v[22:25]
	v_mfma_f32_16x16x32_bf16 v[18:21], v[178:181], v[198:201], v[18:21]
	v_mfma_f32_16x16x32_bf16 v[14:17], v[170:173], v[206:209], v[14:17]
	v_mfma_f32_16x16x32_bf16 v[10:13], v[178:181], v[206:209], v[10:13]
	v_mfma_f32_16x16x32_bf16 v[6:9], v[170:173], v[214:217], v[6:9]
	v_mfma_f32_16x16x32_bf16 v[2:5], v[178:181], v[214:217], v[2:5]
	s_setprio 0
	s_barrier
	s_add_i32 s41, s41, 2
	s_add_u32 s12, s12, 0x100
	s_addc_u32 s13, s13, 0
	s_cmp_gt_u32 s41, 29
	s_cbranch_scc0 .LBB0_579
	s_cmpk_lt_u32 s21, 0x100
	s_cbranch_scc0 .LBB0_582
	s_barrier

; #define PG8_STAGE(bufoff, gbase, voff) do { _Pragma("unroll") for (int _i = 0; _i < 2; ++_i) \
;         __builtin_amdgcn_global_load_lds((const unsigned*)((const char*)(gbase) + (voff)[_i]), (LAS unsigned*)(lds + (bufoff) + ldsw + _i * 8192), 16, 0, 0); } while (0)
; #define PG8_LDA(dst, b, h) do { _Pragma("unroll") for (int m = 0; m < 4; ++m) _Pragma("unroll") for (int k = 0; k < 2; ++k) dst[m][k] = *(const LAS bf16x8*)(lds + PG8_SA(b, h) + aoff + m * 2048 + k * 1024); } while (0)
; #define PG8_LDB(dst, b, h) do { _Pragma("unroll") for (int n = 0; n < 2; ++n) _Pragma("unroll") for (int k = 0; k < 2; ++k) dst[n][k] = *(const LAS bf16x8*)(lds + PG8_SB(b, h) + boff + n * 2048 + k * 1024); } while (0)
; #define PG8_MMA(ai, bj, At, Bt) do { __builtin_amdgcn_s_setprio(1); _Pragma("unroll") for (int m = 0; m < 4; ++m) _Pragma("unroll") for (int n = 0; n < 2; ++n) _Pragma("unroll") for (int k = 0; k < 2; ++k) \
;         acc[ai][bj][m][n] = __builtin_amdgcn_mfma_f32_16x16x32_bf16(Bt[n][k], At[m][k], acc[ai][bj][m][n], 0, 0, 0); __builtin_amdgcn_s_setprio(0); } while (0)
; #define PG8_WAIT_V(n) asm volatile("s_waitcnt vmcnt(" #n ")" ::: "memory")
; #define PG8_WAIT_L(n) asm volatile("s_waitcnt lgkmcnt(" #n ")" ::: "memory")
; #define PG8_BAR __builtin_amdgcn_s_barrier()
; #define PG8_SCHED __builtin_amdgcn_sched_barrier(0)
; template <class Epi, class Sched>
; DI void gemm_phase(LAS unsigned char* lds, const Gemm g, const Sched& S, const Epi& E) {
;     ...
;             const bool last = (t == nt - 2);
;             const char* a1 = cA + (size_t)(t + 1) * kstep;
;             const char* a2 = last ? nA : cA + (size_t)(t + 2) * kstep; const char* b2 = last ? nB : cB + (size_t)(t + 2) * kstep;
;             const char* a3 = a2 + kstep; const char* b3 = b2 + kstep;
;             PG8_LDB(B0, 0, 0); PG8_LDB(B1, 0, 1); PG8_SCHED; PG8_LDA(At, 0, 0); PG8_STAGE(PG8_SA(1, 1), a1 + hstepA, voffA);
;             PG8_WAIT_V(8); PG8_WAIT_L(0); PG8_BAR; PG8_MMA(0, 0, At, B0); PG8_MMA(0, 1, At, B1); PG8_BAR; PG8_SCHED;
;             PG8_LDA(At, 0, 1); PG8_STAGE(PG8_SB(0, 0), b2, voffB); PG8_STAGE(PG8_SB(0, 1), b2 + hstepB, voffB); PG8_STAGE(PG8_SA(0, 0), a2, voffA);
;             PG8_WAIT_V(8); PG8_WAIT_L(0); PG8_BAR; PG8_MMA(1, 0, At, B0); PG8_MMA(1, 1, At, B1); PG8_BAR; PG8_SCHED;
.LBB0_972:
	v_add_u32_e32 v158, s64, v162
	v_add_u32_e32 v180, s65, v162
	ds_read_b128 v[146:149], v158
	ds_read_b128 v[150:153], v158 offset:1024
	ds_read_b128 v[154:157], v158 offset:2048
	ds_read_b128 v[158:161], v158 offset:3072
	ds_read_b128 v[168:171], v180
	ds_read_b128 v[172:175], v180 offset:1024
	ds_read_b128 v[176:179], v180 offset:2048
	ds_read_b128 v[180:183], v180 offset:3072
	s_add_u32 s46, s44, 0xfffe0080
	s_addc_u32 s47, s45, -1
	s_cmp_eq_u32 s72, 4
	s_cselect_b32 s49, s39, s47
	s_cselect_b32 s48, s68, s46
	s_cselect_b32 s47, s37, s71
	s_cselect_b32 s46, s69, s70
	v_lshl_add_u64 v[218:219], s[44:45], 0, v[138:139]
	s_add_i32 m0, s53, 0xc000
	ds_read_b128 v[186:189], v167
	ds_read_b128 v[190:193], v167 offset:1024
	ds_read_b128 v[194:197], v167 offset:2048
	ds_read_b128 v[198:201], v167 offset:3072
	ds_read_b128 v[202:205], v167 offset:4096
	ds_read_b128 v[206:209], v167 offset:5120
	ds_read_b128 v[210:213], v167 offset:6144
	ds_read_b128 v[214:217], v167 offset:7168
	global_load_lds_dwordx4 v[218:219], off
	v_lshl_add_u64 v[218:219], s[44:45], 0, v[140:141]
	s_add_i32 m0, s53, 0xe000
	s_nop 0
	global_load_lds_dwordx4 v[218:219], off
	s_waitcnt vmcnt(8)
	s_waitcnt lgkmcnt(0)
	s_barrier
	s_setprio 1
	v_mfma_f32_16x16x32_bf16 v[126:129], v[146:149], v[186:189], v[126:129]
	v_mfma_f32_16x16x32_bf16 v[122:125], v[154:157], v[186:189], v[122:125]
	v_mfma_f32_16x16x32_bf16 v[118:121], v[146:149], v[194:197], v[118:121]
	v_mfma_f32_16x16x32_bf16 v[114:117], v[154:157], v[194:197], v[114:117]
	v_mfma_f32_16x16x32_bf16 v[110:113], v[146:149], v[202:205], v[110:113]
	v_mfma_f32_16x16x32_bf16 v[106:109], v[154:157], v[202:205], v[106:109]
	v_mfma_f32_16x16x32_bf16 v[102:105], v[146:149], v[210:213], v[102:105]
	v_mfma_f32_16x16x32_bf16 v[98:101], v[154:157], v[210:213], v[98:101]
	v_mfma_f32_16x16x32_bf16 v[126:129], v[150:153], v[190:193], v[126:129]
	v_mfma_f32_16x16x32_bf16 v[122:125], v[158:161], v[190:193], v[122:125]
	v_mfma_f32_16x16x32_bf16 v[118:121], v[150:153], v[198:201], v[118:121]
	v_mfma_f32_16x16x32_bf16 v[114:117], v[158:161], v[198:201], v[114:117]
	v_mfma_f32_16x16x32_bf16 v[110:113], v[150:153], v[206:209], v[110:113]
	v_mfma_f32_16x16x32_bf16 v[106:109], v[158:161], v[206:209], v[106:109]
	v_mfma_f32_16x16x32_bf16 v[102:105], v[150:153], v[214:217], v[102:105]
	v_mfma_f32_16x16x32_bf16 v[98:101], v[158:161], v[214:217], v[98:101]
	s_setprio 0
	s_setprio 1
	v_mfma_f32_16x16x32_bf16 v[94:97], v[168:171], v[186:189], v[94:97]
	v_mfma_f32_16x16x32_bf16 v[90:93], v[176:179], v[186:189], v[90:93]
	v_mfma_f32_16x16x32_bf16 v[86:89], v[168:171], v[194:197], v[86:89]
	v_mfma_f32_16x16x32_bf16 v[82:85], v[176:179], v[194:197], v[82:85]
	v_mfma_f32_16x16x32_bf16 v[78:81], v[168:171], v[202:205], v[78:81]
	v_mfma_f32_16x16x32_bf16 v[74:77], v[176:179], v[202:205], v[74:77]
	v_mfma_f32_16x16x32_bf16 v[70:73], v[168:171], v[210:213], v[70:73]
	v_mfma_f32_16x16x32_bf16 v[66:69], v[176:179], v[210:213], v[66:69]
	v_mfma_f32_16x16x32_bf16 v[94:97], v[172:175], v[190:193], v[94:97]
	v_mfma_f32_16x16x32_bf16 v[90:93], v[180:183], v[190:193], v[90:93]
	v_mfma_f32_16x16x32_bf16 v[86:89], v[172:175], v[198:201], v[86:89]
	v_mfma_f32_16x16x32_bf16 v[82:85], v[180:183], v[198:201], v[82:85]
	v_mfma_f32_16x16x32_bf16 v[78:81], v[172:175], v[206:209], v[78:81]
	v_mfma_f32_16x16x32_bf16 v[74:77], v[180:183], v[206:209], v[74:77]
	v_mfma_f32_16x16x32_bf16 v[70:73], v[172:175], v[214:217], v[70:73]
	v_mfma_f32_16x16x32_bf16 v[66:69], v[180:183], v[214:217], v[66:69]
	s_setprio 0
	s_barrier
	s_add_i32 s73, s64, s52
	v_lshl_add_u64 v[218:219], s[46:47], 0, v[132:133]
	s_mov_b32 m0, s73
	ds_read_b128 v[186:189], v167 offset:16384
	ds_read_b128 v[190:193], v167 offset:17408
	ds_read_b128 v[194:197], v167 offset:18432
	ds_read_b128 v[198:201], v167 offset:19456
	ds_read_b128 v[202:205], v167 offset:20480
	ds_read_b128 v[206:209], v167 offset:21504
	ds_read_b128 v[210:213], v167 offset:22528
	ds_read_b128 v[214:217], v167 offset:23552
	global_load_lds_dwordx4 v[218:219], off
	s_add_i32 m0, s73, 0x2000
	s_add_u32 s74, s46, 0x20000
	v_lshl_add_u64 v[220:221], s[46:47], 0, v[136:137]
	s_addc_u32 s75, s47, 0
	s_add_i32 s73, s65, s52
	global_load_lds_dwordx4 v[220:221], off
	v_lshl_add_u64 v[222:223], s[74:75], 0, v[132:133]
	s_mov_b32 m0, s73
	v_lshl_add_u64 v[224:225], s[48:49], 0, v[134:135]
	global_load_lds_dwordx4 v[222:223], off
	v_lshl_add_u64 v[222:223], s[74:75], 0, v[136:137]
	s_add_i32 m0, s73, 0x2000
	s_nop 0
	global_load_lds_dwordx4 v[222:223], off
	v_lshl_add_u64 v[222:223], s[48:49], 0, v[130:131]
	s_mov_b32 m0, s53
	s_nop 0
	global_load_lds_dwordx4 v[222:223], off
	s_mov_b32 m0, s54
	s_nop 0
	global_load_lds_dwordx4 v[224:225], off
	s_waitcnt vmcnt(8)
	s_waitcnt lgkmcnt(0)
	s_barrier
; #define PG8_STAGE(bufoff, gbase, voff) do { _Pragma("unroll") for (int _i = 0; _i < 2; ++_i) \
;         __builtin_amdgcn_global_load_lds((const unsigned*)((const char*)(gbase) + (voff)[_i]), (LAS unsigned*)(lds + (bufoff) + ldsw + _i * 8192), 16, 0, 0); } while (0)
; #define PG8_LDA(dst, b, h) do { _Pragma("unroll") for (int m = 0; m < 4; ++m) _Pragma("unroll") for (int k = 0; k < 2; ++k) dst[m][k] = *(const LAS bf16x8*)(lds + PG8_SA(b, h) + aoff + m * 2048 + k * 1024); } while (0)
; #define PG8_LDB(dst, b, h) do { _Pragma("unroll") for (int n = 0; n < 2; ++n) _Pragma("unroll") for (int k = 0; k < 2; ++k) dst[n][k] = *(const LAS bf16x8*)(lds + PG8_SB(b, h) + boff + n * 2048 + k * 1024); } while (0)
; #define PG8_MMA(ai, bj, At, Bt) do { __builtin_amdgcn_s_setprio(1); _Pragma("unroll") for (int m = 0; m < 4; ++m) _Pragma("unroll") for (int n = 0; n < 2; ++n) _Pragma("unroll") for (int k = 0; k < 2; ++k) \
;         acc[ai][bj][m][n] = __builtin_amdgcn_mfma_f32_16x16x32_bf16(Bt[n][k], At[m][k], acc[ai][bj][m][n], 0, 0, 0); __builtin_amdgcn_s_setprio(0); } while (0)
; #define PG8_WAIT_V(n) asm volatile("s_waitcnt vmcnt(" #n ")" ::: "memory")
; #define PG8_WAIT_L(n) asm volatile("s_waitcnt lgkmcnt(" #n ")" ::: "memory")
; #define PG8_BAR __builtin_amdgcn_s_barrier()
; #define PG8_SCHED __builtin_amdgcn_sched_barrier(0)
; template <class Epi, class Sched>
; DI void gemm_phase(LAS unsigned char* lds, const Gemm g, const Sched& S, const Epi& E) {
;     ...
;             PG8_WAIT_V(8); PG8_WAIT_L(0); PG8_BAR; PG8_MMA(1, 0, At, B0); PG8_MMA(1, 1, At, B1); PG8_BAR; PG8_SCHED;
;             PG8_LDB(B0, 1, 0); PG8_LDB(B1, 1, 1); PG8_SCHED; PG8_LDA(At, 1, 0); PG8_STAGE(PG8_SA(0, 1), a2 + hstepA, voffA);
;             PG8_WAIT_V(8); PG8_WAIT_L(0); PG8_BAR; PG8_MMA(0, 0, At, B0); PG8_MMA(0, 1, At, B1); PG8_BAR; PG8_SCHED;
	s_setprio 1
	v_mfma_f32_16x16x32_bf16 v[62:65], v[146:149], v[186:189], v[62:65]
	v_mfma_f32_16x16x32_bf16 v[58:61], v[154:157], v[186:189], v[58:61]
	v_mfma_f32_16x16x32_bf16 v[54:57], v[146:149], v[194:197], v[54:57]
	v_mfma_f32_16x16x32_bf16 v[50:53], v[154:157], v[194:197], v[50:53]
	v_mfma_f32_16x16x32_bf16 v[46:49], v[146:149], v[202:205], v[46:49]
	v_mfma_f32_16x16x32_bf16 v[42:45], v[154:157], v[202:205], v[42:45]
	v_mfma_f32_16x16x32_bf16 v[38:41], v[146:149], v[210:213], v[38:41]
	v_mfma_f32_16x16x32_bf16 v[34:37], v[154:157], v[210:213], v[34:37]
	v_mfma_f32_16x16x32_bf16 v[62:65], v[150:153], v[190:193], v[62:65]
	v_mfma_f32_16x16x32_bf16 v[58:61], v[158:161], v[190:193], v[58:61]
	v_mfma_f32_16x16x32_bf16 v[54:57], v[150:153], v[198:201], v[54:57]
	v_mfma_f32_16x16x32_bf16 v[50:53], v[158:161], v[198:201], v[50:53]
	v_mfma_f32_16x16x32_bf16 v[46:49], v[150:153], v[206:209], v[46:49]
	v_mfma_f32_16x16x32_bf16 v[42:45], v[158:161], v[206:209], v[42:45]
	v_mfma_f32_16x16x32_bf16 v[38:41], v[150:153], v[214:217], v[38:41]
	v_mfma_f32_16x16x32_bf16 v[34:37], v[158:161], v[214:217], v[34:37]
	s_setprio 0
	s_setprio 1
	v_mfma_f32_16x16x32_bf16 v[30:33], v[168:171], v[186:189], v[30:33]
	v_mfma_f32_16x16x32_bf16 v[26:29], v[176:179], v[186:189], v[26:29]
	v_mfma_f32_16x16x32_bf16 v[22:25], v[168:171], v[194:197], v[22:25]
	v_mfma_f32_16x16x32_bf16 v[18:21], v[176:179], v[194:197], v[18:21]
	v_mfma_f32_16x16x32_bf16 v[14:17], v[168:171], v[202:205], v[14:17]
	v_mfma_f32_16x16x32_bf16 v[10:13], v[176:179], v[202:205], v[10:13]
	v_mfma_f32_16x16x32_bf16 v[6:9], v[168:171], v[210:213], v[6:9]
	v_mfma_f32_16x16x32_bf16 v[2:5], v[176:179], v[210:213], v[2:5]
	v_mfma_f32_16x16x32_bf16 v[30:33], v[172:175], v[190:193], v[30:33]
	v_mfma_f32_16x16x32_bf16 v[26:29], v[180:183], v[190:193], v[26:29]
	v_mfma_f32_16x16x32_bf16 v[22:25], v[172:175], v[198:201], v[22:25]
	v_mfma_f32_16x16x32_bf16 v[18:21], v[180:183], v[198:201], v[18:21]
	v_mfma_f32_16x16x32_bf16 v[14:17], v[172:175], v[206:209], v[14:17]
	v_mfma_f32_16x16x32_bf16 v[10:13], v[180:183], v[206:209], v[10:13]
	v_mfma_f32_16x16x32_bf16 v[6:9], v[172:175], v[214:217], v[6:9]
	v_mfma_f32_16x16x32_bf16 v[2:5], v[180:183], v[214:217], v[2:5]
	s_setprio 0
	s_barrier
	s_add_i32 s73, 0, 0x18000
	s_add_i32 s74, 0, 0x1c000
	v_add_u32_e32 v158, s73, v162
	v_add_u32_e32 v180, s74, v162
	ds_read_b128 v[146:149], v158
	ds_read_b128 v[150:153], v158 offset:1024
	ds_read_b128 v[154:157], v158 offset:2048
	ds_read_b128 v[158:161], v158 offset:3072
	ds_read_b128 v[168:171], v180
	ds_read_b128 v[172:175], v180 offset:1024
	ds_read_b128 v[176:179], v180 offset:2048
	ds_read_b128 v[180:183], v180 offset:3072
	s_add_u32 s48, s48, 0x20000
	s_addc_u32 s49, s49, 0
	s_mov_b32 m0, s55
	v_lshl_add_u64 v[226:227], s[48:49], 0, v[130:131]
	ds_read_b128 v[186:189], v167 offset:32768
	ds_read_b128 v[190:193], v167 offset:33792
	ds_read_b128 v[194:197], v167 offset:34816
	ds_read_b128 v[198:201], v167 offset:35840
	ds_read_b128 v[202:205], v167 offset:36864
	ds_read_b128 v[206:209], v167 offset:37888
	ds_read_b128 v[210:213], v167 offset:38912
	ds_read_b128 v[214:217], v167 offset:39936
	global_load_lds_dwordx4 v[226:227], off
	v_lshl_add_u64 v[226:227], s[48:49], 0, v[134:135]
	s_mov_b32 m0, s56
	s_nop 0
	global_load_lds_dwordx4 v[226:227], off
	s_waitcnt vmcnt(8)
	s_waitcnt lgkmcnt(0)
	s_barrier
	s_setprio 1
	v_mfma_f32_16x16x32_bf16 v[126:129], v[146:149], v[186:189], v[126:129]
	v_mfma_f32_16x16x32_bf16 v[122:125], v[154:157], v[186:189], v[122:125]
	v_mfma_f32_16x16x32_bf16 v[118:121], v[146:149], v[194:197], v[118:121]
	v_mfma_f32_16x16x32_bf16 v[114:117], v[154:157], v[194:197], v[114:117]
	v_mfma_f32_16x16x32_bf16 v[110:113], v[146:149], v[202:205], v[110:113]
	v_mfma_f32_16x16x32_bf16 v[106:109], v[154:157], v[202:205], v[106:109]
	v_mfma_f32_16x16x32_bf16 v[102:105], v[146:149], v[210:213], v[102:105]
	v_mfma_f32_16x16x32_bf16 v[98:101], v[154:157], v[210:213], v[98:101]
	v_mfma_f32_16x16x32_bf16 v[126:129], v[150:153], v[190:193], v[126:129]
	v_mfma_f32_16x16x32_bf16 v[122:125], v[158:161], v[190:193], v[122:125]
	v_mfma_f32_16x16x32_bf16 v[118:121], v[150:153], v[198:201], v[118:121]
	v_mfma_f32_16x16x32_bf16 v[114:117], v[158:161], v[198:201], v[114:117]
	v_mfma_f32_16x16x32_bf16 v[110:113], v[150:153], v[206:209], v[110:113]
	v_mfma_f32_16x16x32_bf16 v[106:109], v[158:161], v[206:209], v[106:109]
	v_mfma_f32_16x16x32_bf16 v[102:105], v[150:153], v[214:217], v[102:105]
	v_mfma_f32_16x16x32_bf16 v[98:101], v[158:161], v[214:217], v[98:101]
	s_setprio 0
	s_setprio 1
	v_mfma_f32_16x16x32_bf16 v[94:97], v[168:171], v[186:189], v[94:97]
	v_mfma_f32_16x16x32_bf16 v[90:93], v[176:179], v[186:189], v[90:93]
	v_mfma_f32_16x16x32_bf16 v[86:89], v[168:171], v[194:197], v[86:89]
	v_mfma_f32_16x16x32_bf16 v[82:85], v[176:179], v[194:197], v[82:85]
	v_mfma_f32_16x16x32_bf16 v[78:81], v[168:171], v[202:205], v[78:81]
	v_mfma_f32_16x16x32_bf16 v[74:77], v[176:179], v[202:205], v[74:77]
	v_mfma_f32_16x16x32_bf16 v[70:73], v[168:171], v[210:213], v[70:73]
	v_mfma_f32_16x16x32_bf16 v[66:69], v[176:179], v[210:213], v[66:69]
	v_mfma_f32_16x16x32_bf16 v[94:97], v[172:175], v[190:193], v[94:97]
	v_mfma_f32_16x16x32_bf16 v[90:93], v[180:183], v[190:193], v[90:93]
	v_mfma_f32_16x16x32_bf16 v[86:89], v[172:175], v[198:201], v[86:89]
	v_mfma_f32_16x16x32_bf16 v[82:85], v[180:183], v[198:201], v[82:85]
	v_mfma_f32_16x16x32_bf16 v[78:81], v[172:175], v[206:209], v[78:81]
	v_mfma_f32_16x16x32_bf16 v[74:77], v[180:183], v[206:209], v[74:77]
	v_mfma_f32_16x16x32_bf16 v[70:73], v[172:175], v[214:217], v[70:73]
	v_mfma_f32_16x16x32_bf16 v[66:69], v[180:183], v[214:217], v[66:69]
	s_setprio 0
	s_barrier
; #define PG8_STAGE(bufoff, gbase, voff) do { _Pragma("unroll") for (int _i = 0; _i < 2; ++_i) \
;         __builtin_amdgcn_global_load_lds((const unsigned*)((const char*)(gbase) + (voff)[_i]), (LAS unsigned*)(lds + (bufoff) + ldsw + _i * 8192), 16, 0, 0); } while (0)
; #define PG8_LDA(dst, b, h) do { _Pragma("unroll") for (int m = 0; m < 4; ++m) _Pragma("unroll") for (int k = 0; k < 2; ++k) dst[m][k] = *(const LAS bf16x8*)(lds + PG8_SA(b, h) + aoff + m * 2048 + k * 1024); } while (0)
; #define PG8_MMA(ai, bj, At, Bt) do { __builtin_amdgcn_s_setprio(1); _Pragma("unroll") for (int m = 0; m < 4; ++m) _Pragma("unroll") for (int n = 0; n < 2; ++n) _Pragma("unroll") for (int k = 0; k < 2; ++k) \
;         acc[ai][bj][m][n] = __builtin_amdgcn_mfma_f32_16x16x32_bf16(Bt[n][k], At[m][k], acc[ai][bj][m][n], 0, 0, 0); __builtin_amdgcn_s_setprio(0); } while (0)
; #define PG8_WAIT_V(n) asm volatile("s_waitcnt vmcnt(" #n ")" ::: "memory")
; #define PG8_WAIT_L(n) asm volatile("s_waitcnt lgkmcnt(" #n ")" ::: "memory")
; #define PG8_BAR __builtin_amdgcn_s_barrier()
; #define PG8_SCHED __builtin_amdgcn_sched_barrier(0)
; template <class Epi, class Sched>
; DI void gemm_phase(LAS unsigned char* lds, const Gemm g, const Sched& S, const Epi& E) {
;     ...
;             PG8_LDA(At, 1, 1); PG8_STAGE(PG8_SB(1, 0), b3, voffB); PG8_STAGE(PG8_SB(1, 1), b3 + hstepB, voffB); PG8_STAGE(PG8_SA(1, 0), a3, voffA);
;             PG8_WAIT_V(8); PG8_WAIT_L(0); PG8_BAR; PG8_MMA(1, 0, At, B0); PG8_MMA(1, 1, At, B1); PG8_BAR; PG8_SCHED;
;         }
;         if (wr == 0) PG8_BAR;
	s_add_i32 s48, s73, s52
	v_lshl_add_u64 v[218:219], v[218:219], 0, s[20:21]
	s_mov_b32 m0, s48
	ds_read_b128 v[186:189], v167 offset:49152
	ds_read_b128 v[190:193], v167 offset:50176
	ds_read_b128 v[194:197], v167 offset:51200
	ds_read_b128 v[198:201], v167 offset:52224
	ds_read_b128 v[202:205], v167 offset:53248
	ds_read_b128 v[206:209], v167 offset:54272
	ds_read_b128 v[210:213], v167 offset:55296
	ds_read_b128 v[214:217], v167 offset:56320
	global_load_lds_dwordx4 v[218:219], off
	s_add_i32 m0, s48, 0x2000
	s_add_u32 s46, s46, 0x20080
	v_lshl_add_u64 v[218:219], v[220:221], 0, s[20:21]
	s_addc_u32 s47, s47, 0
	s_add_i32 s48, s74, s52
	global_load_lds_dwordx4 v[218:219], off
	v_lshl_add_u64 v[218:219], s[46:47], 0, v[132:133]
	s_mov_b32 m0, s48
	s_nop 0
	global_load_lds_dwordx4 v[218:219], off
	v_lshl_add_u64 v[218:219], s[46:47], 0, v[136:137]
	s_add_i32 m0, s48, 0x2000
	s_nop 0
	global_load_lds_dwordx4 v[218:219], off
	v_lshl_add_u64 v[218:219], v[222:223], 0, s[20:21]
	s_mov_b32 m0, s61
	s_nop 0
	global_load_lds_dwordx4 v[218:219], off
	v_lshl_add_u64 v[218:219], v[224:225], 0, s[20:21]
	s_mov_b32 m0, s62
	s_nop 0
	global_load_lds_dwordx4 v[218:219], off
	s_waitcnt vmcnt(8)
	s_waitcnt lgkmcnt(0)
	s_barrier
	s_setprio 1
	v_mfma_f32_16x16x32_bf16 v[62:65], v[146:149], v[186:189], v[62:65]
	v_mfma_f32_16x16x32_bf16 v[58:61], v[154:157], v[186:189], v[58:61]
	v_mfma_f32_16x16x32_bf16 v[54:57], v[146:149], v[194:197], v[54:57]
	v_mfma_f32_16x16x32_bf16 v[50:53], v[154:157], v[194:197], v[50:53]
	v_mfma_f32_16x16x32_bf16 v[46:49], v[146:149], v[202:205], v[46:49]
	v_mfma_f32_16x16x32_bf16 v[42:45], v[154:157], v[202:205], v[42:45]
	v_mfma_f32_16x16x32_bf16 v[38:41], v[146:149], v[210:213], v[38:41]
	v_mfma_f32_16x16x32_bf16 v[34:37], v[154:157], v[210:213], v[34:37]
	v_mfma_f32_16x16x32_bf16 v[62:65], v[150:153], v[190:193], v[62:65]
	v_mfma_f32_16x16x32_bf16 v[58:61], v[158:161], v[190:193], v[58:61]
	v_mfma_f32_16x16x32_bf16 v[54:57], v[150:153], v[198:201], v[54:57]
	v_mfma_f32_16x16x32_bf16 v[50:53], v[158:161], v[198:201], v[50:53]
	v_mfma_f32_16x16x32_bf16 v[46:49], v[150:153], v[206:209], v[46:49]
	v_mfma_f32_16x16x32_bf16 v[42:45], v[158:161], v[206:209], v[42:45]
	v_mfma_f32_16x16x32_bf16 v[38:41], v[150:153], v[214:217], v[38:41]
	v_mfma_f32_16x16x32_bf16 v[34:37], v[158:161], v[214:217], v[34:37]
	s_setprio 0
	s_setprio 1
	v_mfma_f32_16x16x32_bf16 v[30:33], v[168:171], v[186:189], v[30:33]
	v_mfma_f32_16x16x32_bf16 v[26:29], v[176:179], v[186:189], v[26:29]
	v_mfma_f32_16x16x32_bf16 v[22:25], v[168:171], v[194:197], v[22:25]
	v_mfma_f32_16x16x32_bf16 v[18:21], v[176:179], v[194:197], v[18:21]
	v_mfma_f32_16x16x32_bf16 v[14:17], v[168:171], v[202:205], v[14:17]
	v_mfma_f32_16x16x32_bf16 v[10:13], v[176:179], v[202:205], v[10:13]
	v_mfma_f32_16x16x32_bf16 v[6:9], v[168:171], v[210:213], v[6:9]
	v_mfma_f32_16x16x32_bf16 v[2:5], v[176:179], v[210:213], v[2:5]
	v_mfma_f32_16x16x32_bf16 v[30:33], v[172:175], v[190:193], v[30:33]
	v_mfma_f32_16x16x32_bf16 v[26:29], v[180:183], v[190:193], v[26:29]
	v_mfma_f32_16x16x32_bf16 v[22:25], v[172:175], v[198:201], v[22:25]
	v_mfma_f32_16x16x32_bf16 v[18:21], v[180:183], v[198:201], v[18:21]
	v_mfma_f32_16x16x32_bf16 v[14:17], v[172:175], v[206:209], v[14:17]
	v_mfma_f32_16x16x32_bf16 v[10:13], v[180:183], v[206:209], v[10:13]
	v_mfma_f32_16x16x32_bf16 v[6:9], v[172:175], v[214:217], v[6:9]
	v_mfma_f32_16x16x32_bf16 v[2:5], v[180:183], v[214:217], v[2:5]
	s_setprio 0
	s_barrier
	s_add_i32 s72, s72, 2
	s_add_u32 s44, s44, 0x100
	s_addc_u32 s45, s45, 0
	s_add_u32 s70, s70, 0x100
	s_addc_u32 s71, s71, 0
	s_cmp_gt_u32 s72, 5
	s_cbranch_scc0 .LBB0_972
	s_and_b64 vcc, exec, s[34:35]
	s_cbranch_vccz .LBB0_975
	s_barrier

; #define PG8_STAGE(bufoff, gbase, voff) do { _Pragma("unroll") for (int _i = 0; _i < 2; ++_i) \
;         __builtin_amdgcn_global_load_lds((const unsigned*)((const char*)(gbase) + (voff)[_i]), (LAS unsigned*)(lds + (bufoff) + ldsw + _i * 8192), 16, 0, 0); } while (0)
; #define PG8_LDA(dst, b, h) do { _Pragma("unroll") for (int m = 0; m < 4; ++m) _Pragma("unroll") for (int k = 0; k < 2; ++k) dst[m][k] = *(const LAS bf16x8*)(lds + PG8_SA(b, h) + aoff + m * 2048 + k * 1024); } while (0)
; #define PG8_LDB(dst, b, h) do { _Pragma("unroll") for (int n = 0; n < 2; ++n) _Pragma("unroll") for (int k = 0; k < 2; ++k) dst[n][k] = *(const LAS bf16x8*)(lds + PG8_SB(b, h) + boff + n * 2048 + k * 1024); } while (0)
; #define PG8_MMA(ai, bj, At, Bt) do { __builtin_amdgcn_s_setprio(1); _Pragma("unroll") for (int m = 0; m < 4; ++m) _Pragma("unroll") for (int n = 0; n < 2; ++n) _Pragma("unroll") for (int k = 0; k < 2; ++k) \
;         acc[ai][bj][m][n] = __builtin_amdgcn_mfma_f32_16x16x32_bf16(Bt[n][k], At[m][k], acc[ai][bj][m][n], 0, 0, 0); __builtin_amdgcn_s_setprio(0); } while (0)
; #define PG8_WAIT_V(n) asm volatile("s_waitcnt vmcnt(" #n ")" ::: "memory")
; #define PG8_WAIT_L(n) asm volatile("s_waitcnt lgkmcnt(" #n ")" ::: "memory")
; #define PG8_BAR __builtin_amdgcn_s_barrier()
; #define PG8_SCHED __builtin_amdgcn_sched_barrier(0)
; template <class Epi, class Sched>
; DI void gemm_phase(LAS unsigned char* lds, const Gemm g, const Sched& S, const Epi& E) {
;     ...
;             const bool last = (t == nt - 2);
;             const char* a1 = cA + (size_t)(t + 1) * kstep;
;             const char* a2 = last ? nA : cA + (size_t)(t + 2) * kstep; const char* b2 = last ? nB : cB + (size_t)(t + 2) * kstep;
;             const char* a3 = a2 + kstep; const char* b3 = b2 + kstep;
;             PG8_LDB(B0, 0, 0); PG8_LDB(B1, 0, 1); PG8_SCHED; PG8_LDA(At, 0, 0); PG8_STAGE(PG8_SA(1, 1), a1 + hstepA, voffA);
;             PG8_WAIT_V(8); PG8_WAIT_L(0); PG8_BAR; PG8_MMA(0, 0, At, B0); PG8_MMA(0, 1, At, B1); PG8_BAR; PG8_SCHED;
;             PG8_LDA(At, 0, 1); PG8_STAGE(PG8_SB(0, 0), b2, voffB); PG8_STAGE(PG8_SB(0, 1), b2 + hstepB, voffB); PG8_STAGE(PG8_SA(0, 0), a2, voffA);
;             PG8_WAIT_V(8); PG8_WAIT_L(0); PG8_BAR; PG8_MMA(1, 0, At, B0); PG8_MMA(1, 1, At, B1); PG8_BAR; PG8_SCHED;
.LBB0_1133:
	ds_read_b128 v[146:149], v152
	ds_read_b128 v[156:159], v152 offset:1024
	ds_read_b128 v[160:163], v152 offset:2048
	ds_read_b128 v[164:167], v152 offset:3072
	ds_read_b128 v[168:171], v153
	ds_read_b128 v[172:175], v153 offset:1024
	ds_read_b128 v[176:179], v153 offset:2048
	ds_read_b128 v[180:183], v153 offset:3072
	s_add_u32 s46, s44, 0xfffc0080
	s_addc_u32 s47, s45, -1
	s_cmp_eq_u32 s66, 12
	s_cselect_b32 s49, s35, s47
	s_cselect_b32 s48, s41, s46
	s_cselect_b32 s47, s21, s65
	s_cselect_b32 s46, s63, s64
	v_lshl_add_u64 v[218:219], s[44:45], 0, v[138:139]
	s_add_i32 m0, s43, 0xc000
	ds_read_b128 v[186:189], v154
	ds_read_b128 v[190:193], v154 offset:1024
	ds_read_b128 v[194:197], v154 offset:2048
	ds_read_b128 v[198:201], v154 offset:3072
	ds_read_b128 v[202:205], v154 offset:4096
	ds_read_b128 v[206:209], v154 offset:5120
	ds_read_b128 v[210:213], v154 offset:6144
	ds_read_b128 v[214:217], v154 offset:7168
	global_load_lds_dwordx4 v[218:219], off
	v_lshl_add_u64 v[218:219], s[44:45], 0, v[140:141]
	s_add_i32 m0, s43, 0xe000
	s_nop 0
	global_load_lds_dwordx4 v[218:219], off
	s_waitcnt vmcnt(8)
	s_waitcnt lgkmcnt(0)
	s_barrier
	s_setprio 1
	v_mfma_f32_16x16x32_bf16 v[126:129], v[146:149], v[186:189], v[126:129]
	v_mfma_f32_16x16x32_bf16 v[122:125], v[160:163], v[186:189], v[122:125]
	v_mfma_f32_16x16x32_bf16 v[110:113], v[146:149], v[194:197], v[110:113]
	v_mfma_f32_16x16x32_bf16 v[106:109], v[160:163], v[194:197], v[106:109]
	v_mfma_f32_16x16x32_bf16 v[94:97], v[146:149], v[202:205], v[94:97]
	v_mfma_f32_16x16x32_bf16 v[90:93], v[160:163], v[202:205], v[90:93]
	v_mfma_f32_16x16x32_bf16 v[78:81], v[146:149], v[210:213], v[78:81]
	v_mfma_f32_16x16x32_bf16 v[74:77], v[160:163], v[210:213], v[74:77]
	v_mfma_f32_16x16x32_bf16 v[126:129], v[156:159], v[190:193], v[126:129]
	v_mfma_f32_16x16x32_bf16 v[122:125], v[164:167], v[190:193], v[122:125]
	v_mfma_f32_16x16x32_bf16 v[110:113], v[156:159], v[198:201], v[110:113]
	v_mfma_f32_16x16x32_bf16 v[106:109], v[164:167], v[198:201], v[106:109]
	v_mfma_f32_16x16x32_bf16 v[94:97], v[156:159], v[206:209], v[94:97]
	v_mfma_f32_16x16x32_bf16 v[90:93], v[164:167], v[206:209], v[90:93]
	v_mfma_f32_16x16x32_bf16 v[78:81], v[156:159], v[214:217], v[78:81]
	v_mfma_f32_16x16x32_bf16 v[74:77], v[164:167], v[214:217], v[74:77]
	s_setprio 0
	s_setprio 1
	v_mfma_f32_16x16x32_bf16 v[118:121], v[168:171], v[186:189], v[118:121]
	v_mfma_f32_16x16x32_bf16 v[114:117], v[176:179], v[186:189], v[114:117]
	v_mfma_f32_16x16x32_bf16 v[102:105], v[168:171], v[194:197], v[102:105]
	v_mfma_f32_16x16x32_bf16 v[98:101], v[176:179], v[194:197], v[98:101]
	v_mfma_f32_16x16x32_bf16 v[86:89], v[168:171], v[202:205], v[86:89]
	v_mfma_f32_16x16x32_bf16 v[82:85], v[176:179], v[202:205], v[82:85]
	v_mfma_f32_16x16x32_bf16 v[70:73], v[168:171], v[210:213], v[70:73]
	v_mfma_f32_16x16x32_bf16 v[66:69], v[176:179], v[210:213], v[66:69]
	v_mfma_f32_16x16x32_bf16 v[118:121], v[172:175], v[190:193], v[118:121]
	v_mfma_f32_16x16x32_bf16 v[114:117], v[180:183], v[190:193], v[114:117]
	v_mfma_f32_16x16x32_bf16 v[102:105], v[172:175], v[198:201], v[102:105]
	v_mfma_f32_16x16x32_bf16 v[98:101], v[180:183], v[198:201], v[98:101]
	v_mfma_f32_16x16x32_bf16 v[86:89], v[172:175], v[206:209], v[86:89]
	v_mfma_f32_16x16x32_bf16 v[82:85], v[180:183], v[206:209], v[82:85]
	v_mfma_f32_16x16x32_bf16 v[70:73], v[172:175], v[214:217], v[70:73]
	v_mfma_f32_16x16x32_bf16 v[66:69], v[180:183], v[214:217], v[66:69]
	s_setprio 0
	s_barrier
	s_add_i32 s67, s61, s52
	v_lshl_add_u64 v[218:219], s[46:47], 0, v[132:133]
	s_mov_b32 m0, s67
	ds_read_b128 v[186:189], v154 offset:16384
	ds_read_b128 v[190:193], v154 offset:17408
	ds_read_b128 v[194:197], v154 offset:18432
	ds_read_b128 v[198:201], v154 offset:19456
	ds_read_b128 v[202:205], v154 offset:20480
	ds_read_b128 v[206:209], v154 offset:21504
	ds_read_b128 v[210:213], v154 offset:22528
	ds_read_b128 v[214:217], v154 offset:23552
	global_load_lds_dwordx4 v[218:219], off
	s_add_i32 m0, s67, 0x2000
	s_add_u32 s68, s46, 0x40000
	v_lshl_add_u64 v[220:221], s[46:47], 0, v[136:137]
	s_addc_u32 s69, s47, 0
	s_add_i32 s67, s62, s52
	global_load_lds_dwordx4 v[220:221], off
	v_lshl_add_u64 v[222:223], s[68:69], 0, v[132:133]
	s_mov_b32 m0, s67
	v_lshl_add_u64 v[224:225], s[48:49], 0, v[134:135]
	global_load_lds_dwordx4 v[222:223], off
	v_lshl_add_u64 v[222:223], s[68:69], 0, v[136:137]
	s_add_i32 m0, s67, 0x2000
	s_nop 0
	global_load_lds_dwordx4 v[222:223], off
	v_lshl_add_u64 v[222:223], s[48:49], 0, v[130:131]
	s_mov_b32 m0, s43
	s_nop 0
	global_load_lds_dwordx4 v[222:223], off
	s_mov_b32 m0, s53
	s_nop 0
	global_load_lds_dwordx4 v[224:225], off
	s_waitcnt vmcnt(8)
	s_waitcnt lgkmcnt(0)
	s_barrier
; #define PG8_STAGE(bufoff, gbase, voff) do { _Pragma("unroll") for (int _i = 0; _i < 2; ++_i) \
;         __builtin_amdgcn_global_load_lds((const unsigned*)((const char*)(gbase) + (voff)[_i]), (LAS unsigned*)(lds + (bufoff) + ldsw + _i * 8192), 16, 0, 0); } while (0)
; #define PG8_LDA(dst, b, h) do { _Pragma("unroll") for (int m = 0; m < 4; ++m) _Pragma("unroll") for (int k = 0; k < 2; ++k) dst[m][k] = *(const LAS bf16x8*)(lds + PG8_SA(b, h) + aoff + m * 2048 + k * 1024); } while (0)
; #define PG8_LDB(dst, b, h) do { _Pragma("unroll") for (int n = 0; n < 2; ++n) _Pragma("unroll") for (int k = 0; k < 2; ++k) dst[n][k] = *(const LAS bf16x8*)(lds + PG8_SB(b, h) + boff + n * 2048 + k * 1024); } while (0)
; #define PG8_MMA(ai, bj, At, Bt) do { __builtin_amdgcn_s_setprio(1); _Pragma("unroll") for (int m = 0; m < 4; ++m) _Pragma("unroll") for (int n = 0; n < 2; ++n) _Pragma("unroll") for (int k = 0; k < 2; ++k) \
;         acc[ai][bj][m][n] = __builtin_amdgcn_mfma_f32_16x16x32_bf16(Bt[n][k], At[m][k], acc[ai][bj][m][n], 0, 0, 0); __builtin_amdgcn_s_setprio(0); } while (0)
; #define PG8_WAIT_V(n) asm volatile("s_waitcnt vmcnt(" #n ")" ::: "memory")
; #define PG8_WAIT_L(n) asm volatile("s_waitcnt lgkmcnt(" #n ")" ::: "memory")
; #define PG8_BAR __builtin_amdgcn_s_barrier()
; #define PG8_SCHED __builtin_amdgcn_sched_barrier(0)
; template <class Epi, class Sched>
; DI void gemm_phase(LAS unsigned char* lds, const Gemm g, const Sched& S, const Epi& E) {
;     ...
;             PG8_WAIT_V(8); PG8_WAIT_L(0); PG8_BAR; PG8_MMA(1, 0, At, B0); PG8_MMA(1, 1, At, B1); PG8_BAR; PG8_SCHED;
;             PG8_LDB(B0, 1, 0); PG8_LDB(B1, 1, 1); PG8_SCHED; PG8_LDA(At, 1, 0); PG8_STAGE(PG8_SA(0, 1), a2 + hstepA, voffA);
;             PG8_WAIT_V(8); PG8_WAIT_L(0); PG8_BAR; PG8_MMA(0, 0, At, B0); PG8_MMA(0, 1, At, B1); PG8_BAR; PG8_SCHED;
	s_setprio 1
	v_mfma_f32_16x16x32_bf16 v[62:65], v[146:149], v[186:189], v[62:65]
	v_mfma_f32_16x16x32_bf16 v[58:61], v[160:163], v[186:189], v[58:61]
	v_mfma_f32_16x16x32_bf16 v[46:49], v[146:149], v[194:197], v[46:49]
	v_mfma_f32_16x16x32_bf16 v[42:45], v[160:163], v[194:197], v[42:45]
	v_mfma_f32_16x16x32_bf16 v[30:33], v[146:149], v[202:205], v[30:33]
	v_mfma_f32_16x16x32_bf16 v[26:29], v[160:163], v[202:205], v[26:29]
	v_mfma_f32_16x16x32_bf16 v[14:17], v[146:149], v[210:213], v[14:17]
	v_mfma_f32_16x16x32_bf16 v[10:13], v[160:163], v[210:213], v[10:13]
	v_mfma_f32_16x16x32_bf16 v[62:65], v[156:159], v[190:193], v[62:65]
	v_mfma_f32_16x16x32_bf16 v[58:61], v[164:167], v[190:193], v[58:61]
	v_mfma_f32_16x16x32_bf16 v[46:49], v[156:159], v[198:201], v[46:49]
	v_mfma_f32_16x16x32_bf16 v[42:45], v[164:167], v[198:201], v[42:45]
	v_mfma_f32_16x16x32_bf16 v[30:33], v[156:159], v[206:209], v[30:33]
	v_mfma_f32_16x16x32_bf16 v[26:29], v[164:167], v[206:209], v[26:29]
	v_mfma_f32_16x16x32_bf16 v[14:17], v[156:159], v[214:217], v[14:17]
	v_mfma_f32_16x16x32_bf16 v[10:13], v[164:167], v[214:217], v[10:13]
	s_setprio 0
	s_setprio 1
	v_mfma_f32_16x16x32_bf16 v[54:57], v[168:171], v[186:189], v[54:57]
	v_mfma_f32_16x16x32_bf16 v[50:53], v[176:179], v[186:189], v[50:53]
	v_mfma_f32_16x16x32_bf16 v[38:41], v[168:171], v[194:197], v[38:41]
	v_mfma_f32_16x16x32_bf16 v[34:37], v[176:179], v[194:197], v[34:37]
	v_mfma_f32_16x16x32_bf16 v[22:25], v[168:171], v[202:205], v[22:25]
	v_mfma_f32_16x16x32_bf16 v[18:21], v[176:179], v[202:205], v[18:21]
	v_mfma_f32_16x16x32_bf16 v[6:9], v[168:171], v[210:213], v[6:9]
	v_mfma_f32_16x16x32_bf16 v[2:5], v[176:179], v[210:213], v[2:5]
	v_mfma_f32_16x16x32_bf16 v[54:57], v[172:175], v[190:193], v[54:57]
	v_mfma_f32_16x16x32_bf16 v[50:53], v[180:183], v[190:193], v[50:53]
	v_mfma_f32_16x16x32_bf16 v[38:41], v[172:175], v[198:201], v[38:41]
	v_mfma_f32_16x16x32_bf16 v[34:37], v[180:183], v[198:201], v[34:37]
	v_mfma_f32_16x16x32_bf16 v[22:25], v[172:175], v[206:209], v[22:25]
	v_mfma_f32_16x16x32_bf16 v[18:21], v[180:183], v[206:209], v[18:21]
	v_mfma_f32_16x16x32_bf16 v[6:9], v[172:175], v[214:217], v[6:9]
	v_mfma_f32_16x16x32_bf16 v[2:5], v[180:183], v[214:217], v[2:5]
	s_setprio 0
	s_barrier
	s_add_i32 s67, 0, 0x18000
	s_add_i32 s68, 0, 0x1c000
	v_add_u32_e32 v164, s67, v150
	v_add_u32_e32 v180, s68, v150
	ds_read_b128 v[146:149], v164
	ds_read_b128 v[156:159], v164 offset:1024
	ds_read_b128 v[160:163], v164 offset:2048
	ds_read_b128 v[164:167], v164 offset:3072
	ds_read_b128 v[168:171], v180
	ds_read_b128 v[172:175], v180 offset:1024
	ds_read_b128 v[176:179], v180 offset:2048
	ds_read_b128 v[180:183], v180 offset:3072
	s_add_u32 s48, s48, 0x40000
	s_addc_u32 s49, s49, 0
	s_mov_b32 m0, s54
	v_lshl_add_u64 v[226:227], s[48:49], 0, v[130:131]
	ds_read_b128 v[186:189], v154 offset:32768
	ds_read_b128 v[190:193], v154 offset:33792
	ds_read_b128 v[194:197], v154 offset:34816
	ds_read_b128 v[198:201], v154 offset:35840
	ds_read_b128 v[202:205], v154 offset:36864
	ds_read_b128 v[206:209], v154 offset:37888
	ds_read_b128 v[210:213], v154 offset:38912
	ds_read_b128 v[214:217], v154 offset:39936
	global_load_lds_dwordx4 v[226:227], off
	v_lshl_add_u64 v[226:227], s[48:49], 0, v[134:135]
	s_mov_b32 m0, s55
	s_nop 0
	global_load_lds_dwordx4 v[226:227], off
	s_waitcnt vmcnt(8)
	s_waitcnt lgkmcnt(0)
	s_barrier
	s_setprio 1
	v_mfma_f32_16x16x32_bf16 v[126:129], v[146:149], v[186:189], v[126:129]
	v_mfma_f32_16x16x32_bf16 v[122:125], v[160:163], v[186:189], v[122:125]
	v_mfma_f32_16x16x32_bf16 v[110:113], v[146:149], v[194:197], v[110:113]
	v_mfma_f32_16x16x32_bf16 v[106:109], v[160:163], v[194:197], v[106:109]
	v_mfma_f32_16x16x32_bf16 v[94:97], v[146:149], v[202:205], v[94:97]
	v_mfma_f32_16x16x32_bf16 v[90:93], v[160:163], v[202:205], v[90:93]
	v_mfma_f32_16x16x32_bf16 v[78:81], v[146:149], v[210:213], v[78:81]
	v_mfma_f32_16x16x32_bf16 v[74:77], v[160:163], v[210:213], v[74:77]
	v_mfma_f32_16x16x32_bf16 v[126:129], v[156:159], v[190:193], v[126:129]
	v_mfma_f32_16x16x32_bf16 v[122:125], v[164:167], v[190:193], v[122:125]
	v_mfma_f32_16x16x32_bf16 v[110:113], v[156:159], v[198:201], v[110:113]
	v_mfma_f32_16x16x32_bf16 v[106:109], v[164:167], v[198:201], v[106:109]
	v_mfma_f32_16x16x32_bf16 v[94:97], v[156:159], v[206:209], v[94:97]
	v_mfma_f32_16x16x32_bf16 v[90:93], v[164:167], v[206:209], v[90:93]
	v_mfma_f32_16x16x32_bf16 v[78:81], v[156:159], v[214:217], v[78:81]
	v_mfma_f32_16x16x32_bf16 v[74:77], v[164:167], v[214:217], v[74:77]
	s_setprio 0
	s_setprio 1
	v_mfma_f32_16x16x32_bf16 v[118:121], v[168:171], v[186:189], v[118:121]
	v_mfma_f32_16x16x32_bf16 v[114:117], v[176:179], v[186:189], v[114:117]
	v_mfma_f32_16x16x32_bf16 v[102:105], v[168:171], v[194:197], v[102:105]
	v_mfma_f32_16x16x32_bf16 v[98:101], v[176:179], v[194:197], v[98:101]
	v_mfma_f32_16x16x32_bf16 v[86:89], v[168:171], v[202:205], v[86:89]
	v_mfma_f32_16x16x32_bf16 v[82:85], v[176:179], v[202:205], v[82:85]
	v_mfma_f32_16x16x32_bf16 v[70:73], v[168:171], v[210:213], v[70:73]
	v_mfma_f32_16x16x32_bf16 v[66:69], v[176:179], v[210:213], v[66:69]
	v_mfma_f32_16x16x32_bf16 v[118:121], v[172:175], v[190:193], v[118:121]
	v_mfma_f32_16x16x32_bf16 v[114:117], v[180:183], v[190:193], v[114:117]
	v_mfma_f32_16x16x32_bf16 v[102:105], v[172:175], v[198:201], v[102:105]
	v_mfma_f32_16x16x32_bf16 v[98:101], v[180:183], v[198:201], v[98:101]
	v_mfma_f32_16x16x32_bf16 v[86:89], v[172:175], v[206:209], v[86:89]
	v_mfma_f32_16x16x32_bf16 v[82:85], v[180:183], v[206:209], v[82:85]
	v_mfma_f32_16x16x32_bf16 v[70:73], v[172:175], v[214:217], v[70:73]
	v_mfma_f32_16x16x32_bf16 v[66:69], v[180:183], v[214:217], v[66:69]
	s_setprio 0
	s_barrier
; #define PG8_STAGE(bufoff, gbase, voff) do { _Pragma("unroll") for (int _i = 0; _i < 2; ++_i) \
;         __builtin_amdgcn_global_load_lds((const unsigned*)((const char*)(gbase) + (voff)[_i]), (LAS unsigned*)(lds + (bufoff) + ldsw + _i * 8192), 16, 0, 0); } while (0)
; #define PG8_LDA(dst, b, h) do { _Pragma("unroll") for (int m = 0; m < 4; ++m) _Pragma("unroll") for (int k = 0; k < 2; ++k) dst[m][k] = *(const LAS bf16x8*)(lds + PG8_SA(b, h) + aoff + m * 2048 + k * 1024); } while (0)
; #define PG8_MMA(ai, bj, At, Bt) do { __builtin_amdgcn_s_setprio(1); _Pragma("unroll") for (int m = 0; m < 4; ++m) _Pragma("unroll") for (int n = 0; n < 2; ++n) _Pragma("unroll") for (int k = 0; k < 2; ++k) \
;         acc[ai][bj][m][n] = __builtin_amdgcn_mfma_f32_16x16x32_bf16(Bt[n][k], At[m][k], acc[ai][bj][m][n], 0, 0, 0); __builtin_amdgcn_s_setprio(0); } while (0)
; #define PG8_WAIT_V(n) asm volatile("s_waitcnt vmcnt(" #n ")" ::: "memory")
; #define PG8_WAIT_L(n) asm volatile("s_waitcnt lgkmcnt(" #n ")" ::: "memory")
; #define PG8_BAR __builtin_amdgcn_s_barrier()
; #define PG8_SCHED __builtin_amdgcn_sched_barrier(0)
; template <class Epi, class Sched>
; DI void gemm_phase(LAS unsigned char* lds, const Gemm g, const Sched& S, const Epi& E) {
;     ...
;             PG8_LDA(At, 1, 1); PG8_STAGE(PG8_SB(1, 0), b3, voffB); PG8_STAGE(PG8_SB(1, 1), b3 + hstepB, voffB); PG8_STAGE(PG8_SA(1, 0), a3, voffA);
;             PG8_WAIT_V(8); PG8_WAIT_L(0); PG8_BAR; PG8_MMA(1, 0, At, B0); PG8_MMA(1, 1, At, B1); PG8_BAR; PG8_SCHED;
;         }
;         if (wr == 0) PG8_BAR;
	s_add_i32 s48, s67, s52
	v_lshl_add_u64 v[218:219], v[218:219], 0, s[16:17]
	s_mov_b32 m0, s48
	ds_read_b128 v[186:189], v154 offset:49152
	ds_read_b128 v[190:193], v154 offset:50176
	ds_read_b128 v[194:197], v154 offset:51200
	ds_read_b128 v[198:201], v154 offset:52224
	ds_read_b128 v[202:205], v154 offset:53248
	ds_read_b128 v[206:209], v154 offset:54272
	ds_read_b128 v[210:213], v154 offset:55296
	ds_read_b128 v[214:217], v154 offset:56320
	global_load_lds_dwordx4 v[218:219], off
	s_add_i32 m0, s48, 0x2000
	s_add_u32 s46, s46, 0x40080
	v_lshl_add_u64 v[218:219], v[220:221], 0, s[16:17]
	s_addc_u32 s47, s47, 0
	s_add_i32 s48, s68, s52
	global_load_lds_dwordx4 v[218:219], off
	v_lshl_add_u64 v[218:219], s[46:47], 0, v[132:133]
	s_mov_b32 m0, s48
	s_nop 0
	global_load_lds_dwordx4 v[218:219], off
	v_lshl_add_u64 v[218:219], s[46:47], 0, v[136:137]
	s_add_i32 m0, s48, 0x2000
	s_nop 0
	global_load_lds_dwordx4 v[218:219], off
	v_lshl_add_u64 v[218:219], v[222:223], 0, s[16:17]
	s_mov_b32 m0, s57
	s_nop 0
	global_load_lds_dwordx4 v[218:219], off
	v_lshl_add_u64 v[218:219], v[224:225], 0, s[16:17]
	s_mov_b32 m0, s58
	s_nop 0
	global_load_lds_dwordx4 v[218:219], off
	s_waitcnt vmcnt(8)
	s_waitcnt lgkmcnt(0)
	s_barrier
	s_setprio 1
	v_mfma_f32_16x16x32_bf16 v[62:65], v[146:149], v[186:189], v[62:65]
	v_mfma_f32_16x16x32_bf16 v[58:61], v[160:163], v[186:189], v[58:61]
	v_mfma_f32_16x16x32_bf16 v[46:49], v[146:149], v[194:197], v[46:49]
	v_mfma_f32_16x16x32_bf16 v[42:45], v[160:163], v[194:197], v[42:45]
	v_mfma_f32_16x16x32_bf16 v[30:33], v[146:149], v[202:205], v[30:33]
	v_mfma_f32_16x16x32_bf16 v[26:29], v[160:163], v[202:205], v[26:29]
	v_mfma_f32_16x16x32_bf16 v[14:17], v[146:149], v[210:213], v[14:17]
	v_mfma_f32_16x16x32_bf16 v[10:13], v[160:163], v[210:213], v[10:13]
	v_mfma_f32_16x16x32_bf16 v[62:65], v[156:159], v[190:193], v[62:65]
	v_mfma_f32_16x16x32_bf16 v[58:61], v[164:167], v[190:193], v[58:61]
	v_mfma_f32_16x16x32_bf16 v[46:49], v[156:159], v[198:201], v[46:49]
	v_mfma_f32_16x16x32_bf16 v[42:45], v[164:167], v[198:201], v[42:45]
	v_mfma_f32_16x16x32_bf16 v[30:33], v[156:159], v[206:209], v[30:33]
	v_mfma_f32_16x16x32_bf16 v[26:29], v[164:167], v[206:209], v[26:29]
	v_mfma_f32_16x16x32_bf16 v[14:17], v[156:159], v[214:217], v[14:17]
	v_mfma_f32_16x16x32_bf16 v[10:13], v[164:167], v[214:217], v[10:13]
	s_setprio 0
	s_setprio 1
	v_mfma_f32_16x16x32_bf16 v[54:57], v[168:171], v[186:189], v[54:57]
	v_mfma_f32_16x16x32_bf16 v[50:53], v[176:179], v[186:189], v[50:53]
	v_mfma_f32_16x16x32_bf16 v[38:41], v[168:171], v[194:197], v[38:41]
	v_mfma_f32_16x16x32_bf16 v[34:37], v[176:179], v[194:197], v[34:37]
	v_mfma_f32_16x16x32_bf16 v[22:25], v[168:171], v[202:205], v[22:25]
	v_mfma_f32_16x16x32_bf16 v[18:21], v[176:179], v[202:205], v[18:21]
	v_mfma_f32_16x16x32_bf16 v[6:9], v[168:171], v[210:213], v[6:9]
	v_mfma_f32_16x16x32_bf16 v[2:5], v[176:179], v[210:213], v[2:5]
	v_mfma_f32_16x16x32_bf16 v[54:57], v[172:175], v[190:193], v[54:57]
	v_mfma_f32_16x16x32_bf16 v[50:53], v[180:183], v[190:193], v[50:53]
	v_mfma_f32_16x16x32_bf16 v[38:41], v[172:175], v[198:201], v[38:41]
	v_mfma_f32_16x16x32_bf16 v[34:37], v[180:183], v[198:201], v[34:37]
	v_mfma_f32_16x16x32_bf16 v[22:25], v[172:175], v[206:209], v[22:25]
	v_mfma_f32_16x16x32_bf16 v[18:21], v[180:183], v[206:209], v[18:21]
	v_mfma_f32_16x16x32_bf16 v[6:9], v[172:175], v[214:217], v[6:9]
	v_mfma_f32_16x16x32_bf16 v[2:5], v[180:183], v[214:217], v[2:5]
	s_setprio 0
	s_barrier
	s_add_i32 s66, s66, 2
	s_add_u32 s44, s44, 0x100
	s_addc_u32 s45, s45, 0
	s_add_u32 s64, s64, 0x100
	s_addc_u32 s65, s65, 0
	s_cmp_gt_u32 s66, 13
	s_cbranch_scc0 .LBB0_1133
	s_and_b64 vcc, exec, s[18:19]
	s_cbranch_vccz .LBB0_1136
	s_barrier

; #define PG8_STAGE(bufoff, gbase, voff) do { _Pragma("unroll") for (int _i = 0; _i < 2; ++_i) \
;         __builtin_amdgcn_global_load_lds((const unsigned*)((const char*)(gbase) + (voff)[_i]), (LAS unsigned*)(lds + (bufoff) + ldsw + _i * 8192), 16, 0, 0); } while (0)
; #define PG8_LDA(dst, b, h) do { _Pragma("unroll") for (int m = 0; m < 4; ++m) _Pragma("unroll") for (int k = 0; k < 2; ++k) dst[m][k] = *(const LAS bf16x8*)(lds + PG8_SA(b, h) + aoff + m * 2048 + k * 1024); } while (0)
; #define PG8_LDB(dst, b, h) do { _Pragma("unroll") for (int n = 0; n < 2; ++n) _Pragma("unroll") for (int k = 0; k < 2; ++k) dst[n][k] = *(const LAS bf16x8*)(lds + PG8_SB(b, h) + boff + n * 2048 + k * 1024); } while (0)
; #define PG8_MMA(ai, bj, At, Bt) do { __builtin_amdgcn_s_setprio(1); _Pragma("unroll") for (int m = 0; m < 4; ++m) _Pragma("unroll") for (int n = 0; n < 2; ++n) _Pragma("unroll") for (int k = 0; k < 2; ++k) \
;         acc[ai][bj][m][n] = __builtin_amdgcn_mfma_f32_16x16x32_bf16(Bt[n][k], At[m][k], acc[ai][bj][m][n], 0, 0, 0); __builtin_amdgcn_s_setprio(0); } while (0)
; #define PG8_WAIT_V(n) asm volatile("s_waitcnt vmcnt(" #n ")" ::: "memory")
; #define PG8_WAIT_L(n) asm volatile("s_waitcnt lgkmcnt(" #n ")" ::: "memory")
; #define PG8_BAR __builtin_amdgcn_s_barrier()
; #define PG8_SCHED __builtin_amdgcn_sched_barrier(0)
; template <class Epi, class Sched>
; DI void gemm_phase(LAS unsigned char* lds, const Gemm g, const Sched& S, const Epi& E) {
;     ...
;             const bool last = (t == nt - 2);
;             const char* a1 = cA + (size_t)(t + 1) * kstep;
;             const char* a2 = last ? nA : cA + (size_t)(t + 2) * kstep; const char* b2 = last ? nB : cB + (size_t)(t + 2) * kstep;
;             const char* a3 = a2 + kstep; const char* b3 = b2 + kstep;
;             PG8_LDB(B0, 0, 0); PG8_LDB(B1, 0, 1); PG8_SCHED; PG8_LDA(At, 0, 0); PG8_STAGE(PG8_SA(1, 1), a1 + hstepA, voffA);
;             PG8_WAIT_V(8); PG8_WAIT_L(0); PG8_BAR; PG8_MMA(0, 0, At, B0); PG8_MMA(0, 1, At, B1); PG8_BAR; PG8_SCHED;
;             PG8_LDA(At, 0, 1); PG8_STAGE(PG8_SB(0, 0), b2, voffB); PG8_STAGE(PG8_SB(0, 1), b2 + hstepB, voffB); PG8_STAGE(PG8_SA(0, 0), a2, voffA);
;             PG8_WAIT_V(8); PG8_WAIT_L(0); PG8_BAR; PG8_MMA(1, 0, At, B0); PG8_MMA(1, 1, At, B1); PG8_BAR; PG8_SCHED;
.LBB0_1234:
	ds_read_b128 v[166:169], v160
	ds_read_b128 v[170:173], v160 offset:1024
	ds_read_b128 v[174:177], v160 offset:2048
	ds_read_b128 v[178:181], v160 offset:3072
	ds_read_b128 v[186:189], v161
	ds_read_b128 v[190:193], v161 offset:1024
	ds_read_b128 v[194:197], v161 offset:2048
	ds_read_b128 v[198:201], v161 offset:3072
	s_add_u32 s42, s40, 0xfffc0080
	s_addc_u32 s43, s41, -1
	s_cmp_eq_u32 s65, 12
	s_cselect_b32 s45, s35, s43
	s_cselect_b32 s44, s61, s42
	s_cselect_b32 s43, s21, s64
	s_cselect_b32 s42, s62, s63
	v_lshl_add_u64 v[182:183], s[40:41], 0, v[138:139]
	s_add_i32 m0, s49, 0xc000
	ds_read_b128 v[202:205], v158
	ds_read_b128 v[206:209], v158 offset:1024
	ds_read_b128 v[210:213], v158 offset:2048
	ds_read_b128 v[214:217], v158 offset:3072
	ds_read_b128 v[218:221], v158 offset:4096
	ds_read_b128 v[222:225], v158 offset:5120
	ds_read_b128 v[226:229], v158 offset:6144
	ds_read_b128 v[230:233], v158 offset:7168
	global_load_lds_dwordx4 v[182:183], off
	v_lshl_add_u64 v[182:183], s[40:41], 0, v[140:141]
	s_add_i32 m0, s49, 0xe000
	s_nop 0
	global_load_lds_dwordx4 v[182:183], off
	s_waitcnt vmcnt(8)
	s_waitcnt lgkmcnt(0)
	s_barrier
	s_setprio 1
	v_mfma_f32_16x16x32_bf16 v[126:129], v[166:169], v[202:205], v[126:129]
	v_mfma_f32_16x16x32_bf16 v[118:121], v[174:177], v[202:205], v[118:121]
	v_mfma_f32_16x16x32_bf16 v[110:113], v[166:169], v[210:213], v[110:113]
	v_mfma_f32_16x16x32_bf16 v[102:105], v[174:177], v[210:213], v[102:105]
	v_mfma_f32_16x16x32_bf16 v[94:97], v[166:169], v[218:221], v[94:97]
	v_mfma_f32_16x16x32_bf16 v[86:89], v[174:177], v[218:221], v[86:89]
	v_mfma_f32_16x16x32_bf16 v[78:81], v[166:169], v[226:229], v[78:81]
	v_mfma_f32_16x16x32_bf16 v[70:73], v[174:177], v[226:229], v[70:73]
	v_mfma_f32_16x16x32_bf16 v[126:129], v[170:173], v[206:209], v[126:129]
	v_mfma_f32_16x16x32_bf16 v[118:121], v[178:181], v[206:209], v[118:121]
	v_mfma_f32_16x16x32_bf16 v[110:113], v[170:173], v[214:217], v[110:113]
	v_mfma_f32_16x16x32_bf16 v[102:105], v[178:181], v[214:217], v[102:105]
	v_mfma_f32_16x16x32_bf16 v[94:97], v[170:173], v[222:225], v[94:97]
	v_mfma_f32_16x16x32_bf16 v[86:89], v[178:181], v[222:225], v[86:89]
	v_mfma_f32_16x16x32_bf16 v[78:81], v[170:173], v[230:233], v[78:81]
	v_mfma_f32_16x16x32_bf16 v[70:73], v[178:181], v[230:233], v[70:73]
	s_setprio 0
	s_setprio 1
	v_mfma_f32_16x16x32_bf16 v[122:125], v[186:189], v[202:205], v[122:125]
	v_mfma_f32_16x16x32_bf16 v[114:117], v[194:197], v[202:205], v[114:117]
	v_mfma_f32_16x16x32_bf16 v[106:109], v[186:189], v[210:213], v[106:109]
	v_mfma_f32_16x16x32_bf16 v[98:101], v[194:197], v[210:213], v[98:101]
	v_mfma_f32_16x16x32_bf16 v[90:93], v[186:189], v[218:221], v[90:93]
	v_mfma_f32_16x16x32_bf16 v[82:85], v[194:197], v[218:221], v[82:85]
	v_mfma_f32_16x16x32_bf16 v[74:77], v[186:189], v[226:229], v[74:77]
	v_mfma_f32_16x16x32_bf16 v[66:69], v[194:197], v[226:229], v[66:69]
	v_mfma_f32_16x16x32_bf16 v[122:125], v[190:193], v[206:209], v[122:125]
	v_mfma_f32_16x16x32_bf16 v[114:117], v[198:201], v[206:209], v[114:117]
	v_mfma_f32_16x16x32_bf16 v[106:109], v[190:193], v[214:217], v[106:109]
	v_mfma_f32_16x16x32_bf16 v[98:101], v[198:201], v[214:217], v[98:101]
	v_mfma_f32_16x16x32_bf16 v[90:93], v[190:193], v[222:225], v[90:93]
	v_mfma_f32_16x16x32_bf16 v[82:85], v[198:201], v[222:225], v[82:85]
	v_mfma_f32_16x16x32_bf16 v[74:77], v[190:193], v[230:233], v[74:77]
	v_mfma_f32_16x16x32_bf16 v[66:69], v[198:201], v[230:233], v[66:69]
	s_setprio 0
	s_barrier
	s_add_i32 s66, s57, s46
	v_lshl_add_u64 v[182:183], s[42:43], 0, v[134:135]
	s_mov_b32 m0, s66
	ds_read_b128 v[202:205], v158 offset:16384
	ds_read_b128 v[206:209], v158 offset:17408
	ds_read_b128 v[210:213], v158 offset:18432
	ds_read_b128 v[214:217], v158 offset:19456
	ds_read_b128 v[218:221], v158 offset:20480
	ds_read_b128 v[222:225], v158 offset:21504
	ds_read_b128 v[226:229], v158 offset:22528
	ds_read_b128 v[230:233], v158 offset:23552
	global_load_lds_dwordx4 v[182:183], off
	s_add_i32 m0, s66, 0x2000
	s_add_u32 s66, s42, 0x40000
	v_lshl_add_u64 v[234:235], s[42:43], 0, v[130:131]
	s_addc_u32 s67, s43, 0
	s_add_i32 s68, s58, s46
	global_load_lds_dwordx4 v[234:235], off
	v_lshl_add_u64 v[236:237], s[66:67], 0, v[134:135]
	s_mov_b32 m0, s68
	v_lshl_add_u64 v[238:239], s[44:45], 0, v[132:133]
	global_load_lds_dwordx4 v[236:237], off
	v_lshl_add_u64 v[236:237], s[66:67], 0, v[130:131]
	s_add_i32 m0, s68, 0x2000
	s_nop 0
	global_load_lds_dwordx4 v[236:237], off
	v_lshl_add_u64 v[236:237], s[44:45], 0, v[136:137]
	s_mov_b32 m0, s49
	s_nop 0
	global_load_lds_dwordx4 v[236:237], off
	s_mov_b32 m0, s50
	s_nop 0
	global_load_lds_dwordx4 v[238:239], off
	s_waitcnt vmcnt(8)
	s_waitcnt lgkmcnt(0)
	s_barrier
; #define PG8_STAGE(bufoff, gbase, voff) do { _Pragma("unroll") for (int _i = 0; _i < 2; ++_i) \
;         __builtin_amdgcn_global_load_lds((const unsigned*)((const char*)(gbase) + (voff)[_i]), (LAS unsigned*)(lds + (bufoff) + ldsw + _i * 8192), 16, 0, 0); } while (0)
; #define PG8_LDA(dst, b, h) do { _Pragma("unroll") for (int m = 0; m < 4; ++m) _Pragma("unroll") for (int k = 0; k < 2; ++k) dst[m][k] = *(const LAS bf16x8*)(lds + PG8_SA(b, h) + aoff + m * 2048 + k * 1024); } while (0)
; #define PG8_LDB(dst, b, h) do { _Pragma("unroll") for (int n = 0; n < 2; ++n) _Pragma("unroll") for (int k = 0; k < 2; ++k) dst[n][k] = *(const LAS bf16x8*)(lds + PG8_SB(b, h) + boff + n * 2048 + k * 1024); } while (0)
; #define PG8_MMA(ai, bj, At, Bt) do { __builtin_amdgcn_s_setprio(1); _Pragma("unroll") for (int m = 0; m < 4; ++m) _Pragma("unroll") for (int n = 0; n < 2; ++n) _Pragma("unroll") for (int k = 0; k < 2; ++k) \
;         acc[ai][bj][m][n] = __builtin_amdgcn_mfma_f32_16x16x32_bf16(Bt[n][k], At[m][k], acc[ai][bj][m][n], 0, 0, 0); __builtin_amdgcn_s_setprio(0); } while (0)
; #define PG8_WAIT_V(n) asm volatile("s_waitcnt vmcnt(" #n ")" ::: "memory")
; #define PG8_WAIT_L(n) asm volatile("s_waitcnt lgkmcnt(" #n ")" ::: "memory")
; #define PG8_BAR __builtin_amdgcn_s_barrier()
; #define PG8_SCHED __builtin_amdgcn_sched_barrier(0)
; template <class Epi, class Sched>
; DI void gemm_phase(LAS unsigned char* lds, const Gemm g, const Sched& S, const Epi& E) {
;     ...
;             PG8_WAIT_V(8); PG8_WAIT_L(0); PG8_BAR; PG8_MMA(1, 0, At, B0); PG8_MMA(1, 1, At, B1); PG8_BAR; PG8_SCHED;
;             PG8_LDB(B0, 1, 0); PG8_LDB(B1, 1, 1); PG8_SCHED; PG8_LDA(At, 1, 0); PG8_STAGE(PG8_SA(0, 1), a2 + hstepA, voffA);
;             PG8_WAIT_V(8); PG8_WAIT_L(0); PG8_BAR; PG8_MMA(0, 0, At, B0); PG8_MMA(0, 1, At, B1); PG8_BAR; PG8_SCHED;
	s_setprio 1
	v_mfma_f32_16x16x32_bf16 v[62:65], v[166:169], v[202:205], v[62:65]
	v_mfma_f32_16x16x32_bf16 v[54:57], v[174:177], v[202:205], v[54:57]
	v_mfma_f32_16x16x32_bf16 v[46:49], v[166:169], v[210:213], v[46:49]
	v_mfma_f32_16x16x32_bf16 v[38:41], v[174:177], v[210:213], v[38:41]
	v_mfma_f32_16x16x32_bf16 v[30:33], v[166:169], v[218:221], v[30:33]
	v_mfma_f32_16x16x32_bf16 v[22:25], v[174:177], v[218:221], v[22:25]
	v_mfma_f32_16x16x32_bf16 v[14:17], v[166:169], v[226:229], v[14:17]
	v_mfma_f32_16x16x32_bf16 v[6:9], v[174:177], v[226:229], v[6:9]
	v_mfma_f32_16x16x32_bf16 v[62:65], v[170:173], v[206:209], v[62:65]
	v_mfma_f32_16x16x32_bf16 v[54:57], v[178:181], v[206:209], v[54:57]
	v_mfma_f32_16x16x32_bf16 v[46:49], v[170:173], v[214:217], v[46:49]
	v_mfma_f32_16x16x32_bf16 v[38:41], v[178:181], v[214:217], v[38:41]
	v_mfma_f32_16x16x32_bf16 v[30:33], v[170:173], v[222:225], v[30:33]
	v_mfma_f32_16x16x32_bf16 v[22:25], v[178:181], v[222:225], v[22:25]
	v_mfma_f32_16x16x32_bf16 v[14:17], v[170:173], v[230:233], v[14:17]
	v_mfma_f32_16x16x32_bf16 v[6:9], v[178:181], v[230:233], v[6:9]
	s_setprio 0
	s_setprio 1
	v_mfma_f32_16x16x32_bf16 v[58:61], v[186:189], v[202:205], v[58:61]
	v_mfma_f32_16x16x32_bf16 v[50:53], v[194:197], v[202:205], v[50:53]
	v_mfma_f32_16x16x32_bf16 v[42:45], v[186:189], v[210:213], v[42:45]
	v_mfma_f32_16x16x32_bf16 v[34:37], v[194:197], v[210:213], v[34:37]
	v_mfma_f32_16x16x32_bf16 v[26:29], v[186:189], v[218:221], v[26:29]
	v_mfma_f32_16x16x32_bf16 v[18:21], v[194:197], v[218:221], v[18:21]
	v_mfma_f32_16x16x32_bf16 v[10:13], v[186:189], v[226:229], v[10:13]
	v_mfma_f32_16x16x32_bf16 v[2:5], v[194:197], v[226:229], v[2:5]
	v_mfma_f32_16x16x32_bf16 v[58:61], v[190:193], v[206:209], v[58:61]
	v_mfma_f32_16x16x32_bf16 v[50:53], v[198:201], v[206:209], v[50:53]
	v_mfma_f32_16x16x32_bf16 v[42:45], v[190:193], v[214:217], v[42:45]
	v_mfma_f32_16x16x32_bf16 v[34:37], v[198:201], v[214:217], v[34:37]
	v_mfma_f32_16x16x32_bf16 v[26:29], v[190:193], v[222:225], v[26:29]
	v_mfma_f32_16x16x32_bf16 v[18:21], v[198:201], v[222:225], v[18:21]
	v_mfma_f32_16x16x32_bf16 v[10:13], v[190:193], v[230:233], v[10:13]
	v_mfma_f32_16x16x32_bf16 v[2:5], v[198:201], v[230:233], v[2:5]
	s_setprio 0
	s_barrier
	s_add_i32 s66, 0, 0x18000
	v_add_u32_e32 v165, s66, v156
	s_add_i32 s67, 0, 0x1c000
	ds_read_b128 v[166:169], v165
	ds_read_b128 v[170:173], v165 offset:1024
	ds_read_b128 v[174:177], v165 offset:2048
	ds_read_b128 v[178:181], v165 offset:3072
	v_add_u32_e32 v165, s67, v156
	ds_read_b128 v[186:189], v165
	ds_read_b128 v[190:193], v165 offset:1024
	ds_read_b128 v[194:197], v165 offset:2048
	ds_read_b128 v[198:201], v165 offset:3072
	s_add_u32 s44, s44, 0x40000
	s_addc_u32 s45, s45, 0
	s_mov_b32 m0, s51
	v_lshl_add_u64 v[240:241], s[44:45], 0, v[136:137]
	ds_read_b128 v[202:205], v158 offset:32768
	ds_read_b128 v[206:209], v158 offset:33792
	ds_read_b128 v[210:213], v158 offset:34816
	ds_read_b128 v[214:217], v158 offset:35840
	ds_read_b128 v[218:221], v158 offset:36864
	ds_read_b128 v[222:225], v158 offset:37888
	ds_read_b128 v[226:229], v158 offset:38912
	ds_read_b128 v[230:233], v158 offset:39936
	global_load_lds_dwordx4 v[240:241], off
	v_lshl_add_u64 v[240:241], s[44:45], 0, v[132:133]
	s_mov_b32 m0, s52
	s_nop 0
	global_load_lds_dwordx4 v[240:241], off
	s_waitcnt vmcnt(8)
	s_waitcnt lgkmcnt(0)
	s_barrier
	s_setprio 1
	v_mfma_f32_16x16x32_bf16 v[126:129], v[166:169], v[202:205], v[126:129]
	v_mfma_f32_16x16x32_bf16 v[118:121], v[174:177], v[202:205], v[118:121]
	v_mfma_f32_16x16x32_bf16 v[110:113], v[166:169], v[210:213], v[110:113]
	v_mfma_f32_16x16x32_bf16 v[102:105], v[174:177], v[210:213], v[102:105]
	v_mfma_f32_16x16x32_bf16 v[94:97], v[166:169], v[218:221], v[94:97]
	v_mfma_f32_16x16x32_bf16 v[86:89], v[174:177], v[218:221], v[86:89]
	v_mfma_f32_16x16x32_bf16 v[78:81], v[166:169], v[226:229], v[78:81]
	v_mfma_f32_16x16x32_bf16 v[70:73], v[174:177], v[226:229], v[70:73]
	v_mfma_f32_16x16x32_bf16 v[126:129], v[170:173], v[206:209], v[126:129]
	v_mfma_f32_16x16x32_bf16 v[118:121], v[178:181], v[206:209], v[118:121]
	v_mfma_f32_16x16x32_bf16 v[110:113], v[170:173], v[214:217], v[110:113]
	v_mfma_f32_16x16x32_bf16 v[102:105], v[178:181], v[214:217], v[102:105]
	v_mfma_f32_16x16x32_bf16 v[94:97], v[170:173], v[222:225], v[94:97]
	v_mfma_f32_16x16x32_bf16 v[86:89], v[178:181], v[222:225], v[86:89]
	v_mfma_f32_16x16x32_bf16 v[78:81], v[170:173], v[230:233], v[78:81]
	v_mfma_f32_16x16x32_bf16 v[70:73], v[178:181], v[230:233], v[70:73]
	s_setprio 0
	s_setprio 1
	v_mfma_f32_16x16x32_bf16 v[122:125], v[186:189], v[202:205], v[122:125]
	v_mfma_f32_16x16x32_bf16 v[114:117], v[194:197], v[202:205], v[114:117]
	v_mfma_f32_16x16x32_bf16 v[106:109], v[186:189], v[210:213], v[106:109]
	v_mfma_f32_16x16x32_bf16 v[98:101], v[194:197], v[210:213], v[98:101]
	v_mfma_f32_16x16x32_bf16 v[90:93], v[186:189], v[218:221], v[90:93]
	v_mfma_f32_16x16x32_bf16 v[82:85], v[194:197], v[218:221], v[82:85]
	v_mfma_f32_16x16x32_bf16 v[74:77], v[186:189], v[226:229], v[74:77]
	v_mfma_f32_16x16x32_bf16 v[66:69], v[194:197], v[226:229], v[66:69]
	v_mfma_f32_16x16x32_bf16 v[122:125], v[190:193], v[206:209], v[122:125]
	v_mfma_f32_16x16x32_bf16 v[114:117], v[198:201], v[206:209], v[114:117]
	v_mfma_f32_16x16x32_bf16 v[106:109], v[190:193], v[214:217], v[106:109]
	v_mfma_f32_16x16x32_bf16 v[98:101], v[198:201], v[214:217], v[98:101]
	v_mfma_f32_16x16x32_bf16 v[90:93], v[190:193], v[222:225], v[90:93]
	v_mfma_f32_16x16x32_bf16 v[82:85], v[198:201], v[222:225], v[82:85]
	v_mfma_f32_16x16x32_bf16 v[74:77], v[190:193], v[230:233], v[74:77]
	v_mfma_f32_16x16x32_bf16 v[66:69], v[198:201], v[230:233], v[66:69]
	s_setprio 0
	s_barrier
; #define PG8_STAGE(bufoff, gbase, voff) do { _Pragma("unroll") for (int _i = 0; _i < 2; ++_i) \
;         __builtin_amdgcn_global_load_lds((const unsigned*)((const char*)(gbase) + (voff)[_i]), (LAS unsigned*)(lds + (bufoff) + ldsw + _i * 8192), 16, 0, 0); } while (0)
; #define PG8_LDA(dst, b, h) do { _Pragma("unroll") for (int m = 0; m < 4; ++m) _Pragma("unroll") for (int k = 0; k < 2; ++k) dst[m][k] = *(const LAS bf16x8*)(lds + PG8_SA(b, h) + aoff + m * 2048 + k * 1024); } while (0)
; #define PG8_MMA(ai, bj, At, Bt) do { __builtin_amdgcn_s_setprio(1); _Pragma("unroll") for (int m = 0; m < 4; ++m) _Pragma("unroll") for (int n = 0; n < 2; ++n) _Pragma("unroll") for (int k = 0; k < 2; ++k) \
;         acc[ai][bj][m][n] = __builtin_amdgcn_mfma_f32_16x16x32_bf16(Bt[n][k], At[m][k], acc[ai][bj][m][n], 0, 0, 0); __builtin_amdgcn_s_setprio(0); } while (0)
; #define PG8_WAIT_V(n) asm volatile("s_waitcnt vmcnt(" #n ")" ::: "memory")
; #define PG8_WAIT_L(n) asm volatile("s_waitcnt lgkmcnt(" #n ")" ::: "memory")
; #define PG8_BAR __builtin_amdgcn_s_barrier()
; #define PG8_SCHED __builtin_amdgcn_sched_barrier(0)
; template <class Epi, class Sched>
; DI void gemm_phase(LAS unsigned char* lds, const Gemm g, const Sched& S, const Epi& E) {
;     ...
;             PG8_LDA(At, 1, 1); PG8_STAGE(PG8_SB(1, 0), b3, voffB); PG8_STAGE(PG8_SB(1, 1), b3 + hstepB, voffB); PG8_STAGE(PG8_SA(1, 0), a3, voffA);
;             PG8_WAIT_V(8); PG8_WAIT_L(0); PG8_BAR; PG8_MMA(1, 0, At, B0); PG8_MMA(1, 1, At, B1); PG8_BAR; PG8_SCHED;
;         }
;         if (wr == 0) PG8_BAR;
	s_add_i32 s44, s66, s46
	v_lshl_add_u64 v[182:183], v[182:183], 0, s[16:17]
	s_mov_b32 m0, s44
	ds_read_b128 v[202:205], v158 offset:49152
	ds_read_b128 v[206:209], v158 offset:50176
	ds_read_b128 v[210:213], v158 offset:51200
	ds_read_b128 v[214:217], v158 offset:52224
	ds_read_b128 v[218:221], v158 offset:53248
	ds_read_b128 v[222:225], v158 offset:54272
	ds_read_b128 v[226:229], v158 offset:55296
	ds_read_b128 v[230:233], v158 offset:56320
	global_load_lds_dwordx4 v[182:183], off
	s_add_i32 m0, s44, 0x2000
	s_add_u32 s42, s42, 0x40080
	v_lshl_add_u64 v[182:183], v[234:235], 0, s[16:17]
	s_addc_u32 s43, s43, 0
	s_add_i32 s44, s67, s46
	global_load_lds_dwordx4 v[182:183], off
	v_lshl_add_u64 v[182:183], s[42:43], 0, v[134:135]
	s_mov_b32 m0, s44
	s_nop 0
	global_load_lds_dwordx4 v[182:183], off
	v_lshl_add_u64 v[182:183], s[42:43], 0, v[130:131]
	s_add_i32 m0, s44, 0x2000
	s_nop 0
	global_load_lds_dwordx4 v[182:183], off
	v_lshl_add_u64 v[182:183], v[236:237], 0, s[16:17]
	s_mov_b32 m0, s54
	s_nop 0
	global_load_lds_dwordx4 v[182:183], off
	v_lshl_add_u64 v[182:183], v[238:239], 0, s[16:17]
	s_mov_b32 m0, s55
	s_nop 0
	global_load_lds_dwordx4 v[182:183], off
	s_waitcnt vmcnt(8)
	s_waitcnt lgkmcnt(0)
	s_barrier
	s_setprio 1
	v_mfma_f32_16x16x32_bf16 v[62:65], v[166:169], v[202:205], v[62:65]
	v_mfma_f32_16x16x32_bf16 v[54:57], v[174:177], v[202:205], v[54:57]
	v_mfma_f32_16x16x32_bf16 v[46:49], v[166:169], v[210:213], v[46:49]
	v_mfma_f32_16x16x32_bf16 v[38:41], v[174:177], v[210:213], v[38:41]
	v_mfma_f32_16x16x32_bf16 v[30:33], v[166:169], v[218:221], v[30:33]
	v_mfma_f32_16x16x32_bf16 v[22:25], v[174:177], v[218:221], v[22:25]
	v_mfma_f32_16x16x32_bf16 v[14:17], v[166:169], v[226:229], v[14:17]
	v_mfma_f32_16x16x32_bf16 v[6:9], v[174:177], v[226:229], v[6:9]
	v_mfma_f32_16x16x32_bf16 v[62:65], v[170:173], v[206:209], v[62:65]
	v_mfma_f32_16x16x32_bf16 v[54:57], v[178:181], v[206:209], v[54:57]
	v_mfma_f32_16x16x32_bf16 v[46:49], v[170:173], v[214:217], v[46:49]
	v_mfma_f32_16x16x32_bf16 v[38:41], v[178:181], v[214:217], v[38:41]
	v_mfma_f32_16x16x32_bf16 v[30:33], v[170:173], v[222:225], v[30:33]
	v_mfma_f32_16x16x32_bf16 v[22:25], v[178:181], v[222:225], v[22:25]
	v_mfma_f32_16x16x32_bf16 v[14:17], v[170:173], v[230:233], v[14:17]
	v_mfma_f32_16x16x32_bf16 v[6:9], v[178:181], v[230:233], v[6:9]
	s_setprio 0
	s_setprio 1
	v_mfma_f32_16x16x32_bf16 v[58:61], v[186:189], v[202:205], v[58:61]
	v_mfma_f32_16x16x32_bf16 v[50:53], v[194:197], v[202:205], v[50:53]
	v_mfma_f32_16x16x32_bf16 v[42:45], v[186:189], v[210:213], v[42:45]
	v_mfma_f32_16x16x32_bf16 v[34:37], v[194:197], v[210:213], v[34:37]
	v_mfma_f32_16x16x32_bf16 v[26:29], v[186:189], v[218:221], v[26:29]
	v_mfma_f32_16x16x32_bf16 v[18:21], v[194:197], v[218:221], v[18:21]
	v_mfma_f32_16x16x32_bf16 v[10:13], v[186:189], v[226:229], v[10:13]
	v_mfma_f32_16x16x32_bf16 v[2:5], v[194:197], v[226:229], v[2:5]
	v_mfma_f32_16x16x32_bf16 v[58:61], v[190:193], v[206:209], v[58:61]
	v_mfma_f32_16x16x32_bf16 v[50:53], v[198:201], v[206:209], v[50:53]
	v_mfma_f32_16x16x32_bf16 v[42:45], v[190:193], v[214:217], v[42:45]
	v_mfma_f32_16x16x32_bf16 v[34:37], v[198:201], v[214:217], v[34:37]
	v_mfma_f32_16x16x32_bf16 v[26:29], v[190:193], v[222:225], v[26:29]
	v_mfma_f32_16x16x32_bf16 v[18:21], v[198:201], v[222:225], v[18:21]
	v_mfma_f32_16x16x32_bf16 v[10:13], v[190:193], v[230:233], v[10:13]
	v_mfma_f32_16x16x32_bf16 v[2:5], v[198:201], v[230:233], v[2:5]
	s_setprio 0
	s_barrier
	s_add_i32 s65, s65, 2
	s_add_u32 s40, s40, 0x100
	s_addc_u32 s41, s41, 0
	s_add_u32 s63, s63, 0x100
	s_addc_u32 s64, s64, 0
	s_cmp_gt_u32 s65, 13
	s_cbranch_scc0 .LBB0_1234
	s_and_b64 vcc, exec, s[18:19]
	s_cbranch_vccz .LBB0_1237
	s_barrier

; #define PG8_STAGE(bufoff, gbase, voff) do { _Pragma("unroll") for (int _i = 0; _i < 2; ++_i) \
;         __builtin_amdgcn_global_load_lds((const unsigned*)((const char*)(gbase) + (voff)[_i]), (LAS unsigned*)(lds + (bufoff) + ldsw + _i * 8192), 16, 0, 0); } while (0)
; #define PG8_LDA(dst, b, h) do { _Pragma("unroll") for (int m = 0; m < 4; ++m) _Pragma("unroll") for (int k = 0; k < 2; ++k) dst[m][k] = *(const LAS bf16x8*)(lds + PG8_SA(b, h) + aoff + m * 2048 + k * 1024); } while (0)
; #define PG8_LDB(dst, b, h) do { _Pragma("unroll") for (int n = 0; n < 2; ++n) _Pragma("unroll") for (int k = 0; k < 2; ++k) dst[n][k] = *(const LAS bf16x8*)(lds + PG8_SB(b, h) + boff + n * 2048 + k * 1024); } while (0)
; #define PG8_MMA(ai, bj, At, Bt) do { __builtin_amdgcn_s_setprio(1); _Pragma("unroll") for (int m = 0; m < 4; ++m) _Pragma("unroll") for (int n = 0; n < 2; ++n) _Pragma("unroll") for (int k = 0; k < 2; ++k) \
;         acc[ai][bj][m][n] = __builtin_amdgcn_mfma_f32_16x16x32_bf16(Bt[n][k], At[m][k], acc[ai][bj][m][n], 0, 0, 0); __builtin_amdgcn_s_setprio(0); } while (0)
; #define PG8_WAIT_V(n) asm volatile("s_waitcnt vmcnt(" #n ")" ::: "memory")
; #define PG8_WAIT_L(n) asm volatile("s_waitcnt lgkmcnt(" #n ")" ::: "memory")
; #define PG8_BAR __builtin_amdgcn_s_barrier()
; #define PG8_SCHED __builtin_amdgcn_sched_barrier(0)
; template <class Epi, class Sched>
; DI void gemm_phase(LAS unsigned char* lds, const Gemm g, const Sched& S, const Epi& E) {
;     ...
;             const bool last = (t == nt - 2);
;             const char* a1 = cA + (size_t)(t + 1) * kstep;
;             const char* a2 = last ? nA : cA + (size_t)(t + 2) * kstep; const char* b2 = last ? nB : cB + (size_t)(t + 2) * kstep;
;             const char* a3 = a2 + kstep; const char* b3 = b2 + kstep;
;             PG8_LDB(B0, 0, 0); PG8_LDB(B1, 0, 1); PG8_SCHED; PG8_LDA(At, 0, 0); PG8_STAGE(PG8_SA(1, 1), a1 + hstepA, voffA);
;             PG8_WAIT_V(8); PG8_WAIT_L(0); PG8_BAR; PG8_MMA(0, 0, At, B0); PG8_MMA(0, 1, At, B1); PG8_BAR; PG8_SCHED;
;             PG8_LDA(At, 0, 1); PG8_STAGE(PG8_SB(0, 0), b2, voffB); PG8_STAGE(PG8_SB(0, 1), b2 + hstepB, voffB); PG8_STAGE(PG8_SA(0, 0), a2, voffA);
;             PG8_WAIT_V(8); PG8_WAIT_L(0); PG8_BAR; PG8_MMA(1, 0, At, B0); PG8_MMA(1, 1, At, B1); PG8_BAR; PG8_SCHED;
.LBB0_1331:
	ds_read_b128 v[144:147], v151
	ds_read_b128 v[154:157], v151 offset:1024
	ds_read_b128 v[158:161], v151 offset:2048
	ds_read_b128 v[162:165], v151 offset:3072
	ds_read_b128 v[166:169], v152
	ds_read_b128 v[170:173], v152 offset:1024
	ds_read_b128 v[174:177], v152 offset:2048
	ds_read_b128 v[178:181], v152 offset:3072
	s_add_u32 s18, s16, 0xfff50080
	s_addc_u32 s19, s17, -1
	s_cmp_eq_u32 s47, 40
	s_cselect_b32 s21, s5, s19
	s_cselect_b32 s20, s4, s18
	s_cselect_b32 s19, s15, s46
	s_cselect_b32 s18, s14, s45
	v_lshl_add_u64 v[214:215], s[16:17], 0, v[136:137]
	s_add_i32 m0, s28, 0xc000
	ds_read_b128 v[182:185], v153
	ds_read_b128 v[186:189], v153 offset:1024
	ds_read_b128 v[190:193], v153 offset:2048
	ds_read_b128 v[194:197], v153 offset:3072
	ds_read_b128 v[198:201], v153 offset:4096
	ds_read_b128 v[202:205], v153 offset:5120
	ds_read_b128 v[206:209], v153 offset:6144
	ds_read_b128 v[210:213], v153 offset:7168
	global_load_lds_dwordx4 v[214:215], off
	v_lshl_add_u64 v[214:215], s[16:17], 0, v[138:139]
	s_add_i32 m0, s28, 0xe000
	s_nop 0
	global_load_lds_dwordx4 v[214:215], off
	s_waitcnt vmcnt(8)
	s_waitcnt lgkmcnt(0)
	s_barrier
	s_setprio 1
	v_mfma_f32_16x16x32_bf16 v[124:127], v[144:147], v[182:185], v[124:127]
	v_mfma_f32_16x16x32_bf16 v[120:123], v[158:161], v[182:185], v[120:123]
	v_mfma_f32_16x16x32_bf16 v[108:111], v[144:147], v[190:193], v[108:111]
	v_mfma_f32_16x16x32_bf16 v[104:107], v[158:161], v[190:193], v[104:107]
	v_mfma_f32_16x16x32_bf16 v[92:95], v[144:147], v[198:201], v[92:95]
	v_mfma_f32_16x16x32_bf16 v[88:91], v[158:161], v[198:201], v[88:91]
	v_mfma_f32_16x16x32_bf16 v[76:79], v[144:147], v[206:209], v[76:79]
	v_mfma_f32_16x16x32_bf16 v[72:75], v[158:161], v[206:209], v[72:75]
	v_mfma_f32_16x16x32_bf16 v[124:127], v[154:157], v[186:189], v[124:127]
	v_mfma_f32_16x16x32_bf16 v[120:123], v[162:165], v[186:189], v[120:123]
	v_mfma_f32_16x16x32_bf16 v[108:111], v[154:157], v[194:197], v[108:111]
	v_mfma_f32_16x16x32_bf16 v[104:107], v[162:165], v[194:197], v[104:107]
	v_mfma_f32_16x16x32_bf16 v[92:95], v[154:157], v[202:205], v[92:95]
	v_mfma_f32_16x16x32_bf16 v[88:91], v[162:165], v[202:205], v[88:91]
	v_mfma_f32_16x16x32_bf16 v[76:79], v[154:157], v[210:213], v[76:79]
	v_mfma_f32_16x16x32_bf16 v[72:75], v[162:165], v[210:213], v[72:75]
	s_setprio 0
	s_setprio 1
	v_mfma_f32_16x16x32_bf16 v[116:119], v[166:169], v[182:185], v[116:119]
	v_mfma_f32_16x16x32_bf16 v[112:115], v[174:177], v[182:185], v[112:115]
	v_mfma_f32_16x16x32_bf16 v[100:103], v[166:169], v[190:193], v[100:103]
	v_mfma_f32_16x16x32_bf16 v[96:99], v[174:177], v[190:193], v[96:99]
	v_mfma_f32_16x16x32_bf16 v[84:87], v[166:169], v[198:201], v[84:87]
	v_mfma_f32_16x16x32_bf16 v[80:83], v[174:177], v[198:201], v[80:83]
	v_mfma_f32_16x16x32_bf16 v[68:71], v[166:169], v[206:209], v[68:71]
	v_mfma_f32_16x16x32_bf16 v[64:67], v[174:177], v[206:209], v[64:67]
	v_mfma_f32_16x16x32_bf16 v[116:119], v[170:173], v[186:189], v[116:119]
	v_mfma_f32_16x16x32_bf16 v[112:115], v[178:181], v[186:189], v[112:115]
	v_mfma_f32_16x16x32_bf16 v[100:103], v[170:173], v[194:197], v[100:103]
	v_mfma_f32_16x16x32_bf16 v[96:99], v[178:181], v[194:197], v[96:99]
	v_mfma_f32_16x16x32_bf16 v[84:87], v[170:173], v[202:205], v[84:87]
	v_mfma_f32_16x16x32_bf16 v[80:83], v[178:181], v[202:205], v[80:83]
	v_mfma_f32_16x16x32_bf16 v[68:71], v[170:173], v[210:213], v[68:71]
	v_mfma_f32_16x16x32_bf16 v[64:67], v[178:181], v[210:213], v[64:67]
	s_setprio 0
	s_barrier
	s_add_i32 s48, s39, s27
	v_lshl_add_u64 v[214:215], s[18:19], 0, v[130:131]
	s_mov_b32 m0, s48
	ds_read_b128 v[182:185], v153 offset:16384
	ds_read_b128 v[186:189], v153 offset:17408
	ds_read_b128 v[190:193], v153 offset:18432
	ds_read_b128 v[194:197], v153 offset:19456
	ds_read_b128 v[198:201], v153 offset:20480
	ds_read_b128 v[202:205], v153 offset:21504
	ds_read_b128 v[206:209], v153 offset:22528
	ds_read_b128 v[210:213], v153 offset:23552
	global_load_lds_dwordx4 v[214:215], off
	s_add_i32 m0, s48, 0x2000
	s_add_u32 s48, s18, 0xb0000
	v_lshl_add_u64 v[216:217], s[18:19], 0, v[134:135]
	s_addc_u32 s49, s19, 0
	s_add_i32 s50, s40, s27
	global_load_lds_dwordx4 v[216:217], off
	v_lshl_add_u64 v[218:219], s[48:49], 0, v[130:131]
	s_mov_b32 m0, s50
	v_lshl_add_u64 v[220:221], s[20:21], 0, v[132:133]
	global_load_lds_dwordx4 v[218:219], off
	v_lshl_add_u64 v[218:219], s[48:49], 0, v[134:135]
	s_add_i32 m0, s50, 0x2000
	s_nop 0
	global_load_lds_dwordx4 v[218:219], off
	v_lshl_add_u64 v[218:219], s[20:21], 0, v[128:129]
	s_mov_b32 m0, s28
	s_nop 0
	global_load_lds_dwordx4 v[218:219], off
	s_mov_b32 m0, s29
	s_nop 0
	global_load_lds_dwordx4 v[220:221], off
	s_waitcnt vmcnt(8)
	s_waitcnt lgkmcnt(0)
	s_barrier
; #define PG8_STAGE(bufoff, gbase, voff) do { _Pragma("unroll") for (int _i = 0; _i < 2; ++_i) \
;         __builtin_amdgcn_global_load_lds((const unsigned*)((const char*)(gbase) + (voff)[_i]), (LAS unsigned*)(lds + (bufoff) + ldsw + _i * 8192), 16, 0, 0); } while (0)
; #define PG8_LDA(dst, b, h) do { _Pragma("unroll") for (int m = 0; m < 4; ++m) _Pragma("unroll") for (int k = 0; k < 2; ++k) dst[m][k] = *(const LAS bf16x8*)(lds + PG8_SA(b, h) + aoff + m * 2048 + k * 1024); } while (0)
; #define PG8_LDB(dst, b, h) do { _Pragma("unroll") for (int n = 0; n < 2; ++n) _Pragma("unroll") for (int k = 0; k < 2; ++k) dst[n][k] = *(const LAS bf16x8*)(lds + PG8_SB(b, h) + boff + n * 2048 + k * 1024); } while (0)
; #define PG8_MMA(ai, bj, At, Bt) do { __builtin_amdgcn_s_setprio(1); _Pragma("unroll") for (int m = 0; m < 4; ++m) _Pragma("unroll") for (int n = 0; n < 2; ++n) _Pragma("unroll") for (int k = 0; k < 2; ++k) \
;         acc[ai][bj][m][n] = __builtin_amdgcn_mfma_f32_16x16x32_bf16(Bt[n][k], At[m][k], acc[ai][bj][m][n], 0, 0, 0); __builtin_amdgcn_s_setprio(0); } while (0)
; #define PG8_WAIT_V(n) asm volatile("s_waitcnt vmcnt(" #n ")" ::: "memory")
; #define PG8_WAIT_L(n) asm volatile("s_waitcnt lgkmcnt(" #n ")" ::: "memory")
; #define PG8_BAR __builtin_amdgcn_s_barrier()
; #define PG8_SCHED __builtin_amdgcn_sched_barrier(0)
; template <class Epi, class Sched>
; DI void gemm_phase(LAS unsigned char* lds, const Gemm g, const Sched& S, const Epi& E) {
;     ...
;             PG8_WAIT_V(8); PG8_WAIT_L(0); PG8_BAR; PG8_MMA(1, 0, At, B0); PG8_MMA(1, 1, At, B1); PG8_BAR; PG8_SCHED;
;             PG8_LDB(B0, 1, 0); PG8_LDB(B1, 1, 1); PG8_SCHED; PG8_LDA(At, 1, 0); PG8_STAGE(PG8_SA(0, 1), a2 + hstepA, voffA);
;             PG8_WAIT_V(8); PG8_WAIT_L(0); PG8_BAR; PG8_MMA(0, 0, At, B0); PG8_MMA(0, 1, At, B1); PG8_BAR; PG8_SCHED;
	s_setprio 1
	v_mfma_f32_16x16x32_bf16 v[60:63], v[144:147], v[182:185], v[60:63]
	v_mfma_f32_16x16x32_bf16 v[56:59], v[158:161], v[182:185], v[56:59]
	v_mfma_f32_16x16x32_bf16 v[44:47], v[144:147], v[190:193], v[44:47]
	v_mfma_f32_16x16x32_bf16 v[40:43], v[158:161], v[190:193], v[40:43]
	v_mfma_f32_16x16x32_bf16 v[28:31], v[144:147], v[198:201], v[28:31]
	v_mfma_f32_16x16x32_bf16 v[24:27], v[158:161], v[198:201], v[24:27]
	v_mfma_f32_16x16x32_bf16 v[12:15], v[144:147], v[206:209], v[12:15]
	v_mfma_f32_16x16x32_bf16 v[8:11], v[158:161], v[206:209], v[8:11]
	v_mfma_f32_16x16x32_bf16 v[60:63], v[154:157], v[186:189], v[60:63]
	v_mfma_f32_16x16x32_bf16 v[56:59], v[162:165], v[186:189], v[56:59]
	v_mfma_f32_16x16x32_bf16 v[44:47], v[154:157], v[194:197], v[44:47]
	v_mfma_f32_16x16x32_bf16 v[40:43], v[162:165], v[194:197], v[40:43]
	v_mfma_f32_16x16x32_bf16 v[28:31], v[154:157], v[202:205], v[28:31]
	v_mfma_f32_16x16x32_bf16 v[24:27], v[162:165], v[202:205], v[24:27]
	v_mfma_f32_16x16x32_bf16 v[12:15], v[154:157], v[210:213], v[12:15]
	v_mfma_f32_16x16x32_bf16 v[8:11], v[162:165], v[210:213], v[8:11]
	s_setprio 0
	s_setprio 1
	v_mfma_f32_16x16x32_bf16 v[52:55], v[166:169], v[182:185], v[52:55]
	v_mfma_f32_16x16x32_bf16 v[48:51], v[174:177], v[182:185], v[48:51]
	v_mfma_f32_16x16x32_bf16 v[36:39], v[166:169], v[190:193], v[36:39]
	v_mfma_f32_16x16x32_bf16 v[32:35], v[174:177], v[190:193], v[32:35]
	v_mfma_f32_16x16x32_bf16 v[20:23], v[166:169], v[198:201], v[20:23]
	v_mfma_f32_16x16x32_bf16 v[16:19], v[174:177], v[198:201], v[16:19]
	v_mfma_f32_16x16x32_bf16 v[4:7], v[166:169], v[206:209], v[4:7]
	v_mfma_f32_16x16x32_bf16 v[0:3], v[174:177], v[206:209], v[0:3]
	v_mfma_f32_16x16x32_bf16 v[52:55], v[170:173], v[186:189], v[52:55]
	v_mfma_f32_16x16x32_bf16 v[48:51], v[178:181], v[186:189], v[48:51]
	v_mfma_f32_16x16x32_bf16 v[36:39], v[170:173], v[194:197], v[36:39]
	v_mfma_f32_16x16x32_bf16 v[32:35], v[178:181], v[194:197], v[32:35]
	v_mfma_f32_16x16x32_bf16 v[20:23], v[170:173], v[202:205], v[20:23]
	v_mfma_f32_16x16x32_bf16 v[16:19], v[178:181], v[202:205], v[16:19]
	v_mfma_f32_16x16x32_bf16 v[4:7], v[170:173], v[210:213], v[4:7]
	v_mfma_f32_16x16x32_bf16 v[0:3], v[178:181], v[210:213], v[0:3]
	s_setprio 0
	s_barrier
	s_add_i32 s48, 0, 0x18000
	s_add_i32 s49, 0, 0x1c000
	v_add_u32_e32 v162, s48, v149
	v_add_u32_e32 v178, s49, v149
	ds_read_b128 v[144:147], v162
	ds_read_b128 v[154:157], v162 offset:1024
	ds_read_b128 v[158:161], v162 offset:2048
	ds_read_b128 v[162:165], v162 offset:3072
	ds_read_b128 v[166:169], v178
	ds_read_b128 v[170:173], v178 offset:1024
	ds_read_b128 v[174:177], v178 offset:2048
	ds_read_b128 v[178:181], v178 offset:3072
	s_add_u32 s20, s20, 0xb0000
	s_addc_u32 s21, s21, 0
	s_mov_b32 m0, s33
	v_lshl_add_u64 v[222:223], s[20:21], 0, v[128:129]
	ds_read_b128 v[182:185], v153 offset:32768
	ds_read_b128 v[186:189], v153 offset:33792
	ds_read_b128 v[190:193], v153 offset:34816
	ds_read_b128 v[194:197], v153 offset:35840
	ds_read_b128 v[198:201], v153 offset:36864
	ds_read_b128 v[202:205], v153 offset:37888
	ds_read_b128 v[206:209], v153 offset:38912
	ds_read_b128 v[210:213], v153 offset:39936
	global_load_lds_dwordx4 v[222:223], off
	v_lshl_add_u64 v[222:223], s[20:21], 0, v[132:133]
	s_mov_b32 m0, s34
	s_nop 0
	global_load_lds_dwordx4 v[222:223], off
	s_waitcnt vmcnt(8)
	s_waitcnt lgkmcnt(0)
	s_barrier
	s_setprio 1
	v_mfma_f32_16x16x32_bf16 v[124:127], v[144:147], v[182:185], v[124:127]
	v_mfma_f32_16x16x32_bf16 v[120:123], v[158:161], v[182:185], v[120:123]
	v_mfma_f32_16x16x32_bf16 v[108:111], v[144:147], v[190:193], v[108:111]
	v_mfma_f32_16x16x32_bf16 v[104:107], v[158:161], v[190:193], v[104:107]
	v_mfma_f32_16x16x32_bf16 v[92:95], v[144:147], v[198:201], v[92:95]
	v_mfma_f32_16x16x32_bf16 v[88:91], v[158:161], v[198:201], v[88:91]
	v_mfma_f32_16x16x32_bf16 v[76:79], v[144:147], v[206:209], v[76:79]
	v_mfma_f32_16x16x32_bf16 v[72:75], v[158:161], v[206:209], v[72:75]
	v_mfma_f32_16x16x32_bf16 v[124:127], v[154:157], v[186:189], v[124:127]
	v_mfma_f32_16x16x32_bf16 v[120:123], v[162:165], v[186:189], v[120:123]
	v_mfma_f32_16x16x32_bf16 v[108:111], v[154:157], v[194:197], v[108:111]
	v_mfma_f32_16x16x32_bf16 v[104:107], v[162:165], v[194:197], v[104:107]
	v_mfma_f32_16x16x32_bf16 v[92:95], v[154:157], v[202:205], v[92:95]
	v_mfma_f32_16x16x32_bf16 v[88:91], v[162:165], v[202:205], v[88:91]
	v_mfma_f32_16x16x32_bf16 v[76:79], v[154:157], v[210:213], v[76:79]
	v_mfma_f32_16x16x32_bf16 v[72:75], v[162:165], v[210:213], v[72:75]
	s_setprio 0
	s_setprio 1
	v_mfma_f32_16x16x32_bf16 v[116:119], v[166:169], v[182:185], v[116:119]
	v_mfma_f32_16x16x32_bf16 v[112:115], v[174:177], v[182:185], v[112:115]
	v_mfma_f32_16x16x32_bf16 v[100:103], v[166:169], v[190:193], v[100:103]
	v_mfma_f32_16x16x32_bf16 v[96:99], v[174:177], v[190:193], v[96:99]
	v_mfma_f32_16x16x32_bf16 v[84:87], v[166:169], v[198:201], v[84:87]
	v_mfma_f32_16x16x32_bf16 v[80:83], v[174:177], v[198:201], v[80:83]
	v_mfma_f32_16x16x32_bf16 v[68:71], v[166:169], v[206:209], v[68:71]
	v_mfma_f32_16x16x32_bf16 v[64:67], v[174:177], v[206:209], v[64:67]
	v_mfma_f32_16x16x32_bf16 v[116:119], v[170:173], v[186:189], v[116:119]
	v_mfma_f32_16x16x32_bf16 v[112:115], v[178:181], v[186:189], v[112:115]
	v_mfma_f32_16x16x32_bf16 v[100:103], v[170:173], v[194:197], v[100:103]
	v_mfma_f32_16x16x32_bf16 v[96:99], v[178:181], v[194:197], v[96:99]
	v_mfma_f32_16x16x32_bf16 v[84:87], v[170:173], v[202:205], v[84:87]
	v_mfma_f32_16x16x32_bf16 v[80:83], v[178:181], v[202:205], v[80:83]
	v_mfma_f32_16x16x32_bf16 v[68:71], v[170:173], v[210:213], v[68:71]
	v_mfma_f32_16x16x32_bf16 v[64:67], v[178:181], v[210:213], v[64:67]
	s_setprio 0
	s_barrier
; #define PG8_STAGE(bufoff, gbase, voff) do { _Pragma("unroll") for (int _i = 0; _i < 2; ++_i) \
;         __builtin_amdgcn_global_load_lds((const unsigned*)((const char*)(gbase) + (voff)[_i]), (LAS unsigned*)(lds + (bufoff) + ldsw + _i * 8192), 16, 0, 0); } while (0)
; #define PG8_LDA(dst, b, h) do { _Pragma("unroll") for (int m = 0; m < 4; ++m) _Pragma("unroll") for (int k = 0; k < 2; ++k) dst[m][k] = *(const LAS bf16x8*)(lds + PG8_SA(b, h) + aoff + m * 2048 + k * 1024); } while (0)
; #define PG8_MMA(ai, bj, At, Bt) do { __builtin_amdgcn_s_setprio(1); _Pragma("unroll") for (int m = 0; m < 4; ++m) _Pragma("unroll") for (int n = 0; n < 2; ++n) _Pragma("unroll") for (int k = 0; k < 2; ++k) \
;         acc[ai][bj][m][n] = __builtin_amdgcn_mfma_f32_16x16x32_bf16(Bt[n][k], At[m][k], acc[ai][bj][m][n], 0, 0, 0); __builtin_amdgcn_s_setprio(0); } while (0)
; #define PG8_WAIT_V(n) asm volatile("s_waitcnt vmcnt(" #n ")" ::: "memory")
; #define PG8_WAIT_L(n) asm volatile("s_waitcnt lgkmcnt(" #n ")" ::: "memory")
; #define PG8_BAR __builtin_amdgcn_s_barrier()
; #define PG8_SCHED __builtin_amdgcn_sched_barrier(0)
; template <class Epi, class Sched>
; DI void gemm_phase(LAS unsigned char* lds, const Gemm g, const Sched& S, const Epi& E) {
;     ...
;             PG8_LDA(At, 1, 1); PG8_STAGE(PG8_SB(1, 0), b3, voffB); PG8_STAGE(PG8_SB(1, 1), b3 + hstepB, voffB); PG8_STAGE(PG8_SA(1, 0), a3, voffA);
;             PG8_WAIT_V(8); PG8_WAIT_L(0); PG8_BAR; PG8_MMA(1, 0, At, B0); PG8_MMA(1, 1, At, B1); PG8_BAR; PG8_SCHED;
;         }
;         if (wr == 0) PG8_BAR;
	s_add_i32 s20, s48, s27
	v_lshl_add_u64 v[214:215], v[214:215], 0, s[10:11]
	s_mov_b32 m0, s20
	ds_read_b128 v[182:185], v153 offset:49152
	ds_read_b128 v[186:189], v153 offset:50176
	ds_read_b128 v[190:193], v153 offset:51200
	ds_read_b128 v[194:197], v153 offset:52224
	ds_read_b128 v[198:201], v153 offset:53248
	ds_read_b128 v[202:205], v153 offset:54272
	ds_read_b128 v[206:209], v153 offset:55296
	ds_read_b128 v[210:213], v153 offset:56320
	global_load_lds_dwordx4 v[214:215], off
	s_add_i32 m0, s20, 0x2000
	s_add_u32 s18, s18, 0xb0080
	v_lshl_add_u64 v[214:215], v[216:217], 0, s[10:11]
	s_addc_u32 s19, s19, 0
	s_add_i32 s20, s49, s27
	global_load_lds_dwordx4 v[214:215], off
	v_lshl_add_u64 v[214:215], s[18:19], 0, v[130:131]
	s_mov_b32 m0, s20
	s_nop 0
	global_load_lds_dwordx4 v[214:215], off
	v_lshl_add_u64 v[214:215], s[18:19], 0, v[134:135]
	s_add_i32 m0, s20, 0x2000
	s_nop 0
	global_load_lds_dwordx4 v[214:215], off
	v_lshl_add_u64 v[214:215], v[218:219], 0, s[10:11]
	s_mov_b32 m0, s36
	s_nop 0
	global_load_lds_dwordx4 v[214:215], off
	v_lshl_add_u64 v[214:215], v[220:221], 0, s[10:11]
	s_mov_b32 m0, s37
	s_nop 0
	global_load_lds_dwordx4 v[214:215], off
	s_waitcnt vmcnt(8)
	s_waitcnt lgkmcnt(0)
	s_barrier
	s_setprio 1
	v_mfma_f32_16x16x32_bf16 v[60:63], v[144:147], v[182:185], v[60:63]
	v_mfma_f32_16x16x32_bf16 v[56:59], v[158:161], v[182:185], v[56:59]
	v_mfma_f32_16x16x32_bf16 v[44:47], v[144:147], v[190:193], v[44:47]
	v_mfma_f32_16x16x32_bf16 v[40:43], v[158:161], v[190:193], v[40:43]
	v_mfma_f32_16x16x32_bf16 v[28:31], v[144:147], v[198:201], v[28:31]
	v_mfma_f32_16x16x32_bf16 v[24:27], v[158:161], v[198:201], v[24:27]
	v_mfma_f32_16x16x32_bf16 v[12:15], v[144:147], v[206:209], v[12:15]
	v_mfma_f32_16x16x32_bf16 v[8:11], v[158:161], v[206:209], v[8:11]
	v_mfma_f32_16x16x32_bf16 v[60:63], v[154:157], v[186:189], v[60:63]
	v_mfma_f32_16x16x32_bf16 v[56:59], v[162:165], v[186:189], v[56:59]
	v_mfma_f32_16x16x32_bf16 v[44:47], v[154:157], v[194:197], v[44:47]
	v_mfma_f32_16x16x32_bf16 v[40:43], v[162:165], v[194:197], v[40:43]
	v_mfma_f32_16x16x32_bf16 v[28:31], v[154:157], v[202:205], v[28:31]
	v_mfma_f32_16x16x32_bf16 v[24:27], v[162:165], v[202:205], v[24:27]
	v_mfma_f32_16x16x32_bf16 v[12:15], v[154:157], v[210:213], v[12:15]
	v_mfma_f32_16x16x32_bf16 v[8:11], v[162:165], v[210:213], v[8:11]
	s_setprio 0
	s_setprio 1
	v_mfma_f32_16x16x32_bf16 v[52:55], v[166:169], v[182:185], v[52:55]
	v_mfma_f32_16x16x32_bf16 v[48:51], v[174:177], v[182:185], v[48:51]
	v_mfma_f32_16x16x32_bf16 v[36:39], v[166:169], v[190:193], v[36:39]
	v_mfma_f32_16x16x32_bf16 v[32:35], v[174:177], v[190:193], v[32:35]
	v_mfma_f32_16x16x32_bf16 v[20:23], v[166:169], v[198:201], v[20:23]
	v_mfma_f32_16x16x32_bf16 v[16:19], v[174:177], v[198:201], v[16:19]
	v_mfma_f32_16x16x32_bf16 v[4:7], v[166:169], v[206:209], v[4:7]
	v_mfma_f32_16x16x32_bf16 v[0:3], v[174:177], v[206:209], v[0:3]
	v_mfma_f32_16x16x32_bf16 v[52:55], v[170:173], v[186:189], v[52:55]
	v_mfma_f32_16x16x32_bf16 v[48:51], v[178:181], v[186:189], v[48:51]
	v_mfma_f32_16x16x32_bf16 v[36:39], v[170:173], v[194:197], v[36:39]
	v_mfma_f32_16x16x32_bf16 v[32:35], v[178:181], v[194:197], v[32:35]
	v_mfma_f32_16x16x32_bf16 v[20:23], v[170:173], v[202:205], v[20:23]
	v_mfma_f32_16x16x32_bf16 v[16:19], v[178:181], v[202:205], v[16:19]
	v_mfma_f32_16x16x32_bf16 v[4:7], v[170:173], v[210:213], v[4:7]
	v_mfma_f32_16x16x32_bf16 v[0:3], v[178:181], v[210:213], v[0:3]
	s_setprio 0
	s_barrier
	s_add_i32 s47, s47, 2
	s_add_u32 s16, s16, 0x100
	s_addc_u32 s17, s17, 0
	s_add_u32 s45, s45, 0x100
	s_addc_u32 s46, s46, 0
	s_cmp_gt_u32 s47, 41
	s_cbranch_scc0 .LBB0_1331
	s_and_b64 vcc, exec, s[12:13]
	s_cbranch_vccz .LBB0_1334
	s_barrier
